# GEMM K-loops: in the SP2 load segments the six LDS-DMA loads are issued before the eight LDS fragment reads
# speedup vs baseline: 1.0002x; 1.0002x over previous
; #define PG8_STAGE(bufoff, gbase, voff) do { _Pragma("unroll") for (int _i = 0; _i < 2; ++_i) \
;         __builtin_amdgcn_global_load_lds((const unsigned*)((const char*)(gbase) + (voff)[_i]), (PG8_LAS unsigned*)(lds + (bufoff) + ldsw + _i * 8192), 16, 0, 0); } while (0)
; #define PG8_LDA(dst, b, h) do { _Pragma("unroll") for (int m = 0; m < 4; ++m) _Pragma("unroll") for (int k = 0; k < 2; ++k) dst[m][k] = *(const PG8_LAS bf16x8*)(lds + PG8_SA(b, h) + aoff + m * 2048 + k * 1024); } while (0)
; #define PG8_LDB(dst, b, h) do { _Pragma("unroll") for (int n = 0; n < 2; ++n) _Pragma("unroll") for (int k = 0; k < 2; ++k) dst[n][k] = *(const PG8_LAS bf16x8*)(lds + PG8_SB(b, h) + boff + n * 2048 + k * 1024); } while (0)
; #define PG8_MMA(ai, bj, At, Bt) do { __builtin_amdgcn_s_setprio(1); _Pragma("unroll") for (int m = 0; m < 4; ++m) _Pragma("unroll") for (int n = 0; n < 2; ++n) _Pragma("unroll") for (int k = 0; k < 2; ++k) \
;         acc[ai][bj][m][n] = __builtin_amdgcn_mfma_f32_16x16x32_bf16(Bt[n][k], At[m][k], acc[ai][bj][m][n], 0, 0, 0); __builtin_amdgcn_s_setprio(0); } while (0)
; #define PG8_WAIT_V(n) asm volatile("s_waitcnt vmcnt(" #n ")" ::: "memory")
; #define PG8_WAIT_L(n) asm volatile("s_waitcnt lgkmcnt(" #n ")" ::: "memory")
; #define PG8_BAR __builtin_amdgcn_s_barrier()
; #define PG8_SCHED __builtin_amdgcn_sched_barrier(0)
; template <class Epi, class Sched, bool ALIGN_EPI = false, bool SP2 = false>
; __device__ __forceinline__ void gemm_phase(PG8_LAS unsigned char* lds, const Gemm g, const Sched& S, const Epi& E) {
;     ...
;             PG8_LDB(B0, 0, 0); PG8_LDB(B1, 0, 1); PG8_SCHED; PG8_LDA(At, 0, 0); PG8_STAGE(PG8_SA(1, 1), a1 + hstepA, voffA);
;             PG8_WAIT_V(8); PG8_WAIT_L(0); PG8_BAR; PG8_MMA(0, 0, At, B0); PG8_MMA(0, 1, At, B1); PG8_BAR; PG8_SCHED;
;             PG8_LDA(At, 0, 1); PG8_STAGE(PG8_SB(0, 0), b2, voffB); PG8_STAGE(PG8_SB(0, 1), b2 + hstepB, voffB); PG8_STAGE(PG8_SA(0, 0), a2, voffA);
;             PG8_WAIT_V(8); PG8_WAIT_L(0); PG8_BAR; PG8_MMA(1, 0, At, B0); PG8_MMA(1, 1, At, B1); PG8_BAR; PG8_SCHED;
.LBB0_210:
	ds_read_b128 v[146:149], v155
	ds_read_b128 v[158:161], v155 offset:1024
	ds_read_b128 v[162:165], v155 offset:2048
	ds_read_b128 v[166:169], v155 offset:3072
	ds_read_b128 v[170:173], v156
	ds_read_b128 v[174:177], v156 offset:1024
	ds_read_b128 v[178:181], v156 offset:2048
	ds_read_b128 v[182:185], v156 offset:3072
	s_add_u32 s26, s24, 0xfff00080
	s_addc_u32 s27, s25, -1
	s_cmp_eq_u32 s53, 60
	s_cselect_b32 s29, s17, s27
	s_cselect_b32 s28, s49, s26
	s_cselect_b32 s27, s15, s52
	s_cselect_b32 s26, s50, s51
	v_lshl_add_u64 v[214:215], s[24:25], 0, v[138:139]
	s_add_i32 m0, s23, 0xc000
	ds_read_b128 v[186:189], v157
	ds_read_b128 v[190:193], v157 offset:1024
	ds_read_b128 v[194:197], v157 offset:2048
	ds_read_b128 v[198:201], v157 offset:3072
	ds_read_b128 v[202:205], v157 offset:4096
	ds_read_b128 v[206:209], v157 offset:5120
	ds_read_b128 v[210:213], v157 offset:6144
	ds_read_b128 v[218:221], v157 offset:7168
	global_load_lds_dwordx4 v[214:215], off
	v_lshl_add_u64 v[214:215], s[24:25], 0, v[140:141]
	s_add_i32 m0, s23, 0xe000
	s_nop 0
	global_load_lds_dwordx4 v[214:215], off
	s_waitcnt vmcnt(8)
	s_waitcnt lgkmcnt(0)
	s_barrier
	s_setprio 1
	s_waitcnt lgkmcnt(0)
	v_mfma_f32_16x16x32_bf16 v[126:129], v[146:149], v[186:189], v[126:129]
	v_mfma_f32_16x16x32_bf16 v[122:125], v[162:165], v[186:189], v[122:125]
	v_mfma_f32_16x16x32_bf16 v[118:121], v[146:149], v[194:197], v[118:121]
	v_mfma_f32_16x16x32_bf16 v[114:117], v[162:165], v[194:197], v[114:117]
	v_mfma_f32_16x16x32_bf16 v[106:109], v[146:149], v[202:205], v[106:109]
	v_mfma_f32_16x16x32_bf16 v[98:101], v[162:165], v[202:205], v[98:101]
	v_mfma_f32_16x16x32_bf16 v[78:81], v[146:149], v[210:213], v[78:81]
	v_mfma_f32_16x16x32_bf16 v[74:77], v[162:165], v[210:213], v[74:77]
	v_mfma_f32_16x16x32_bf16 v[126:129], v[158:161], v[190:193], v[126:129]
	v_mfma_f32_16x16x32_bf16 v[122:125], v[166:169], v[190:193], v[122:125]
	v_mfma_f32_16x16x32_bf16 v[118:121], v[158:161], v[198:201], v[118:121]
	v_mfma_f32_16x16x32_bf16 v[114:117], v[166:169], v[198:201], v[114:117]
	v_mfma_f32_16x16x32_bf16 v[106:109], v[158:161], v[206:209], v[106:109]
	v_mfma_f32_16x16x32_bf16 v[98:101], v[166:169], v[206:209], v[98:101]
	v_mfma_f32_16x16x32_bf16 v[78:81], v[158:161], v[218:221], v[78:81]
	v_mfma_f32_16x16x32_bf16 v[74:77], v[166:169], v[218:221], v[74:77]
	s_setprio 0
	s_setprio 1
	v_mfma_f32_16x16x32_bf16 v[110:113], v[170:173], v[186:189], v[110:113]
	v_mfma_f32_16x16x32_bf16 v[102:105], v[178:181], v[186:189], v[102:105]
	v_mfma_f32_16x16x32_bf16 v[94:97], v[170:173], v[194:197], v[94:97]
	v_mfma_f32_16x16x32_bf16 v[90:93], v[178:181], v[194:197], v[90:93]
	v_mfma_f32_16x16x32_bf16 v[86:89], v[170:173], v[202:205], v[86:89]
	v_mfma_f32_16x16x32_bf16 v[82:85], v[178:181], v[202:205], v[82:85]
	v_mfma_f32_16x16x32_bf16 v[70:73], v[170:173], v[210:213], v[70:73]
	v_mfma_f32_16x16x32_bf16 v[66:69], v[178:181], v[210:213], v[66:69]
	v_mfma_f32_16x16x32_bf16 v[110:113], v[174:177], v[190:193], v[110:113]
	v_mfma_f32_16x16x32_bf16 v[102:105], v[182:185], v[190:193], v[102:105]
	v_mfma_f32_16x16x32_bf16 v[94:97], v[174:177], v[198:201], v[94:97]
	v_mfma_f32_16x16x32_bf16 v[90:93], v[182:185], v[198:201], v[90:93]
	v_mfma_f32_16x16x32_bf16 v[86:89], v[174:177], v[206:209], v[86:89]
	v_mfma_f32_16x16x32_bf16 v[82:85], v[182:185], v[206:209], v[82:85]
	v_mfma_f32_16x16x32_bf16 v[70:73], v[174:177], v[218:221], v[70:73]
	v_mfma_f32_16x16x32_bf16 v[66:69], v[182:185], v[218:221], v[66:69]
	s_setprio 0
	s_barrier
	s_add_i32 s54, s45, s35
	v_lshl_add_u64 v[214:215], s[26:27], 0, v[134:135]
	s_mov_b32 m0, s54
	global_load_lds_dwordx4 v[214:215], off
	s_add_i32 m0, s54, 0x2000
	s_add_u32 s54, s26, 0x100000
	v_lshl_add_u64 v[222:223], s[26:27], 0, v[130:131]
	s_addc_u32 s55, s27, 0
	s_add_i32 s56, s46, s35
	global_load_lds_dwordx4 v[222:223], off
	v_lshl_add_u64 v[224:225], s[54:55], 0, v[134:135]
	s_mov_b32 m0, s56
	v_lshl_add_u64 v[226:227], s[28:29], 0, v[132:133]
	global_load_lds_dwordx4 v[224:225], off
	v_lshl_add_u64 v[224:225], s[54:55], 0, v[130:131]
	s_add_i32 m0, s56, 0x2000
	s_nop 0
	global_load_lds_dwordx4 v[224:225], off
	v_lshl_add_u64 v[224:225], s[28:29], 0, v[136:137]
	s_mov_b32 m0, s23
	s_nop 0
	global_load_lds_dwordx4 v[224:225], off
	s_mov_b32 m0, s38
	s_nop 0
	global_load_lds_dwordx4 v[226:227], off
	ds_read_b128 v[186:189], v157 offset:16384
	ds_read_b128 v[190:193], v157 offset:17408
	ds_read_b128 v[194:197], v157 offset:18432
	ds_read_b128 v[198:201], v157 offset:19456
	ds_read_b128 v[202:205], v157 offset:20480
	ds_read_b128 v[206:209], v157 offset:21504
	ds_read_b128 v[210:213], v157 offset:22528
	ds_read_b128 v[218:221], v157 offset:23552
	s_waitcnt vmcnt(8)
	s_waitcnt lgkmcnt(0)
	s_barrier
; #define PG8_STAGE(bufoff, gbase, voff) do { _Pragma("unroll") for (int _i = 0; _i < 2; ++_i) \
;         __builtin_amdgcn_global_load_lds((const unsigned*)((const char*)(gbase) + (voff)[_i]), (PG8_LAS unsigned*)(lds + (bufoff) + ldsw + _i * 8192), 16, 0, 0); } while (0)
; #define PG8_LDA(dst, b, h) do { _Pragma("unroll") for (int m = 0; m < 4; ++m) _Pragma("unroll") for (int k = 0; k < 2; ++k) dst[m][k] = *(const PG8_LAS bf16x8*)(lds + PG8_SA(b, h) + aoff + m * 2048 + k * 1024); } while (0)
; #define PG8_LDB(dst, b, h) do { _Pragma("unroll") for (int n = 0; n < 2; ++n) _Pragma("unroll") for (int k = 0; k < 2; ++k) dst[n][k] = *(const PG8_LAS bf16x8*)(lds + PG8_SB(b, h) + boff + n * 2048 + k * 1024); } while (0)
; #define PG8_MMA(ai, bj, At, Bt) do { __builtin_amdgcn_s_setprio(1); _Pragma("unroll") for (int m = 0; m < 4; ++m) _Pragma("unroll") for (int n = 0; n < 2; ++n) _Pragma("unroll") for (int k = 0; k < 2; ++k) \
;         acc[ai][bj][m][n] = __builtin_amdgcn_mfma_f32_16x16x32_bf16(Bt[n][k], At[m][k], acc[ai][bj][m][n], 0, 0, 0); __builtin_amdgcn_s_setprio(0); } while (0)
; #define PG8_WAIT_V(n) asm volatile("s_waitcnt vmcnt(" #n ")" ::: "memory")
; #define PG8_WAIT_L(n) asm volatile("s_waitcnt lgkmcnt(" #n ")" ::: "memory")
; #define PG8_BAR __builtin_amdgcn_s_barrier()
; #define PG8_SCHED __builtin_amdgcn_sched_barrier(0)
; template <class Epi, class Sched, bool ALIGN_EPI = false, bool SP2 = false>
; __device__ __forceinline__ void gemm_phase(PG8_LAS unsigned char* lds, const Gemm g, const Sched& S, const Epi& E) {
;     ...
;             PG8_WAIT_V(8); PG8_WAIT_L(0); PG8_BAR; PG8_MMA(1, 0, At, B0); PG8_MMA(1, 1, At, B1); PG8_BAR; PG8_SCHED;
;             PG8_LDB(B0, 1, 0); PG8_LDB(B1, 1, 1); PG8_SCHED; PG8_LDA(At, 1, 0); PG8_STAGE(PG8_SA(0, 1), a2 + hstepA, voffA);
;             PG8_WAIT_V(8); PG8_WAIT_L(0); PG8_BAR; PG8_MMA(0, 0, At, B0); PG8_MMA(0, 1, At, B1); PG8_BAR; PG8_SCHED;
	s_setprio 1
	s_waitcnt lgkmcnt(0)
	v_mfma_f32_16x16x32_bf16 v[62:65], v[146:149], v[186:189], v[62:65]
	v_mfma_f32_16x16x32_bf16 v[58:61], v[162:165], v[186:189], v[58:61]
	v_mfma_f32_16x16x32_bf16 v[50:53], v[146:149], v[194:197], v[50:53]
	v_mfma_f32_16x16x32_bf16 v[42:45], v[162:165], v[194:197], v[42:45]
	v_mfma_f32_16x16x32_bf16 v[34:37], v[146:149], v[202:205], v[34:37]
	v_mfma_f32_16x16x32_bf16 v[26:29], v[162:165], v[202:205], v[26:29]
	v_mfma_f32_16x16x32_bf16 v[18:21], v[146:149], v[210:213], v[18:21]
	v_mfma_f32_16x16x32_bf16 v[10:13], v[162:165], v[210:213], v[10:13]
	v_mfma_f32_16x16x32_bf16 v[62:65], v[158:161], v[190:193], v[62:65]
	v_mfma_f32_16x16x32_bf16 v[58:61], v[166:169], v[190:193], v[58:61]
	v_mfma_f32_16x16x32_bf16 v[50:53], v[158:161], v[198:201], v[50:53]
	v_mfma_f32_16x16x32_bf16 v[42:45], v[166:169], v[198:201], v[42:45]
	v_mfma_f32_16x16x32_bf16 v[34:37], v[158:161], v[206:209], v[34:37]
	v_mfma_f32_16x16x32_bf16 v[26:29], v[166:169], v[206:209], v[26:29]
	v_mfma_f32_16x16x32_bf16 v[18:21], v[158:161], v[218:221], v[18:21]
	v_mfma_f32_16x16x32_bf16 v[10:13], v[166:169], v[218:221], v[10:13]
	s_setprio 0
	s_setprio 1
	v_mfma_f32_16x16x32_bf16 v[54:57], v[170:173], v[186:189], v[54:57]
	v_mfma_f32_16x16x32_bf16 v[46:49], v[178:181], v[186:189], v[46:49]
	v_mfma_f32_16x16x32_bf16 v[38:41], v[170:173], v[194:197], v[38:41]
	v_mfma_f32_16x16x32_bf16 v[30:33], v[178:181], v[194:197], v[30:33]
	v_mfma_f32_16x16x32_bf16 v[22:25], v[170:173], v[202:205], v[22:25]
	v_mfma_f32_16x16x32_bf16 v[14:17], v[178:181], v[202:205], v[14:17]
	v_mfma_f32_16x16x32_bf16 v[6:9], v[170:173], v[210:213], v[6:9]
	v_mfma_f32_16x16x32_bf16 v[2:5], v[178:181], v[210:213], v[2:5]
	v_mfma_f32_16x16x32_bf16 v[54:57], v[174:177], v[190:193], v[54:57]
	v_mfma_f32_16x16x32_bf16 v[46:49], v[182:185], v[190:193], v[46:49]
	v_mfma_f32_16x16x32_bf16 v[38:41], v[174:177], v[198:201], v[38:41]
	v_mfma_f32_16x16x32_bf16 v[30:33], v[182:185], v[198:201], v[30:33]
	v_mfma_f32_16x16x32_bf16 v[22:25], v[174:177], v[206:209], v[22:25]
	v_mfma_f32_16x16x32_bf16 v[14:17], v[182:185], v[206:209], v[14:17]
	v_mfma_f32_16x16x32_bf16 v[6:9], v[174:177], v[218:221], v[6:9]
	v_mfma_f32_16x16x32_bf16 v[2:5], v[182:185], v[218:221], v[2:5]
	s_setprio 0
	s_barrier
	s_add_i32 s54, 0, 0x18000
	v_add_u32_e32 v150, s54, v151
	s_add_i32 s55, 0, 0x1c000
	ds_read_b128 v[146:149], v150
	ds_read_b128 v[158:161], v150 offset:1024
	ds_read_b128 v[162:165], v150 offset:2048
	ds_read_b128 v[166:169], v150 offset:3072
	v_add_u32_e32 v150, s55, v151
	ds_read_b128 v[170:173], v150
	ds_read_b128 v[174:177], v150 offset:1024
	ds_read_b128 v[178:181], v150 offset:2048
	ds_read_b128 v[182:185], v150 offset:3072
	s_add_u32 s28, s28, 0x100000
	s_addc_u32 s29, s29, 0
	s_mov_b32 m0, s39
	v_lshl_add_u64 v[228:229], s[28:29], 0, v[136:137]
	ds_read_b128 v[186:189], v157 offset:32768
	ds_read_b128 v[190:193], v157 offset:33792
	ds_read_b128 v[194:197], v157 offset:34816
	ds_read_b128 v[198:201], v157 offset:35840
	ds_read_b128 v[202:205], v157 offset:36864
	ds_read_b128 v[206:209], v157 offset:37888
	ds_read_b128 v[210:213], v157 offset:38912
	ds_read_b128 v[218:221], v157 offset:39936
	global_load_lds_dwordx4 v[228:229], off
	v_lshl_add_u64 v[228:229], s[28:29], 0, v[132:133]
	s_mov_b32 m0, s40
	s_nop 0
	global_load_lds_dwordx4 v[228:229], off
	s_waitcnt vmcnt(8)
	s_waitcnt lgkmcnt(0)
	s_barrier
	s_setprio 1
	s_waitcnt lgkmcnt(0)
	v_mfma_f32_16x16x32_bf16 v[126:129], v[146:149], v[186:189], v[126:129]
	v_mfma_f32_16x16x32_bf16 v[122:125], v[162:165], v[186:189], v[122:125]
	v_mfma_f32_16x16x32_bf16 v[118:121], v[146:149], v[194:197], v[118:121]
	v_mfma_f32_16x16x32_bf16 v[114:117], v[162:165], v[194:197], v[114:117]
	v_mfma_f32_16x16x32_bf16 v[106:109], v[146:149], v[202:205], v[106:109]
	v_mfma_f32_16x16x32_bf16 v[98:101], v[162:165], v[202:205], v[98:101]
	v_mfma_f32_16x16x32_bf16 v[78:81], v[146:149], v[210:213], v[78:81]
	v_mfma_f32_16x16x32_bf16 v[74:77], v[162:165], v[210:213], v[74:77]
	v_mfma_f32_16x16x32_bf16 v[126:129], v[158:161], v[190:193], v[126:129]
	v_mfma_f32_16x16x32_bf16 v[122:125], v[166:169], v[190:193], v[122:125]
	v_mfma_f32_16x16x32_bf16 v[118:121], v[158:161], v[198:201], v[118:121]
	v_mfma_f32_16x16x32_bf16 v[114:117], v[166:169], v[198:201], v[114:117]
	v_mfma_f32_16x16x32_bf16 v[106:109], v[158:161], v[206:209], v[106:109]
	v_mfma_f32_16x16x32_bf16 v[98:101], v[166:169], v[206:209], v[98:101]
	v_mfma_f32_16x16x32_bf16 v[78:81], v[158:161], v[218:221], v[78:81]
	v_mfma_f32_16x16x32_bf16 v[74:77], v[166:169], v[218:221], v[74:77]
	s_setprio 0
	s_setprio 1
	v_mfma_f32_16x16x32_bf16 v[110:113], v[170:173], v[186:189], v[110:113]
	v_mfma_f32_16x16x32_bf16 v[102:105], v[178:181], v[186:189], v[102:105]
	v_mfma_f32_16x16x32_bf16 v[94:97], v[170:173], v[194:197], v[94:97]
	v_mfma_f32_16x16x32_bf16 v[90:93], v[178:181], v[194:197], v[90:93]
	v_mfma_f32_16x16x32_bf16 v[86:89], v[170:173], v[202:205], v[86:89]
	v_mfma_f32_16x16x32_bf16 v[82:85], v[178:181], v[202:205], v[82:85]
	v_mfma_f32_16x16x32_bf16 v[70:73], v[170:173], v[210:213], v[70:73]
	v_mfma_f32_16x16x32_bf16 v[66:69], v[178:181], v[210:213], v[66:69]
	v_mfma_f32_16x16x32_bf16 v[110:113], v[174:177], v[190:193], v[110:113]
	v_mfma_f32_16x16x32_bf16 v[102:105], v[182:185], v[190:193], v[102:105]
	v_mfma_f32_16x16x32_bf16 v[94:97], v[174:177], v[198:201], v[94:97]
	v_mfma_f32_16x16x32_bf16 v[90:93], v[182:185], v[198:201], v[90:93]
	v_mfma_f32_16x16x32_bf16 v[86:89], v[174:177], v[206:209], v[86:89]
	v_mfma_f32_16x16x32_bf16 v[82:85], v[182:185], v[206:209], v[82:85]
	v_mfma_f32_16x16x32_bf16 v[70:73], v[174:177], v[218:221], v[70:73]
	v_mfma_f32_16x16x32_bf16 v[66:69], v[182:185], v[218:221], v[66:69]
	s_setprio 0
	s_barrier
; #define PG8_STAGE(bufoff, gbase, voff) do { _Pragma("unroll") for (int _i = 0; _i < 2; ++_i) \
;         __builtin_amdgcn_global_load_lds((const unsigned*)((const char*)(gbase) + (voff)[_i]), (PG8_LAS unsigned*)(lds + (bufoff) + ldsw + _i * 8192), 16, 0, 0); } while (0)
; #define PG8_LDA(dst, b, h) do { _Pragma("unroll") for (int m = 0; m < 4; ++m) _Pragma("unroll") for (int k = 0; k < 2; ++k) dst[m][k] = *(const PG8_LAS bf16x8*)(lds + PG8_SA(b, h) + aoff + m * 2048 + k * 1024); } while (0)
; #define PG8_MMA(ai, bj, At, Bt) do { __builtin_amdgcn_s_setprio(1); _Pragma("unroll") for (int m = 0; m < 4; ++m) _Pragma("unroll") for (int n = 0; n < 2; ++n) _Pragma("unroll") for (int k = 0; k < 2; ++k) \
;         acc[ai][bj][m][n] = __builtin_amdgcn_mfma_f32_16x16x32_bf16(Bt[n][k], At[m][k], acc[ai][bj][m][n], 0, 0, 0); __builtin_amdgcn_s_setprio(0); } while (0)
; #define PG8_WAIT_V(n) asm volatile("s_waitcnt vmcnt(" #n ")" ::: "memory")
; #define PG8_WAIT_L(n) asm volatile("s_waitcnt lgkmcnt(" #n ")" ::: "memory")
; #define PG8_BAR __builtin_amdgcn_s_barrier()
; #define PG8_SCHED __builtin_amdgcn_sched_barrier(0)
; template <class Epi, class Sched, bool ALIGN_EPI = false, bool SP2 = false>
; __device__ __forceinline__ void gemm_phase(PG8_LAS unsigned char* lds, const Gemm g, const Sched& S, const Epi& E) {
;     ...
;         for (int t = 0; t < nt; t += 2) {
;             const bool last = (t == nt - 2);
;             const char* a1 = cA + (size_t)(t + 1) * kstep;
;             const char* a2 = last ? nA : cA + (size_t)(t + 2) * kstep; const char* b2 = last ? nB : cB + (size_t)(t + 2) * kstep;
;     ...
;             PG8_LDA(At, 1, 1); PG8_STAGE(PG8_SB(1, 0), b3, voffB); PG8_STAGE(PG8_SB(1, 1), b3 + hstepB, voffB); PG8_STAGE(PG8_SA(1, 0), a3, voffA);
;             PG8_WAIT_V(8); PG8_WAIT_L(0); PG8_BAR; PG8_MMA(1, 0, At, B0); PG8_MMA(1, 1, At, B1); PG8_BAR; PG8_SCHED;
	s_add_i32 s28, s54, s35
	v_lshl_add_u64 v[214:215], v[214:215], 0, s[10:11]
	s_mov_b32 m0, s28
	global_load_lds_dwordx4 v[214:215], off
	s_add_i32 m0, s28, 0x2000
	s_add_u32 s26, s26, 0x100080
	v_lshl_add_u64 v[214:215], v[222:223], 0, s[10:11]
	s_addc_u32 s27, s27, 0
	s_add_i32 s28, s55, s35
	global_load_lds_dwordx4 v[214:215], off
	v_lshl_add_u64 v[214:215], s[26:27], 0, v[134:135]
	s_mov_b32 m0, s28
	s_nop 0
	global_load_lds_dwordx4 v[214:215], off
	v_lshl_add_u64 v[214:215], s[26:27], 0, v[130:131]
	s_add_i32 m0, s28, 0x2000
	s_nop 0
	global_load_lds_dwordx4 v[214:215], off
	v_lshl_add_u64 v[214:215], v[224:225], 0, s[10:11]
	s_mov_b32 m0, s42
	s_nop 0
	global_load_lds_dwordx4 v[214:215], off
	v_lshl_add_u64 v[214:215], v[226:227], 0, s[10:11]
	s_mov_b32 m0, s43
	s_nop 0
	global_load_lds_dwordx4 v[214:215], off
	ds_read_b128 v[186:189], v157 offset:49152
	ds_read_b128 v[190:193], v157 offset:50176
	ds_read_b128 v[194:197], v157 offset:51200
	ds_read_b128 v[198:201], v157 offset:52224
	ds_read_b128 v[202:205], v157 offset:53248
	ds_read_b128 v[206:209], v157 offset:54272
	ds_read_b128 v[210:213], v157 offset:55296
	ds_read_b128 v[218:221], v157 offset:56320
	s_waitcnt vmcnt(8)
	s_waitcnt lgkmcnt(0)
	s_barrier
	s_setprio 1
	s_waitcnt lgkmcnt(0)
	v_mfma_f32_16x16x32_bf16 v[62:65], v[146:149], v[186:189], v[62:65]
	v_mfma_f32_16x16x32_bf16 v[58:61], v[162:165], v[186:189], v[58:61]
	v_mfma_f32_16x16x32_bf16 v[50:53], v[146:149], v[194:197], v[50:53]
	v_mfma_f32_16x16x32_bf16 v[42:45], v[162:165], v[194:197], v[42:45]
	v_mfma_f32_16x16x32_bf16 v[34:37], v[146:149], v[202:205], v[34:37]
	v_mfma_f32_16x16x32_bf16 v[26:29], v[162:165], v[202:205], v[26:29]
	v_mfma_f32_16x16x32_bf16 v[18:21], v[146:149], v[210:213], v[18:21]
	v_mfma_f32_16x16x32_bf16 v[10:13], v[162:165], v[210:213], v[10:13]
	v_mfma_f32_16x16x32_bf16 v[62:65], v[158:161], v[190:193], v[62:65]
	v_mfma_f32_16x16x32_bf16 v[58:61], v[166:169], v[190:193], v[58:61]
	v_mfma_f32_16x16x32_bf16 v[50:53], v[158:161], v[198:201], v[50:53]
	v_mfma_f32_16x16x32_bf16 v[42:45], v[166:169], v[198:201], v[42:45]
	v_mfma_f32_16x16x32_bf16 v[34:37], v[158:161], v[206:209], v[34:37]
	v_mfma_f32_16x16x32_bf16 v[26:29], v[166:169], v[206:209], v[26:29]
	v_mfma_f32_16x16x32_bf16 v[18:21], v[158:161], v[218:221], v[18:21]
	v_mfma_f32_16x16x32_bf16 v[10:13], v[166:169], v[218:221], v[10:13]
	s_setprio 0
	s_setprio 1
	v_mfma_f32_16x16x32_bf16 v[54:57], v[170:173], v[186:189], v[54:57]
	v_mfma_f32_16x16x32_bf16 v[46:49], v[178:181], v[186:189], v[46:49]
	v_mfma_f32_16x16x32_bf16 v[38:41], v[170:173], v[194:197], v[38:41]
	v_mfma_f32_16x16x32_bf16 v[30:33], v[178:181], v[194:197], v[30:33]
	v_mfma_f32_16x16x32_bf16 v[22:25], v[170:173], v[202:205], v[22:25]
	v_mfma_f32_16x16x32_bf16 v[14:17], v[178:181], v[202:205], v[14:17]
	v_mfma_f32_16x16x32_bf16 v[6:9], v[170:173], v[210:213], v[6:9]
	v_mfma_f32_16x16x32_bf16 v[2:5], v[178:181], v[210:213], v[2:5]
	v_mfma_f32_16x16x32_bf16 v[54:57], v[174:177], v[190:193], v[54:57]
	v_mfma_f32_16x16x32_bf16 v[46:49], v[182:185], v[190:193], v[46:49]
	v_mfma_f32_16x16x32_bf16 v[38:41], v[174:177], v[198:201], v[38:41]
	v_mfma_f32_16x16x32_bf16 v[30:33], v[182:185], v[198:201], v[30:33]
	v_mfma_f32_16x16x32_bf16 v[22:25], v[174:177], v[206:209], v[22:25]
	v_mfma_f32_16x16x32_bf16 v[14:17], v[182:185], v[206:209], v[14:17]
	v_mfma_f32_16x16x32_bf16 v[6:9], v[174:177], v[218:221], v[6:9]
	v_mfma_f32_16x16x32_bf16 v[2:5], v[182:185], v[218:221], v[2:5]
	s_setprio 0
	s_barrier
	s_add_i32 s53, s53, 2
	s_add_u32 s24, s24, 0x100
	s_addc_u32 s25, s25, 0
	s_add_u32 s51, s51, 0x100
	s_addc_u32 s52, s52, 0
	s_cmp_gt_u32 s53, 61
	s_cbranch_scc0 .LBB0_210
	s_and_b64 vcc, exec, s[12:13]
	s_cbranch_vccz .LBB0_213
	s_barrier

; #define PG8_STAGE(bufoff, gbase, voff) do { _Pragma("unroll") for (int _i = 0; _i < 2; ++_i) \
;         __builtin_amdgcn_global_load_lds((const unsigned*)((const char*)(gbase) + (voff)[_i]), (PG8_LAS unsigned*)(lds + (bufoff) + ldsw + _i * 8192), 16, 0, 0); } while (0)
; #define PG8_LDA(dst, b, h) do { _Pragma("unroll") for (int m = 0; m < 4; ++m) _Pragma("unroll") for (int k = 0; k < 2; ++k) dst[m][k] = *(const PG8_LAS bf16x8*)(lds + PG8_SA(b, h) + aoff + m * 2048 + k * 1024); } while (0)
; #define PG8_LDB(dst, b, h) do { _Pragma("unroll") for (int n = 0; n < 2; ++n) _Pragma("unroll") for (int k = 0; k < 2; ++k) dst[n][k] = *(const PG8_LAS bf16x8*)(lds + PG8_SB(b, h) + boff + n * 2048 + k * 1024); } while (0)
; #define PG8_MMA(ai, bj, At, Bt) do { __builtin_amdgcn_s_setprio(1); _Pragma("unroll") for (int m = 0; m < 4; ++m) _Pragma("unroll") for (int n = 0; n < 2; ++n) _Pragma("unroll") for (int k = 0; k < 2; ++k) \
;         acc[ai][bj][m][n] = __builtin_amdgcn_mfma_f32_16x16x32_bf16(Bt[n][k], At[m][k], acc[ai][bj][m][n], 0, 0, 0); __builtin_amdgcn_s_setprio(0); } while (0)
; #define PG8_WAIT_V(n) asm volatile("s_waitcnt vmcnt(" #n ")" ::: "memory")
; #define PG8_WAIT_L(n) asm volatile("s_waitcnt lgkmcnt(" #n ")" ::: "memory")
; template <class Epi, class Sched, bool ALIGN_EPI = false, bool SP2 = false>
; __device__ __forceinline__ void gemm_phase(PG8_LAS unsigned char* lds, const Gemm g, const Sched& S, const Epi& E) {
;     ...
;             const bool last = (t == nt - 2);
;             const char* a1 = cA + (size_t)(t + 1) * kstep;
;             const char* a2 = last ? nA : cA + (size_t)(t + 2) * kstep; const char* b2 = last ? nB : cB + (size_t)(t + 2) * kstep;
;             const char* a3 = a2 + kstep; const char* b3 = b2 + kstep;
;             if (last && has_next) S.a_ready(nxt);
;             if constexpr (SP2) {
;             PG8_LDB(B0, 0, 0); PG8_LDB(B1, 0, 1); PG8_SCHED; PG8_LDA(At, 0, 0); PG8_STAGE(PG8_SA(1, 1), a1 + hstepA, voffA);
;             PG8_WAIT_V(8); PG8_WAIT_L(0); PG8_BAR; PG8_MMA(0, 0, At, B0); PG8_MMA(0, 1, At, B1); PG8_BAR; PG8_SCHED;
;             PG8_LDA(At, 0, 1); PG8_STAGE(PG8_SB(0, 0), b2, voffB); PG8_STAGE(PG8_SB(0, 1), b2 + hstepB, voffB); PG8_STAGE(PG8_SA(0, 0), a2, voffA);
;             PG8_WAIT_V(8); PG8_WAIT_L(0); PG8_BAR; PG8_MMA(1, 0, At, B0); PG8_MMA(1, 1, At, B1); PG8_BAR; PG8_SCHED;
.LBB0_241:
	s_lshl_b32 s26, s54, 7
	s_add_u32 s27, s16, s26
	s_addc_u32 s28, s17, 0
	v_add_u32_e32 v170, s46, v1
	s_add_u32 s29, s27, 0x100
	ds_read_b128 v[178:181], v170
	ds_read_b128 v[182:185], v170 offset:1024
	ds_read_b128 v[186:189], v170 offset:2048
	ds_read_b128 v[190:193], v170 offset:3072
	v_add_u32_e32 v170, s47, v1
	s_addc_u32 s55, s28, 0
	ds_read_b128 v[194:197], v170
	ds_read_b128 v[198:201], v170 offset:1024
	ds_read_b128 v[202:205], v170 offset:2048
	ds_read_b128 v[206:209], v170 offset:3072
	s_and_b64 s[24:25], s[22:23], exec
	s_cselect_b32 s25, s50, s55
	s_cselect_b32 s24, s51, s29
	s_add_u32 s26, s18, s26
	s_addc_u32 s29, s19, 0
	s_add_u32 s26, s26, 0x100
	s_addc_u32 s29, s29, 0
	s_and_b64 s[22:23], s[22:23], exec
	s_cselect_b32 s23, s52, s29
	s_cselect_b32 s22, s53, s26
	s_add_u32 s26, s27, 0x100080
	s_addc_u32 s27, s28, 0
	v_lshl_add_u64 v[214:215], s[26:27], 0, v[132:133]
	s_add_i32 m0, s1, 0xc000
	ds_read_b128 v[210:213], v175
	ds_read_b128 v[218:221], v175 offset:1024
	ds_read_b128 v[222:225], v175 offset:2048
	ds_read_b128 v[226:229], v175 offset:3072
	ds_read_b128 v[230:233], v175 offset:4096
	ds_read_b128 v[234:237], v175 offset:5120
	ds_read_b128 v[238:241], v175 offset:6144
	ds_read_b128 v[242:245], v175 offset:7168
	global_load_lds_dwordx4 v[214:215], off
	v_lshl_add_u64 v[214:215], s[26:27], 0, v[134:135]
	s_add_i32 m0, s1, 0xe000
	s_nop 0
	global_load_lds_dwordx4 v[214:215], off
	s_waitcnt vmcnt(8)
	s_waitcnt lgkmcnt(0)
	s_barrier
	s_setprio 1
	s_waitcnt lgkmcnt(0)
	v_mfma_f32_16x16x32_bf16 v[126:129], v[178:181], v[210:213], v[126:129]
	v_mfma_f32_16x16x32_bf16 v[122:125], v[186:189], v[210:213], v[122:125]
	v_mfma_f32_16x16x32_bf16 v[118:121], v[178:181], v[222:225], v[118:121]
	v_mfma_f32_16x16x32_bf16 v[114:117], v[186:189], v[222:225], v[114:117]
	v_mfma_f32_16x16x32_bf16 v[110:113], v[178:181], v[230:233], v[110:113]
	v_mfma_f32_16x16x32_bf16 v[102:105], v[186:189], v[230:233], v[102:105]
	v_mfma_f32_16x16x32_bf16 v[94:97], v[178:181], v[238:241], v[94:97]
	v_mfma_f32_16x16x32_bf16 v[86:89], v[186:189], v[238:241], v[86:89]
	v_mfma_f32_16x16x32_bf16 v[126:129], v[182:185], v[218:221], v[126:129]
	v_mfma_f32_16x16x32_bf16 v[122:125], v[190:193], v[218:221], v[122:125]
	v_mfma_f32_16x16x32_bf16 v[118:121], v[182:185], v[226:229], v[118:121]
	v_mfma_f32_16x16x32_bf16 v[114:117], v[190:193], v[226:229], v[114:117]
	v_mfma_f32_16x16x32_bf16 v[110:113], v[182:185], v[234:237], v[110:113]
	v_mfma_f32_16x16x32_bf16 v[102:105], v[190:193], v[234:237], v[102:105]
	v_mfma_f32_16x16x32_bf16 v[94:97], v[182:185], v[242:245], v[94:97]
	v_mfma_f32_16x16x32_bf16 v[86:89], v[190:193], v[242:245], v[86:89]
	s_setprio 0
	s_setprio 1
	v_mfma_f32_16x16x32_bf16 v[106:109], v[194:197], v[210:213], v[106:109]
	v_mfma_f32_16x16x32_bf16 v[98:101], v[202:205], v[210:213], v[98:101]
	v_mfma_f32_16x16x32_bf16 v[90:93], v[194:197], v[222:225], v[90:93]
	v_mfma_f32_16x16x32_bf16 v[82:85], v[202:205], v[222:225], v[82:85]
	v_mfma_f32_16x16x32_bf16 v[78:81], v[194:197], v[230:233], v[78:81]
	v_mfma_f32_16x16x32_bf16 v[74:77], v[202:205], v[230:233], v[74:77]
	v_mfma_f32_16x16x32_bf16 v[70:73], v[194:197], v[238:241], v[70:73]
	v_mfma_f32_16x16x32_bf16 v[66:69], v[202:205], v[238:241], v[66:69]
	v_mfma_f32_16x16x32_bf16 v[106:109], v[198:201], v[218:221], v[106:109]
	v_mfma_f32_16x16x32_bf16 v[98:101], v[206:209], v[218:221], v[98:101]
	v_mfma_f32_16x16x32_bf16 v[90:93], v[198:201], v[226:229], v[90:93]
	v_mfma_f32_16x16x32_bf16 v[82:85], v[206:209], v[226:229], v[82:85]
	v_mfma_f32_16x16x32_bf16 v[78:81], v[198:201], v[234:237], v[78:81]
	v_mfma_f32_16x16x32_bf16 v[74:77], v[206:209], v[234:237], v[74:77]
	v_mfma_f32_16x16x32_bf16 v[70:73], v[198:201], v[242:245], v[70:73]
	v_mfma_f32_16x16x32_bf16 v[66:69], v[206:209], v[242:245], v[66:69]
	s_setprio 0
	s_barrier
	s_add_i32 s26, s46, s39
	v_lshl_add_u64 v[214:215], s[22:23], 0, v[130:131]
	s_mov_b32 m0, s26
	global_load_lds_dwordx4 v[214:215], off
	s_add_i32 m0, s26, 0x2000
	s_add_u32 s26, s22, 0x100000
	v_lshl_add_u64 v[246:247], s[22:23], 0, v[136:137]
	s_addc_u32 s27, s23, 0
	s_add_i32 s28, s47, s39
	global_load_lds_dwordx4 v[246:247], off
	v_lshl_add_u64 v[248:249], s[26:27], 0, v[130:131]
	s_mov_b32 m0, s28
	v_lshl_add_u64 v[250:251], s[24:25], 0, v[134:135]
	global_load_lds_dwordx4 v[248:249], off
	v_lshl_add_u64 v[248:249], s[26:27], 0, v[136:137]
	s_add_i32 m0, s28, 0x2000
	s_nop 0
	global_load_lds_dwordx4 v[248:249], off
	v_lshl_add_u64 v[248:249], s[24:25], 0, v[132:133]
	s_mov_b32 m0, s1
	s_nop 0
	global_load_lds_dwordx4 v[248:249], off
	s_mov_b32 m0, s40
	s_nop 0
	global_load_lds_dwordx4 v[250:251], off
	ds_read_b128 v[210:213], v175 offset:16384
	ds_read_b128 v[218:221], v175 offset:17408
	ds_read_b128 v[222:225], v175 offset:18432
	ds_read_b128 v[226:229], v175 offset:19456
	ds_read_b128 v[230:233], v175 offset:20480
	ds_read_b128 v[234:237], v175 offset:21504
	ds_read_b128 v[238:241], v175 offset:22528
	ds_read_b128 v[242:245], v175 offset:23552
	s_waitcnt vmcnt(8)
	s_waitcnt lgkmcnt(0)
	s_barrier
; #define PG8_STAGE(bufoff, gbase, voff) do { _Pragma("unroll") for (int _i = 0; _i < 2; ++_i) \
;         __builtin_amdgcn_global_load_lds((const unsigned*)((const char*)(gbase) + (voff)[_i]), (PG8_LAS unsigned*)(lds + (bufoff) + ldsw + _i * 8192), 16, 0, 0); } while (0)
; #define PG8_LDA(dst, b, h) do { _Pragma("unroll") for (int m = 0; m < 4; ++m) _Pragma("unroll") for (int k = 0; k < 2; ++k) dst[m][k] = *(const PG8_LAS bf16x8*)(lds + PG8_SA(b, h) + aoff + m * 2048 + k * 1024); } while (0)
; #define PG8_LDB(dst, b, h) do { _Pragma("unroll") for (int n = 0; n < 2; ++n) _Pragma("unroll") for (int k = 0; k < 2; ++k) dst[n][k] = *(const PG8_LAS bf16x8*)(lds + PG8_SB(b, h) + boff + n * 2048 + k * 1024); } while (0)
; #define PG8_MMA(ai, bj, At, Bt) do { __builtin_amdgcn_s_setprio(1); _Pragma("unroll") for (int m = 0; m < 4; ++m) _Pragma("unroll") for (int n = 0; n < 2; ++n) _Pragma("unroll") for (int k = 0; k < 2; ++k) \
;         acc[ai][bj][m][n] = __builtin_amdgcn_mfma_f32_16x16x32_bf16(Bt[n][k], At[m][k], acc[ai][bj][m][n], 0, 0, 0); __builtin_amdgcn_s_setprio(0); } while (0)
; #define PG8_WAIT_V(n) asm volatile("s_waitcnt vmcnt(" #n ")" ::: "memory")
; #define PG8_WAIT_L(n) asm volatile("s_waitcnt lgkmcnt(" #n ")" ::: "memory")
; #define PG8_BAR __builtin_amdgcn_s_barrier()
; #define PG8_SCHED __builtin_amdgcn_sched_barrier(0)
; template <class Epi, class Sched, bool ALIGN_EPI = false, bool SP2 = false>
; __device__ __forceinline__ void gemm_phase(PG8_LAS unsigned char* lds, const Gemm g, const Sched& S, const Epi& E) {
;     ...
;             PG8_WAIT_V(8); PG8_WAIT_L(0); PG8_BAR; PG8_MMA(1, 0, At, B0); PG8_MMA(1, 1, At, B1); PG8_BAR; PG8_SCHED;
;             PG8_LDB(B0, 1, 0); PG8_LDB(B1, 1, 1); PG8_SCHED; PG8_LDA(At, 1, 0); PG8_STAGE(PG8_SA(0, 1), a2 + hstepA, voffA);
;             PG8_WAIT_V(8); PG8_WAIT_L(0); PG8_BAR; PG8_MMA(0, 0, At, B0); PG8_MMA(0, 1, At, B1); PG8_BAR; PG8_SCHED;
	s_setprio 1
	s_waitcnt lgkmcnt(0)
	v_mfma_f32_16x16x32_bf16 v[62:65], v[178:181], v[210:213], v[62:65]
	v_mfma_f32_16x16x32_bf16 v[58:61], v[186:189], v[210:213], v[58:61]
	v_mfma_f32_16x16x32_bf16 v[50:53], v[178:181], v[222:225], v[50:53]
	v_mfma_f32_16x16x32_bf16 v[42:45], v[186:189], v[222:225], v[42:45]
	v_mfma_f32_16x16x32_bf16 v[34:37], v[178:181], v[230:233], v[34:37]
	v_mfma_f32_16x16x32_bf16 v[26:29], v[186:189], v[230:233], v[26:29]
	v_mfma_f32_16x16x32_bf16 v[18:21], v[178:181], v[238:241], v[18:21]
	v_mfma_f32_16x16x32_bf16 v[10:13], v[186:189], v[238:241], v[10:13]
	v_mfma_f32_16x16x32_bf16 v[62:65], v[182:185], v[218:221], v[62:65]
	v_mfma_f32_16x16x32_bf16 v[58:61], v[190:193], v[218:221], v[58:61]
	v_mfma_f32_16x16x32_bf16 v[50:53], v[182:185], v[226:229], v[50:53]
	v_mfma_f32_16x16x32_bf16 v[42:45], v[190:193], v[226:229], v[42:45]
	v_mfma_f32_16x16x32_bf16 v[34:37], v[182:185], v[234:237], v[34:37]
	v_mfma_f32_16x16x32_bf16 v[26:29], v[190:193], v[234:237], v[26:29]
	v_mfma_f32_16x16x32_bf16 v[18:21], v[182:185], v[242:245], v[18:21]
	v_mfma_f32_16x16x32_bf16 v[10:13], v[190:193], v[242:245], v[10:13]
	s_setprio 0
	s_setprio 1
	v_mfma_f32_16x16x32_bf16 v[54:57], v[194:197], v[210:213], v[54:57]
	v_mfma_f32_16x16x32_bf16 v[46:49], v[202:205], v[210:213], v[46:49]
	v_mfma_f32_16x16x32_bf16 v[38:41], v[194:197], v[222:225], v[38:41]
	v_mfma_f32_16x16x32_bf16 v[30:33], v[202:205], v[222:225], v[30:33]
	v_mfma_f32_16x16x32_bf16 v[22:25], v[194:197], v[230:233], v[22:25]
	v_mfma_f32_16x16x32_bf16 v[14:17], v[202:205], v[230:233], v[14:17]
	v_mfma_f32_16x16x32_bf16 v[6:9], v[194:197], v[238:241], v[6:9]
	v_mfma_f32_16x16x32_bf16 v[2:5], v[202:205], v[238:241], v[2:5]
	v_mfma_f32_16x16x32_bf16 v[54:57], v[198:201], v[218:221], v[54:57]
	v_mfma_f32_16x16x32_bf16 v[46:49], v[206:209], v[218:221], v[46:49]
	v_mfma_f32_16x16x32_bf16 v[38:41], v[198:201], v[226:229], v[38:41]
	v_mfma_f32_16x16x32_bf16 v[30:33], v[206:209], v[226:229], v[30:33]
	v_mfma_f32_16x16x32_bf16 v[22:25], v[198:201], v[234:237], v[22:25]
	v_mfma_f32_16x16x32_bf16 v[14:17], v[206:209], v[234:237], v[14:17]
	v_mfma_f32_16x16x32_bf16 v[6:9], v[198:201], v[242:245], v[6:9]
	v_mfma_f32_16x16x32_bf16 v[2:5], v[206:209], v[242:245], v[2:5]
	s_setprio 0
	s_barrier
	s_add_i32 s26, 0, 0x18000
	v_add_u32_e32 v170, s26, v1
	s_add_i32 s27, 0, 0x1c000
	ds_read_b128 v[178:181], v170
	ds_read_b128 v[182:185], v170 offset:1024
	ds_read_b128 v[186:189], v170 offset:2048
	ds_read_b128 v[190:193], v170 offset:3072
	v_add_u32_e32 v170, s27, v1
	ds_read_b128 v[194:197], v170
	ds_read_b128 v[198:201], v170 offset:1024
	ds_read_b128 v[202:205], v170 offset:2048
	ds_read_b128 v[206:209], v170 offset:3072
	s_add_u32 s24, s24, 0x100000
	s_addc_u32 s25, s25, 0
	s_mov_b32 m0, s41
	v_lshl_add_u64 v[252:253], s[24:25], 0, v[132:133]
	ds_read_b128 v[210:213], v175 offset:32768
	ds_read_b128 v[218:221], v175 offset:33792
	ds_read_b128 v[222:225], v175 offset:34816
	ds_read_b128 v[226:229], v175 offset:35840
	ds_read_b128 v[230:233], v175 offset:36864
	ds_read_b128 v[234:237], v175 offset:37888
	ds_read_b128 v[238:241], v175 offset:38912
	ds_read_b128 v[242:245], v175 offset:39936
	global_load_lds_dwordx4 v[252:253], off
	v_lshl_add_u64 v[252:253], s[24:25], 0, v[134:135]
	s_mov_b32 m0, s42
	s_nop 0
	global_load_lds_dwordx4 v[252:253], off
	s_waitcnt vmcnt(8)
	s_waitcnt lgkmcnt(0)
	s_barrier
	s_setprio 1
	s_waitcnt lgkmcnt(0)
	v_mfma_f32_16x16x32_bf16 v[126:129], v[178:181], v[210:213], v[126:129]
	v_mfma_f32_16x16x32_bf16 v[122:125], v[186:189], v[210:213], v[122:125]
	v_mfma_f32_16x16x32_bf16 v[118:121], v[178:181], v[222:225], v[118:121]
	v_mfma_f32_16x16x32_bf16 v[114:117], v[186:189], v[222:225], v[114:117]
	v_mfma_f32_16x16x32_bf16 v[110:113], v[178:181], v[230:233], v[110:113]
	v_mfma_f32_16x16x32_bf16 v[102:105], v[186:189], v[230:233], v[102:105]
	v_mfma_f32_16x16x32_bf16 v[94:97], v[178:181], v[238:241], v[94:97]
	v_mfma_f32_16x16x32_bf16 v[86:89], v[186:189], v[238:241], v[86:89]
	v_mfma_f32_16x16x32_bf16 v[126:129], v[182:185], v[218:221], v[126:129]
	v_mfma_f32_16x16x32_bf16 v[122:125], v[190:193], v[218:221], v[122:125]
	v_mfma_f32_16x16x32_bf16 v[118:121], v[182:185], v[226:229], v[118:121]
	v_mfma_f32_16x16x32_bf16 v[114:117], v[190:193], v[226:229], v[114:117]
	v_mfma_f32_16x16x32_bf16 v[110:113], v[182:185], v[234:237], v[110:113]
	v_mfma_f32_16x16x32_bf16 v[102:105], v[190:193], v[234:237], v[102:105]
	v_mfma_f32_16x16x32_bf16 v[94:97], v[182:185], v[242:245], v[94:97]
	v_mfma_f32_16x16x32_bf16 v[86:89], v[190:193], v[242:245], v[86:89]
	s_setprio 0
	s_setprio 1
	v_mfma_f32_16x16x32_bf16 v[106:109], v[194:197], v[210:213], v[106:109]
	v_mfma_f32_16x16x32_bf16 v[98:101], v[202:205], v[210:213], v[98:101]
	v_mfma_f32_16x16x32_bf16 v[90:93], v[194:197], v[222:225], v[90:93]
	v_mfma_f32_16x16x32_bf16 v[82:85], v[202:205], v[222:225], v[82:85]
	v_mfma_f32_16x16x32_bf16 v[78:81], v[194:197], v[230:233], v[78:81]
	v_mfma_f32_16x16x32_bf16 v[74:77], v[202:205], v[230:233], v[74:77]
	v_mfma_f32_16x16x32_bf16 v[70:73], v[194:197], v[238:241], v[70:73]
	v_mfma_f32_16x16x32_bf16 v[66:69], v[202:205], v[238:241], v[66:69]
	v_mfma_f32_16x16x32_bf16 v[106:109], v[198:201], v[218:221], v[106:109]
	v_mfma_f32_16x16x32_bf16 v[98:101], v[206:209], v[218:221], v[98:101]
	v_mfma_f32_16x16x32_bf16 v[90:93], v[198:201], v[226:229], v[90:93]
	v_mfma_f32_16x16x32_bf16 v[82:85], v[206:209], v[226:229], v[82:85]
	v_mfma_f32_16x16x32_bf16 v[78:81], v[198:201], v[234:237], v[78:81]
	v_mfma_f32_16x16x32_bf16 v[74:77], v[206:209], v[234:237], v[74:77]
	v_mfma_f32_16x16x32_bf16 v[70:73], v[198:201], v[242:245], v[70:73]
	v_mfma_f32_16x16x32_bf16 v[66:69], v[206:209], v[242:245], v[66:69]
	s_setprio 0
	s_barrier
; #define PG8_STAGE(bufoff, gbase, voff) do { _Pragma("unroll") for (int _i = 0; _i < 2; ++_i) \
;         __builtin_amdgcn_global_load_lds((const unsigned*)((const char*)(gbase) + (voff)[_i]), (PG8_LAS unsigned*)(lds + (bufoff) + ldsw + _i * 8192), 16, 0, 0); } while (0)
; #define PG8_LDA(dst, b, h) do { _Pragma("unroll") for (int m = 0; m < 4; ++m) _Pragma("unroll") for (int k = 0; k < 2; ++k) dst[m][k] = *(const PG8_LAS bf16x8*)(lds + PG8_SA(b, h) + aoff + m * 2048 + k * 1024); } while (0)
; #define PG8_MMA(ai, bj, At, Bt) do { __builtin_amdgcn_s_setprio(1); _Pragma("unroll") for (int m = 0; m < 4; ++m) _Pragma("unroll") for (int n = 0; n < 2; ++n) _Pragma("unroll") for (int k = 0; k < 2; ++k) \
;         acc[ai][bj][m][n] = __builtin_amdgcn_mfma_f32_16x16x32_bf16(Bt[n][k], At[m][k], acc[ai][bj][m][n], 0, 0, 0); __builtin_amdgcn_s_setprio(0); } while (0)
; #define PG8_WAIT_V(n) asm volatile("s_waitcnt vmcnt(" #n ")" ::: "memory")
; #define PG8_WAIT_L(n) asm volatile("s_waitcnt lgkmcnt(" #n ")" ::: "memory")
; #define PG8_BAR __builtin_amdgcn_s_barrier()
; #define PG8_SCHED __builtin_amdgcn_sched_barrier(0)
; template <class Epi, class Sched, bool ALIGN_EPI = false, bool SP2 = false>
; __device__ __forceinline__ void gemm_phase(PG8_LAS unsigned char* lds, const Gemm g, const Sched& S, const Epi& E) {
;     ...
;             PG8_LDA(At, 1, 1); PG8_STAGE(PG8_SB(1, 0), b3, voffB); PG8_STAGE(PG8_SB(1, 1), b3 + hstepB, voffB); PG8_STAGE(PG8_SA(1, 0), a3, voffA);
;             PG8_WAIT_V(8); PG8_WAIT_L(0); PG8_BAR; PG8_MMA(1, 0, At, B0); PG8_MMA(1, 1, At, B1); PG8_BAR; PG8_SCHED;
	s_add_i32 s24, s26, s39
	v_lshl_add_u64 v[214:215], v[214:215], 0, s[10:11]
	s_mov_b32 m0, s24
	global_load_lds_dwordx4 v[214:215], off
	s_add_i32 m0, s24, 0x2000
	s_add_u32 s22, s22, 0x100080
	v_lshl_add_u64 v[214:215], v[246:247], 0, s[10:11]
	s_addc_u32 s23, s23, 0
	s_add_i32 s24, s27, s39
	global_load_lds_dwordx4 v[214:215], off
	v_lshl_add_u64 v[214:215], s[22:23], 0, v[130:131]
	s_mov_b32 m0, s24
	s_nop 0
	global_load_lds_dwordx4 v[214:215], off
	v_lshl_add_u64 v[214:215], s[22:23], 0, v[136:137]
	s_add_i32 m0, s24, 0x2000
	s_nop 0
	global_load_lds_dwordx4 v[214:215], off
	v_lshl_add_u64 v[214:215], v[248:249], 0, s[10:11]
	s_mov_b32 m0, s43
	s_nop 0
	global_load_lds_dwordx4 v[214:215], off
	v_lshl_add_u64 v[214:215], v[250:251], 0, s[10:11]
	s_mov_b32 m0, s44
	s_nop 0
	global_load_lds_dwordx4 v[214:215], off
	ds_read_b128 v[210:213], v175 offset:49152
	ds_read_b128 v[218:221], v175 offset:50176
	ds_read_b128 v[222:225], v175 offset:51200
	ds_read_b128 v[226:229], v175 offset:52224
	ds_read_b128 v[230:233], v175 offset:53248
	ds_read_b128 v[234:237], v175 offset:54272
	ds_read_b128 v[238:241], v175 offset:55296
	ds_read_b128 v[242:245], v175 offset:56320
	s_waitcnt vmcnt(8)
	s_waitcnt lgkmcnt(0)
	s_barrier
	s_setprio 1
	s_waitcnt lgkmcnt(0)
	v_mfma_f32_16x16x32_bf16 v[62:65], v[178:181], v[210:213], v[62:65]
	v_mfma_f32_16x16x32_bf16 v[58:61], v[186:189], v[210:213], v[58:61]
	v_mfma_f32_16x16x32_bf16 v[50:53], v[178:181], v[222:225], v[50:53]
	v_mfma_f32_16x16x32_bf16 v[42:45], v[186:189], v[222:225], v[42:45]
	v_mfma_f32_16x16x32_bf16 v[34:37], v[178:181], v[230:233], v[34:37]
	v_mfma_f32_16x16x32_bf16 v[26:29], v[186:189], v[230:233], v[26:29]
	v_mfma_f32_16x16x32_bf16 v[18:21], v[178:181], v[238:241], v[18:21]
	v_mfma_f32_16x16x32_bf16 v[10:13], v[186:189], v[238:241], v[10:13]
	v_mfma_f32_16x16x32_bf16 v[62:65], v[182:185], v[218:221], v[62:65]
	v_mfma_f32_16x16x32_bf16 v[58:61], v[190:193], v[218:221], v[58:61]
	v_mfma_f32_16x16x32_bf16 v[50:53], v[182:185], v[226:229], v[50:53]
	v_mfma_f32_16x16x32_bf16 v[42:45], v[190:193], v[226:229], v[42:45]
	v_mfma_f32_16x16x32_bf16 v[34:37], v[182:185], v[234:237], v[34:37]
	v_mfma_f32_16x16x32_bf16 v[26:29], v[190:193], v[234:237], v[26:29]
	v_mfma_f32_16x16x32_bf16 v[18:21], v[182:185], v[242:245], v[18:21]
	v_mfma_f32_16x16x32_bf16 v[10:13], v[190:193], v[242:245], v[10:13]
	s_setprio 0
	s_setprio 1
	v_mfma_f32_16x16x32_bf16 v[54:57], v[194:197], v[210:213], v[54:57]
	v_mfma_f32_16x16x32_bf16 v[46:49], v[202:205], v[210:213], v[46:49]
	v_mfma_f32_16x16x32_bf16 v[38:41], v[194:197], v[222:225], v[38:41]
	v_mfma_f32_16x16x32_bf16 v[30:33], v[202:205], v[222:225], v[30:33]
	v_mfma_f32_16x16x32_bf16 v[22:25], v[194:197], v[230:233], v[22:25]
	v_mfma_f32_16x16x32_bf16 v[14:17], v[202:205], v[230:233], v[14:17]
	v_mfma_f32_16x16x32_bf16 v[6:9], v[194:197], v[238:241], v[6:9]
	v_mfma_f32_16x16x32_bf16 v[2:5], v[202:205], v[238:241], v[2:5]
	v_mfma_f32_16x16x32_bf16 v[54:57], v[198:201], v[218:221], v[54:57]
	v_mfma_f32_16x16x32_bf16 v[46:49], v[206:209], v[218:221], v[46:49]
	v_mfma_f32_16x16x32_bf16 v[38:41], v[198:201], v[226:229], v[38:41]
	v_mfma_f32_16x16x32_bf16 v[30:33], v[206:209], v[226:229], v[30:33]
	v_mfma_f32_16x16x32_bf16 v[22:25], v[198:201], v[234:237], v[22:25]
	v_mfma_f32_16x16x32_bf16 v[14:17], v[206:209], v[234:237], v[14:17]
	v_mfma_f32_16x16x32_bf16 v[6:9], v[198:201], v[242:245], v[6:9]
	v_mfma_f32_16x16x32_bf16 v[2:5], v[206:209], v[242:245], v[2:5]
	s_setprio 0
	s_barrier
	s_add_i32 s22, s54, 2
	s_cmp_gt_u32 s54, 61
	s_mov_b32 s54, s22
	s_cbranch_scc1 .LBB0_255

; #define PG8_STAGE(bufoff, gbase, voff) do { _Pragma("unroll") for (int _i = 0; _i < 2; ++_i) \
;         __builtin_amdgcn_global_load_lds((const unsigned*)((const char*)(gbase) + (voff)[_i]), (PG8_LAS unsigned*)(lds + (bufoff) + ldsw + _i * 8192), 16, 0, 0); } while (0)
; #define PG8_LDA(dst, b, h) do { _Pragma("unroll") for (int m = 0; m < 4; ++m) _Pragma("unroll") for (int k = 0; k < 2; ++k) dst[m][k] = *(const PG8_LAS bf16x8*)(lds + PG8_SA(b, h) + aoff + m * 2048 + k * 1024); } while (0)
; #define PG8_LDB(dst, b, h) do { _Pragma("unroll") for (int n = 0; n < 2; ++n) _Pragma("unroll") for (int k = 0; k < 2; ++k) dst[n][k] = *(const PG8_LAS bf16x8*)(lds + PG8_SB(b, h) + boff + n * 2048 + k * 1024); } while (0)
; #define PG8_MMA(ai, bj, At, Bt) do { __builtin_amdgcn_s_setprio(1); _Pragma("unroll") for (int m = 0; m < 4; ++m) _Pragma("unroll") for (int n = 0; n < 2; ++n) _Pragma("unroll") for (int k = 0; k < 2; ++k) \
;         acc[ai][bj][m][n] = __builtin_amdgcn_mfma_f32_16x16x32_bf16(Bt[n][k], At[m][k], acc[ai][bj][m][n], 0, 0, 0); __builtin_amdgcn_s_setprio(0); } while (0)
; #define PG8_WAIT_V(n) asm volatile("s_waitcnt vmcnt(" #n ")" ::: "memory")
; #define PG8_WAIT_L(n) asm volatile("s_waitcnt lgkmcnt(" #n ")" ::: "memory")
; template <class Epi, class Sched, bool ALIGN_EPI = false, bool SP2 = false>
; __device__ __forceinline__ void gemm_phase(PG8_LAS unsigned char* lds, const Gemm g, const Sched& S, const Epi& E) {
;     ...
;             const bool last = (t == nt - 2);
;             const char* a1 = cA + (size_t)(t + 1) * kstep;
;             const char* a2 = last ? nA : cA + (size_t)(t + 2) * kstep; const char* b2 = last ? nB : cB + (size_t)(t + 2) * kstep;
;             const char* a3 = a2 + kstep; const char* b3 = b2 + kstep;
;             if (last && has_next) S.a_ready(nxt);
;             if constexpr (SP2) {
;             PG8_LDB(B0, 0, 0); PG8_LDB(B1, 0, 1); PG8_SCHED; PG8_LDA(At, 0, 0); PG8_STAGE(PG8_SA(1, 1), a1 + hstepA, voffA);
;             PG8_WAIT_V(8); PG8_WAIT_L(0); PG8_BAR; PG8_MMA(0, 0, At, B0); PG8_MMA(0, 1, At, B1); PG8_BAR; PG8_SCHED;
;             PG8_LDA(At, 0, 1); PG8_STAGE(PG8_SB(0, 0), b2, voffB); PG8_STAGE(PG8_SB(0, 1), b2 + hstepB, voffB); PG8_STAGE(PG8_SA(0, 0), a2, voffA);
;             PG8_WAIT_V(8); PG8_WAIT_L(0); PG8_BAR; PG8_MMA(1, 0, At, B0); PG8_MMA(1, 1, At, B1); PG8_BAR; PG8_SCHED;
.LBB0_443:
	ds_read_b128 v[146:149], v155
	ds_read_b128 v[158:161], v155 offset:1024
	ds_read_b128 v[162:165], v155 offset:2048
	ds_read_b128 v[166:169], v155 offset:3072
	ds_read_b128 v[174:177], v156
	ds_read_b128 v[178:181], v156 offset:1024
	ds_read_b128 v[182:185], v156 offset:2048
	ds_read_b128 v[186:189], v156 offset:3072
	s_add_u32 s28, s26, 0xfff00080
	s_addc_u32 s29, s27, -1
	s_cmp_eq_u32 s53, 60
	s_cselect_b32 s31, s17, s29
	s_cselect_b32 s30, s49, s28
	s_cselect_b32 s29, s19, s52
	s_cselect_b32 s28, s50, s51
	v_lshl_add_u64 v[170:171], s[26:27], 0, v[138:139]
	s_add_i32 m0, s25, 0xc000
	ds_read_b128 v[190:193], v157
	ds_read_b128 v[194:197], v157 offset:1024
	ds_read_b128 v[198:201], v157 offset:2048
	ds_read_b128 v[202:205], v157 offset:3072
	ds_read_b128 v[206:209], v157 offset:4096
	ds_read_b128 v[210:213], v157 offset:5120
	ds_read_b128 v[218:221], v157 offset:6144
	ds_read_b128 v[222:225], v157 offset:7168
	global_load_lds_dwordx4 v[170:171], off
	v_lshl_add_u64 v[170:171], s[26:27], 0, v[140:141]
	s_add_i32 m0, s25, 0xe000
	s_nop 0
	global_load_lds_dwordx4 v[170:171], off
	s_waitcnt vmcnt(8)
	s_waitcnt lgkmcnt(0)
	s_barrier
	s_setprio 1
	s_waitcnt lgkmcnt(0)
	v_mfma_f32_16x16x32_bf16 v[126:129], v[146:149], v[190:193], v[126:129]
	v_mfma_f32_16x16x32_bf16 v[122:125], v[162:165], v[190:193], v[122:125]
	v_mfma_f32_16x16x32_bf16 v[118:121], v[146:149], v[198:201], v[118:121]
	v_mfma_f32_16x16x32_bf16 v[114:117], v[162:165], v[198:201], v[114:117]
	v_mfma_f32_16x16x32_bf16 v[106:109], v[146:149], v[206:209], v[106:109]
	v_mfma_f32_16x16x32_bf16 v[98:101], v[162:165], v[206:209], v[98:101]
	v_mfma_f32_16x16x32_bf16 v[78:81], v[146:149], v[218:221], v[78:81]
	v_mfma_f32_16x16x32_bf16 v[74:77], v[162:165], v[218:221], v[74:77]
	v_mfma_f32_16x16x32_bf16 v[126:129], v[158:161], v[194:197], v[126:129]
	v_mfma_f32_16x16x32_bf16 v[122:125], v[166:169], v[194:197], v[122:125]
	v_mfma_f32_16x16x32_bf16 v[118:121], v[158:161], v[202:205], v[118:121]
	v_mfma_f32_16x16x32_bf16 v[114:117], v[166:169], v[202:205], v[114:117]
	v_mfma_f32_16x16x32_bf16 v[106:109], v[158:161], v[210:213], v[106:109]
	v_mfma_f32_16x16x32_bf16 v[98:101], v[166:169], v[210:213], v[98:101]
	v_mfma_f32_16x16x32_bf16 v[78:81], v[158:161], v[222:225], v[78:81]
	v_mfma_f32_16x16x32_bf16 v[74:77], v[166:169], v[222:225], v[74:77]
	s_setprio 0
	s_setprio 1
	v_mfma_f32_16x16x32_bf16 v[110:113], v[174:177], v[190:193], v[110:113]
	v_mfma_f32_16x16x32_bf16 v[102:105], v[182:185], v[190:193], v[102:105]
	v_mfma_f32_16x16x32_bf16 v[94:97], v[174:177], v[198:201], v[94:97]
	v_mfma_f32_16x16x32_bf16 v[90:93], v[182:185], v[198:201], v[90:93]
	v_mfma_f32_16x16x32_bf16 v[86:89], v[174:177], v[206:209], v[86:89]
	v_mfma_f32_16x16x32_bf16 v[82:85], v[182:185], v[206:209], v[82:85]
	v_mfma_f32_16x16x32_bf16 v[70:73], v[174:177], v[218:221], v[70:73]
	v_mfma_f32_16x16x32_bf16 v[66:69], v[182:185], v[218:221], v[66:69]
	v_mfma_f32_16x16x32_bf16 v[110:113], v[178:181], v[194:197], v[110:113]
	v_mfma_f32_16x16x32_bf16 v[102:105], v[186:189], v[194:197], v[102:105]
	v_mfma_f32_16x16x32_bf16 v[94:97], v[178:181], v[202:205], v[94:97]
	v_mfma_f32_16x16x32_bf16 v[90:93], v[186:189], v[202:205], v[90:93]
	v_mfma_f32_16x16x32_bf16 v[86:89], v[178:181], v[210:213], v[86:89]
	v_mfma_f32_16x16x32_bf16 v[82:85], v[186:189], v[210:213], v[82:85]
	v_mfma_f32_16x16x32_bf16 v[70:73], v[178:181], v[222:225], v[70:73]
	v_mfma_f32_16x16x32_bf16 v[66:69], v[186:189], v[222:225], v[66:69]
	s_setprio 0
	s_barrier
	s_add_i32 s54, s45, s37
	v_lshl_add_u64 v[170:171], s[28:29], 0, v[134:135]
	s_mov_b32 m0, s54
	global_load_lds_dwordx4 v[170:171], off
	s_add_i32 m0, s54, 0x2000
	s_add_u32 s54, s28, 0x100000
	v_lshl_add_u64 v[214:215], s[28:29], 0, v[130:131]
	s_addc_u32 s55, s29, 0
	s_add_i32 s56, s46, s37
	global_load_lds_dwordx4 v[214:215], off
	v_lshl_add_u64 v[226:227], s[54:55], 0, v[134:135]
	s_mov_b32 m0, s56
	v_lshl_add_u64 v[228:229], s[30:31], 0, v[132:133]
	global_load_lds_dwordx4 v[226:227], off
	v_lshl_add_u64 v[226:227], s[54:55], 0, v[130:131]
	s_add_i32 m0, s56, 0x2000
	s_nop 0
	global_load_lds_dwordx4 v[226:227], off
	v_lshl_add_u64 v[226:227], s[30:31], 0, v[136:137]
	s_mov_b32 m0, s25
	s_nop 0
	global_load_lds_dwordx4 v[226:227], off
	s_mov_b32 m0, s40
	s_nop 0
	global_load_lds_dwordx4 v[228:229], off
	ds_read_b128 v[190:193], v157 offset:16384
	ds_read_b128 v[194:197], v157 offset:17408
	ds_read_b128 v[198:201], v157 offset:18432
	ds_read_b128 v[202:205], v157 offset:19456
	ds_read_b128 v[206:209], v157 offset:20480
	ds_read_b128 v[210:213], v157 offset:21504
	ds_read_b128 v[218:221], v157 offset:22528
	ds_read_b128 v[222:225], v157 offset:23552
	s_waitcnt vmcnt(8)
	s_waitcnt lgkmcnt(0)
	s_barrier
; #define PG8_STAGE(bufoff, gbase, voff) do { _Pragma("unroll") for (int _i = 0; _i < 2; ++_i) \
;         __builtin_amdgcn_global_load_lds((const unsigned*)((const char*)(gbase) + (voff)[_i]), (PG8_LAS unsigned*)(lds + (bufoff) + ldsw + _i * 8192), 16, 0, 0); } while (0)
; #define PG8_LDA(dst, b, h) do { _Pragma("unroll") for (int m = 0; m < 4; ++m) _Pragma("unroll") for (int k = 0; k < 2; ++k) dst[m][k] = *(const PG8_LAS bf16x8*)(lds + PG8_SA(b, h) + aoff + m * 2048 + k * 1024); } while (0)
; #define PG8_LDB(dst, b, h) do { _Pragma("unroll") for (int n = 0; n < 2; ++n) _Pragma("unroll") for (int k = 0; k < 2; ++k) dst[n][k] = *(const PG8_LAS bf16x8*)(lds + PG8_SB(b, h) + boff + n * 2048 + k * 1024); } while (0)
; #define PG8_MMA(ai, bj, At, Bt) do { __builtin_amdgcn_s_setprio(1); _Pragma("unroll") for (int m = 0; m < 4; ++m) _Pragma("unroll") for (int n = 0; n < 2; ++n) _Pragma("unroll") for (int k = 0; k < 2; ++k) \
;         acc[ai][bj][m][n] = __builtin_amdgcn_mfma_f32_16x16x32_bf16(Bt[n][k], At[m][k], acc[ai][bj][m][n], 0, 0, 0); __builtin_amdgcn_s_setprio(0); } while (0)
; #define PG8_WAIT_V(n) asm volatile("s_waitcnt vmcnt(" #n ")" ::: "memory")
; #define PG8_WAIT_L(n) asm volatile("s_waitcnt lgkmcnt(" #n ")" ::: "memory")
; #define PG8_BAR __builtin_amdgcn_s_barrier()
; #define PG8_SCHED __builtin_amdgcn_sched_barrier(0)
; template <class Epi, class Sched, bool ALIGN_EPI = false, bool SP2 = false>
; __device__ __forceinline__ void gemm_phase(PG8_LAS unsigned char* lds, const Gemm g, const Sched& S, const Epi& E) {
;     ...
;             PG8_WAIT_V(8); PG8_WAIT_L(0); PG8_BAR; PG8_MMA(1, 0, At, B0); PG8_MMA(1, 1, At, B1); PG8_BAR; PG8_SCHED;
;             PG8_LDB(B0, 1, 0); PG8_LDB(B1, 1, 1); PG8_SCHED; PG8_LDA(At, 1, 0); PG8_STAGE(PG8_SA(0, 1), a2 + hstepA, voffA);
;             PG8_WAIT_V(8); PG8_WAIT_L(0); PG8_BAR; PG8_MMA(0, 0, At, B0); PG8_MMA(0, 1, At, B1); PG8_BAR; PG8_SCHED;
	s_setprio 1
	s_waitcnt lgkmcnt(0)
	v_mfma_f32_16x16x32_bf16 v[62:65], v[146:149], v[190:193], v[62:65]
	v_mfma_f32_16x16x32_bf16 v[58:61], v[162:165], v[190:193], v[58:61]
	v_mfma_f32_16x16x32_bf16 v[50:53], v[146:149], v[198:201], v[50:53]
	v_mfma_f32_16x16x32_bf16 v[42:45], v[162:165], v[198:201], v[42:45]
	v_mfma_f32_16x16x32_bf16 v[34:37], v[146:149], v[206:209], v[34:37]
	v_mfma_f32_16x16x32_bf16 v[26:29], v[162:165], v[206:209], v[26:29]
	v_mfma_f32_16x16x32_bf16 v[18:21], v[146:149], v[218:221], v[18:21]
	v_mfma_f32_16x16x32_bf16 v[10:13], v[162:165], v[218:221], v[10:13]
	v_mfma_f32_16x16x32_bf16 v[62:65], v[158:161], v[194:197], v[62:65]
	v_mfma_f32_16x16x32_bf16 v[58:61], v[166:169], v[194:197], v[58:61]
	v_mfma_f32_16x16x32_bf16 v[50:53], v[158:161], v[202:205], v[50:53]
	v_mfma_f32_16x16x32_bf16 v[42:45], v[166:169], v[202:205], v[42:45]
	v_mfma_f32_16x16x32_bf16 v[34:37], v[158:161], v[210:213], v[34:37]
	v_mfma_f32_16x16x32_bf16 v[26:29], v[166:169], v[210:213], v[26:29]
	v_mfma_f32_16x16x32_bf16 v[18:21], v[158:161], v[222:225], v[18:21]
	v_mfma_f32_16x16x32_bf16 v[10:13], v[166:169], v[222:225], v[10:13]
	s_setprio 0
	s_setprio 1
	v_mfma_f32_16x16x32_bf16 v[54:57], v[174:177], v[190:193], v[54:57]
	v_mfma_f32_16x16x32_bf16 v[46:49], v[182:185], v[190:193], v[46:49]
	v_mfma_f32_16x16x32_bf16 v[38:41], v[174:177], v[198:201], v[38:41]
	v_mfma_f32_16x16x32_bf16 v[30:33], v[182:185], v[198:201], v[30:33]
	v_mfma_f32_16x16x32_bf16 v[22:25], v[174:177], v[206:209], v[22:25]
	v_mfma_f32_16x16x32_bf16 v[14:17], v[182:185], v[206:209], v[14:17]
	v_mfma_f32_16x16x32_bf16 v[6:9], v[174:177], v[218:221], v[6:9]
	v_mfma_f32_16x16x32_bf16 v[2:5], v[182:185], v[218:221], v[2:5]
	v_mfma_f32_16x16x32_bf16 v[54:57], v[178:181], v[194:197], v[54:57]
	v_mfma_f32_16x16x32_bf16 v[46:49], v[186:189], v[194:197], v[46:49]
	v_mfma_f32_16x16x32_bf16 v[38:41], v[178:181], v[202:205], v[38:41]
	v_mfma_f32_16x16x32_bf16 v[30:33], v[186:189], v[202:205], v[30:33]
	v_mfma_f32_16x16x32_bf16 v[22:25], v[178:181], v[210:213], v[22:25]
	v_mfma_f32_16x16x32_bf16 v[14:17], v[186:189], v[210:213], v[14:17]
	v_mfma_f32_16x16x32_bf16 v[6:9], v[178:181], v[222:225], v[6:9]
	v_mfma_f32_16x16x32_bf16 v[2:5], v[186:189], v[222:225], v[2:5]
	s_setprio 0
	s_barrier
	s_add_i32 s54, 0, 0x18000
	v_add_u32_e32 v150, s54, v151
	s_add_i32 s55, 0, 0x1c000
	ds_read_b128 v[146:149], v150
	ds_read_b128 v[158:161], v150 offset:1024
	ds_read_b128 v[162:165], v150 offset:2048
	ds_read_b128 v[166:169], v150 offset:3072
	v_add_u32_e32 v150, s55, v151
	ds_read_b128 v[174:177], v150
	ds_read_b128 v[178:181], v150 offset:1024
	ds_read_b128 v[182:185], v150 offset:2048
	ds_read_b128 v[186:189], v150 offset:3072
	s_add_u32 s30, s30, 0x100000
	s_addc_u32 s31, s31, 0
	s_mov_b32 m0, s41
	v_lshl_add_u64 v[230:231], s[30:31], 0, v[136:137]
	ds_read_b128 v[190:193], v157 offset:32768
	ds_read_b128 v[194:197], v157 offset:33792
	ds_read_b128 v[198:201], v157 offset:34816
	ds_read_b128 v[202:205], v157 offset:35840
	ds_read_b128 v[206:209], v157 offset:36864
	ds_read_b128 v[210:213], v157 offset:37888
	ds_read_b128 v[218:221], v157 offset:38912
	ds_read_b128 v[222:225], v157 offset:39936
	global_load_lds_dwordx4 v[230:231], off
	v_lshl_add_u64 v[230:231], s[30:31], 0, v[132:133]
	s_mov_b32 m0, s42
	s_nop 0
	global_load_lds_dwordx4 v[230:231], off
	s_waitcnt vmcnt(8)
	s_waitcnt lgkmcnt(0)
	s_barrier
	s_setprio 1
	s_waitcnt lgkmcnt(0)
	v_mfma_f32_16x16x32_bf16 v[126:129], v[146:149], v[190:193], v[126:129]
	v_mfma_f32_16x16x32_bf16 v[122:125], v[162:165], v[190:193], v[122:125]
	v_mfma_f32_16x16x32_bf16 v[118:121], v[146:149], v[198:201], v[118:121]
	v_mfma_f32_16x16x32_bf16 v[114:117], v[162:165], v[198:201], v[114:117]
	v_mfma_f32_16x16x32_bf16 v[106:109], v[146:149], v[206:209], v[106:109]
	v_mfma_f32_16x16x32_bf16 v[98:101], v[162:165], v[206:209], v[98:101]
	v_mfma_f32_16x16x32_bf16 v[78:81], v[146:149], v[218:221], v[78:81]
	v_mfma_f32_16x16x32_bf16 v[74:77], v[162:165], v[218:221], v[74:77]
	v_mfma_f32_16x16x32_bf16 v[126:129], v[158:161], v[194:197], v[126:129]
	v_mfma_f32_16x16x32_bf16 v[122:125], v[166:169], v[194:197], v[122:125]
	v_mfma_f32_16x16x32_bf16 v[118:121], v[158:161], v[202:205], v[118:121]
	v_mfma_f32_16x16x32_bf16 v[114:117], v[166:169], v[202:205], v[114:117]
	v_mfma_f32_16x16x32_bf16 v[106:109], v[158:161], v[210:213], v[106:109]
	v_mfma_f32_16x16x32_bf16 v[98:101], v[166:169], v[210:213], v[98:101]
	v_mfma_f32_16x16x32_bf16 v[78:81], v[158:161], v[222:225], v[78:81]
	v_mfma_f32_16x16x32_bf16 v[74:77], v[166:169], v[222:225], v[74:77]
	s_setprio 0
	s_setprio 1
	v_mfma_f32_16x16x32_bf16 v[110:113], v[174:177], v[190:193], v[110:113]
	v_mfma_f32_16x16x32_bf16 v[102:105], v[182:185], v[190:193], v[102:105]
	v_mfma_f32_16x16x32_bf16 v[94:97], v[174:177], v[198:201], v[94:97]
	v_mfma_f32_16x16x32_bf16 v[90:93], v[182:185], v[198:201], v[90:93]
	v_mfma_f32_16x16x32_bf16 v[86:89], v[174:177], v[206:209], v[86:89]
	v_mfma_f32_16x16x32_bf16 v[82:85], v[182:185], v[206:209], v[82:85]
	v_mfma_f32_16x16x32_bf16 v[70:73], v[174:177], v[218:221], v[70:73]
	v_mfma_f32_16x16x32_bf16 v[66:69], v[182:185], v[218:221], v[66:69]
	v_mfma_f32_16x16x32_bf16 v[110:113], v[178:181], v[194:197], v[110:113]
	v_mfma_f32_16x16x32_bf16 v[102:105], v[186:189], v[194:197], v[102:105]
	v_mfma_f32_16x16x32_bf16 v[94:97], v[178:181], v[202:205], v[94:97]
	v_mfma_f32_16x16x32_bf16 v[90:93], v[186:189], v[202:205], v[90:93]
	v_mfma_f32_16x16x32_bf16 v[86:89], v[178:181], v[210:213], v[86:89]
	v_mfma_f32_16x16x32_bf16 v[82:85], v[186:189], v[210:213], v[82:85]
	v_mfma_f32_16x16x32_bf16 v[70:73], v[178:181], v[222:225], v[70:73]
	v_mfma_f32_16x16x32_bf16 v[66:69], v[186:189], v[222:225], v[66:69]
	s_setprio 0
	s_barrier
; #define PG8_STAGE(bufoff, gbase, voff) do { _Pragma("unroll") for (int _i = 0; _i < 2; ++_i) \
;         __builtin_amdgcn_global_load_lds((const unsigned*)((const char*)(gbase) + (voff)[_i]), (PG8_LAS unsigned*)(lds + (bufoff) + ldsw + _i * 8192), 16, 0, 0); } while (0)
; #define PG8_LDA(dst, b, h) do { _Pragma("unroll") for (int m = 0; m < 4; ++m) _Pragma("unroll") for (int k = 0; k < 2; ++k) dst[m][k] = *(const PG8_LAS bf16x8*)(lds + PG8_SA(b, h) + aoff + m * 2048 + k * 1024); } while (0)
; #define PG8_MMA(ai, bj, At, Bt) do { __builtin_amdgcn_s_setprio(1); _Pragma("unroll") for (int m = 0; m < 4; ++m) _Pragma("unroll") for (int n = 0; n < 2; ++n) _Pragma("unroll") for (int k = 0; k < 2; ++k) \
;         acc[ai][bj][m][n] = __builtin_amdgcn_mfma_f32_16x16x32_bf16(Bt[n][k], At[m][k], acc[ai][bj][m][n], 0, 0, 0); __builtin_amdgcn_s_setprio(0); } while (0)
; #define PG8_WAIT_V(n) asm volatile("s_waitcnt vmcnt(" #n ")" ::: "memory")
; #define PG8_WAIT_L(n) asm volatile("s_waitcnt lgkmcnt(" #n ")" ::: "memory")
; #define PG8_BAR __builtin_amdgcn_s_barrier()
; #define PG8_SCHED __builtin_amdgcn_sched_barrier(0)
; template <class Epi, class Sched, bool ALIGN_EPI = false, bool SP2 = false>
; __device__ __forceinline__ void gemm_phase(PG8_LAS unsigned char* lds, const Gemm g, const Sched& S, const Epi& E) {
;     ...
;             PG8_LDA(At, 1, 1); PG8_STAGE(PG8_SB(1, 0), b3, voffB); PG8_STAGE(PG8_SB(1, 1), b3 + hstepB, voffB); PG8_STAGE(PG8_SA(1, 0), a3, voffA);
;             PG8_WAIT_V(8); PG8_WAIT_L(0); PG8_BAR; PG8_MMA(1, 0, At, B0); PG8_MMA(1, 1, At, B1); PG8_BAR; PG8_SCHED;
;     ...
;         if constexpr (ALIGN_EPI) { if (wr == 0) PG8_BAR; }
	s_add_i32 s30, s54, s37
	v_lshl_add_u64 v[170:171], v[170:171], 0, s[12:13]
	s_mov_b32 m0, s30
	global_load_lds_dwordx4 v[170:171], off
	s_add_i32 m0, s30, 0x2000
	s_add_u32 s28, s28, 0x100080
	v_lshl_add_u64 v[170:171], v[214:215], 0, s[12:13]
	s_addc_u32 s29, s29, 0
	s_add_i32 s30, s55, s37
	global_load_lds_dwordx4 v[170:171], off
	v_lshl_add_u64 v[170:171], s[28:29], 0, v[134:135]
	s_mov_b32 m0, s30
	s_nop 0
	global_load_lds_dwordx4 v[170:171], off
	v_lshl_add_u64 v[170:171], s[28:29], 0, v[130:131]
	s_add_i32 m0, s30, 0x2000
	s_nop 0
	global_load_lds_dwordx4 v[170:171], off
	v_lshl_add_u64 v[170:171], v[226:227], 0, s[12:13]
	s_mov_b32 m0, s43
	s_nop 0
	global_load_lds_dwordx4 v[170:171], off
	v_lshl_add_u64 v[170:171], v[228:229], 0, s[12:13]
	s_mov_b32 m0, s44
	s_nop 0
	global_load_lds_dwordx4 v[170:171], off
	ds_read_b128 v[190:193], v157 offset:49152
	ds_read_b128 v[194:197], v157 offset:50176
	ds_read_b128 v[198:201], v157 offset:51200
	ds_read_b128 v[202:205], v157 offset:52224
	ds_read_b128 v[206:209], v157 offset:53248
	ds_read_b128 v[210:213], v157 offset:54272
	ds_read_b128 v[218:221], v157 offset:55296
	ds_read_b128 v[222:225], v157 offset:56320
	s_waitcnt vmcnt(8)
	s_waitcnt lgkmcnt(0)
	s_barrier
	s_setprio 1
	s_waitcnt lgkmcnt(0)
	v_mfma_f32_16x16x32_bf16 v[62:65], v[146:149], v[190:193], v[62:65]
	v_mfma_f32_16x16x32_bf16 v[58:61], v[162:165], v[190:193], v[58:61]
	v_mfma_f32_16x16x32_bf16 v[50:53], v[146:149], v[198:201], v[50:53]
	v_mfma_f32_16x16x32_bf16 v[42:45], v[162:165], v[198:201], v[42:45]
	v_mfma_f32_16x16x32_bf16 v[34:37], v[146:149], v[206:209], v[34:37]
	v_mfma_f32_16x16x32_bf16 v[26:29], v[162:165], v[206:209], v[26:29]
	v_mfma_f32_16x16x32_bf16 v[18:21], v[146:149], v[218:221], v[18:21]
	v_mfma_f32_16x16x32_bf16 v[10:13], v[162:165], v[218:221], v[10:13]
	v_mfma_f32_16x16x32_bf16 v[62:65], v[158:161], v[194:197], v[62:65]
	v_mfma_f32_16x16x32_bf16 v[58:61], v[166:169], v[194:197], v[58:61]
	v_mfma_f32_16x16x32_bf16 v[50:53], v[158:161], v[202:205], v[50:53]
	v_mfma_f32_16x16x32_bf16 v[42:45], v[166:169], v[202:205], v[42:45]
	v_mfma_f32_16x16x32_bf16 v[34:37], v[158:161], v[210:213], v[34:37]
	v_mfma_f32_16x16x32_bf16 v[26:29], v[166:169], v[210:213], v[26:29]
	v_mfma_f32_16x16x32_bf16 v[18:21], v[158:161], v[222:225], v[18:21]
	v_mfma_f32_16x16x32_bf16 v[10:13], v[166:169], v[222:225], v[10:13]
	s_setprio 0
	s_setprio 1
	v_mfma_f32_16x16x32_bf16 v[54:57], v[174:177], v[190:193], v[54:57]
	v_mfma_f32_16x16x32_bf16 v[46:49], v[182:185], v[190:193], v[46:49]
	v_mfma_f32_16x16x32_bf16 v[38:41], v[174:177], v[198:201], v[38:41]
	v_mfma_f32_16x16x32_bf16 v[30:33], v[182:185], v[198:201], v[30:33]
	v_mfma_f32_16x16x32_bf16 v[22:25], v[174:177], v[206:209], v[22:25]
	v_mfma_f32_16x16x32_bf16 v[14:17], v[182:185], v[206:209], v[14:17]
	v_mfma_f32_16x16x32_bf16 v[6:9], v[174:177], v[218:221], v[6:9]
	v_mfma_f32_16x16x32_bf16 v[2:5], v[182:185], v[218:221], v[2:5]
	v_mfma_f32_16x16x32_bf16 v[54:57], v[178:181], v[194:197], v[54:57]
	v_mfma_f32_16x16x32_bf16 v[46:49], v[186:189], v[194:197], v[46:49]
	v_mfma_f32_16x16x32_bf16 v[38:41], v[178:181], v[202:205], v[38:41]
	v_mfma_f32_16x16x32_bf16 v[30:33], v[186:189], v[202:205], v[30:33]
	v_mfma_f32_16x16x32_bf16 v[22:25], v[178:181], v[210:213], v[22:25]
	v_mfma_f32_16x16x32_bf16 v[14:17], v[186:189], v[210:213], v[14:17]
	v_mfma_f32_16x16x32_bf16 v[6:9], v[178:181], v[222:225], v[6:9]
	v_mfma_f32_16x16x32_bf16 v[2:5], v[186:189], v[222:225], v[2:5]
	s_setprio 0
	s_barrier
	s_add_i32 s53, s53, 2
	s_add_u32 s26, s26, 0x100
	s_addc_u32 s27, s27, 0
	s_add_u32 s51, s51, 0x100
	s_addc_u32 s52, s52, 0
	s_cmp_gt_u32 s53, 61
	s_cbranch_scc0 .LBB0_443
	s_and_b64 vcc, exec, s[14:15]
	s_cbranch_vccz .LBB0_446
	s_barrier

; #define PG8_STAGE(bufoff, gbase, voff) do { _Pragma("unroll") for (int _i = 0; _i < 2; ++_i) \
;         __builtin_amdgcn_global_load_lds((const unsigned*)((const char*)(gbase) + (voff)[_i]), (PG8_LAS unsigned*)(lds + (bufoff) + ldsw + _i * 8192), 16, 0, 0); } while (0)
; #define PG8_LDA(dst, b, h) do { _Pragma("unroll") for (int m = 0; m < 4; ++m) _Pragma("unroll") for (int k = 0; k < 2; ++k) dst[m][k] = *(const PG8_LAS bf16x8*)(lds + PG8_SA(b, h) + aoff + m * 2048 + k * 1024); } while (0)
; #define PG8_LDB(dst, b, h) do { _Pragma("unroll") for (int n = 0; n < 2; ++n) _Pragma("unroll") for (int k = 0; k < 2; ++k) dst[n][k] = *(const PG8_LAS bf16x8*)(lds + PG8_SB(b, h) + boff + n * 2048 + k * 1024); } while (0)
; #define PG8_MMA(ai, bj, At, Bt) do { __builtin_amdgcn_s_setprio(1); _Pragma("unroll") for (int m = 0; m < 4; ++m) _Pragma("unroll") for (int n = 0; n < 2; ++n) _Pragma("unroll") for (int k = 0; k < 2; ++k) \
;         acc[ai][bj][m][n] = __builtin_amdgcn_mfma_f32_16x16x32_bf16(Bt[n][k], At[m][k], acc[ai][bj][m][n], 0, 0, 0); __builtin_amdgcn_s_setprio(0); } while (0)
; #define PG8_WAIT_V(n) asm volatile("s_waitcnt vmcnt(" #n ")" ::: "memory")
; #define PG8_WAIT_L(n) asm volatile("s_waitcnt lgkmcnt(" #n ")" ::: "memory")
; template <class Epi, class Sched, bool ALIGN_EPI = false, bool SP2 = false>
; __device__ __forceinline__ void gemm_phase(PG8_LAS unsigned char* lds, const Gemm g, const Sched& S, const Epi& E) {
;     ...
;             const bool last = (t == nt - 2);
;             const char* a1 = cA + (size_t)(t + 1) * kstep;
;             const char* a2 = last ? nA : cA + (size_t)(t + 2) * kstep; const char* b2 = last ? nB : cB + (size_t)(t + 2) * kstep;
;             const char* a3 = a2 + kstep; const char* b3 = b2 + kstep;
;             if (last && has_next) S.a_ready(nxt);
;             if constexpr (SP2) {
;             PG8_LDB(B0, 0, 0); PG8_LDB(B1, 0, 1); PG8_SCHED; PG8_LDA(At, 0, 0); PG8_STAGE(PG8_SA(1, 1), a1 + hstepA, voffA);
;             PG8_WAIT_V(8); PG8_WAIT_L(0); PG8_BAR; PG8_MMA(0, 0, At, B0); PG8_MMA(0, 1, At, B1); PG8_BAR; PG8_SCHED;
;             PG8_LDA(At, 0, 1); PG8_STAGE(PG8_SB(0, 0), b2, voffB); PG8_STAGE(PG8_SB(0, 1), b2 + hstepB, voffB); PG8_STAGE(PG8_SA(0, 0), a2, voffA);
;             PG8_WAIT_V(8); PG8_WAIT_L(0); PG8_BAR; PG8_MMA(1, 0, At, B0); PG8_MMA(1, 1, At, B1); PG8_BAR; PG8_SCHED;
.LBB0_966:
	ds_read_b128 v[154:157], v150
	ds_read_b128 v[158:161], v150 offset:1024
	ds_read_b128 v[162:165], v150 offset:2048
	ds_read_b128 v[166:169], v150 offset:3072
	ds_read_b128 v[170:173], v151
	ds_read_b128 v[174:177], v151 offset:1024
	ds_read_b128 v[178:181], v151 offset:2048
	ds_read_b128 v[182:185], v151 offset:3072
	s_add_u32 s34, s30, 0xfff00080
	s_addc_u32 s35, s31, -1
	s_cmp_eq_u32 s61, 60
	s_cselect_b32 s37, s23, s35
	s_cselect_b32 s36, s57, s34
	s_cselect_b32 s35, s21, s60
	s_cselect_b32 s34, s58, s59
	v_lshl_add_u64 v[146:147], s[30:31], 0, v[138:139]
	s_add_i32 m0, s29, 0xc000
	ds_read_b128 v[186:189], v152
	ds_read_b128 v[190:193], v152 offset:1024
	ds_read_b128 v[194:197], v152 offset:2048
	ds_read_b128 v[198:201], v152 offset:3072
	ds_read_b128 v[202:205], v152 offset:4096
	ds_read_b128 v[206:209], v152 offset:5120
	ds_read_b128 v[210:213], v152 offset:6144
	ds_read_b128 v[218:221], v152 offset:7168
	global_load_lds_dwordx4 v[146:147], off
	v_lshl_add_u64 v[146:147], s[30:31], 0, v[140:141]
	s_add_i32 m0, s29, 0xe000
	s_nop 0
	global_load_lds_dwordx4 v[146:147], off
	s_waitcnt vmcnt(8)
	s_waitcnt lgkmcnt(0)
	s_barrier
	s_setprio 1
	s_waitcnt lgkmcnt(0)
	v_mfma_f32_16x16x32_bf16 v[126:129], v[154:157], v[186:189], v[126:129]
	v_mfma_f32_16x16x32_bf16 v[122:125], v[162:165], v[186:189], v[122:125]
	v_mfma_f32_16x16x32_bf16 v[114:117], v[154:157], v[194:197], v[114:117]
	v_mfma_f32_16x16x32_bf16 v[106:109], v[162:165], v[194:197], v[106:109]
	v_mfma_f32_16x16x32_bf16 v[98:101], v[154:157], v[202:205], v[98:101]
	v_mfma_f32_16x16x32_bf16 v[90:93], v[162:165], v[202:205], v[90:93]
	v_mfma_f32_16x16x32_bf16 v[82:85], v[154:157], v[210:213], v[82:85]
	v_mfma_f32_16x16x32_bf16 v[74:77], v[162:165], v[210:213], v[74:77]
	v_mfma_f32_16x16x32_bf16 v[126:129], v[158:161], v[190:193], v[126:129]
	v_mfma_f32_16x16x32_bf16 v[122:125], v[166:169], v[190:193], v[122:125]
	v_mfma_f32_16x16x32_bf16 v[114:117], v[158:161], v[198:201], v[114:117]
	v_mfma_f32_16x16x32_bf16 v[106:109], v[166:169], v[198:201], v[106:109]
	v_mfma_f32_16x16x32_bf16 v[98:101], v[158:161], v[206:209], v[98:101]
	v_mfma_f32_16x16x32_bf16 v[90:93], v[166:169], v[206:209], v[90:93]
	v_mfma_f32_16x16x32_bf16 v[82:85], v[158:161], v[218:221], v[82:85]
	v_mfma_f32_16x16x32_bf16 v[74:77], v[166:169], v[218:221], v[74:77]
	s_setprio 0
	s_setprio 1
	v_mfma_f32_16x16x32_bf16 v[118:121], v[170:173], v[186:189], v[118:121]
	v_mfma_f32_16x16x32_bf16 v[110:113], v[178:181], v[186:189], v[110:113]
	v_mfma_f32_16x16x32_bf16 v[102:105], v[170:173], v[194:197], v[102:105]
	v_mfma_f32_16x16x32_bf16 v[94:97], v[178:181], v[194:197], v[94:97]
	v_mfma_f32_16x16x32_bf16 v[86:89], v[170:173], v[202:205], v[86:89]
	v_mfma_f32_16x16x32_bf16 v[78:81], v[178:181], v[202:205], v[78:81]
	v_mfma_f32_16x16x32_bf16 v[70:73], v[170:173], v[210:213], v[70:73]
	v_mfma_f32_16x16x32_bf16 v[66:69], v[178:181], v[210:213], v[66:69]
	v_mfma_f32_16x16x32_bf16 v[118:121], v[174:177], v[190:193], v[118:121]
	v_mfma_f32_16x16x32_bf16 v[110:113], v[182:185], v[190:193], v[110:113]
	v_mfma_f32_16x16x32_bf16 v[102:105], v[174:177], v[198:201], v[102:105]
	v_mfma_f32_16x16x32_bf16 v[94:97], v[182:185], v[198:201], v[94:97]
	v_mfma_f32_16x16x32_bf16 v[86:89], v[174:177], v[206:209], v[86:89]
	v_mfma_f32_16x16x32_bf16 v[78:81], v[182:185], v[206:209], v[78:81]
	v_mfma_f32_16x16x32_bf16 v[70:73], v[174:177], v[218:221], v[70:73]
	v_mfma_f32_16x16x32_bf16 v[66:69], v[182:185], v[218:221], v[66:69]
	s_setprio 0
	s_barrier
	s_add_i32 s62, s50, s42
	v_lshl_add_u64 v[146:147], s[34:35], 0, v[132:133]
	s_mov_b32 m0, s62
	global_load_lds_dwordx4 v[146:147], off
	s_add_i32 m0, s62, 0x2000
	s_add_u32 s62, s34, 0x100000
	v_lshl_add_u64 v[214:215], s[34:35], 0, v[136:137]
	s_addc_u32 s63, s35, 0
	s_add_i32 s64, s51, s42
	global_load_lds_dwordx4 v[214:215], off
	v_lshl_add_u64 v[222:223], s[62:63], 0, v[132:133]
	s_mov_b32 m0, s64
	v_lshl_add_u64 v[224:225], s[36:37], 0, v[134:135]
	global_load_lds_dwordx4 v[222:223], off
	v_lshl_add_u64 v[222:223], s[62:63], 0, v[136:137]
	s_add_i32 m0, s64, 0x2000
	s_nop 0
	global_load_lds_dwordx4 v[222:223], off
	v_lshl_add_u64 v[222:223], s[36:37], 0, v[130:131]
	s_mov_b32 m0, s29
	s_nop 0
	global_load_lds_dwordx4 v[222:223], off
	s_mov_b32 m0, s43
	s_nop 0
	global_load_lds_dwordx4 v[224:225], off
	ds_read_b128 v[186:189], v152 offset:16384
	ds_read_b128 v[190:193], v152 offset:17408
	ds_read_b128 v[194:197], v152 offset:18432
	ds_read_b128 v[198:201], v152 offset:19456
	ds_read_b128 v[202:205], v152 offset:20480
	ds_read_b128 v[206:209], v152 offset:21504
	ds_read_b128 v[210:213], v152 offset:22528
	ds_read_b128 v[218:221], v152 offset:23552
	s_waitcnt vmcnt(8)
	s_waitcnt lgkmcnt(0)
	s_barrier
; #define PG8_STAGE(bufoff, gbase, voff) do { _Pragma("unroll") for (int _i = 0; _i < 2; ++_i) \
;         __builtin_amdgcn_global_load_lds((const unsigned*)((const char*)(gbase) + (voff)[_i]), (PG8_LAS unsigned*)(lds + (bufoff) + ldsw + _i * 8192), 16, 0, 0); } while (0)
; #define PG8_LDA(dst, b, h) do { _Pragma("unroll") for (int m = 0; m < 4; ++m) _Pragma("unroll") for (int k = 0; k < 2; ++k) dst[m][k] = *(const PG8_LAS bf16x8*)(lds + PG8_SA(b, h) + aoff + m * 2048 + k * 1024); } while (0)
; #define PG8_LDB(dst, b, h) do { _Pragma("unroll") for (int n = 0; n < 2; ++n) _Pragma("unroll") for (int k = 0; k < 2; ++k) dst[n][k] = *(const PG8_LAS bf16x8*)(lds + PG8_SB(b, h) + boff + n * 2048 + k * 1024); } while (0)
; #define PG8_MMA(ai, bj, At, Bt) do { __builtin_amdgcn_s_setprio(1); _Pragma("unroll") for (int m = 0; m < 4; ++m) _Pragma("unroll") for (int n = 0; n < 2; ++n) _Pragma("unroll") for (int k = 0; k < 2; ++k) \
;         acc[ai][bj][m][n] = __builtin_amdgcn_mfma_f32_16x16x32_bf16(Bt[n][k], At[m][k], acc[ai][bj][m][n], 0, 0, 0); __builtin_amdgcn_s_setprio(0); } while (0)
; #define PG8_WAIT_V(n) asm volatile("s_waitcnt vmcnt(" #n ")" ::: "memory")
; #define PG8_WAIT_L(n) asm volatile("s_waitcnt lgkmcnt(" #n ")" ::: "memory")
; #define PG8_BAR __builtin_amdgcn_s_barrier()
; #define PG8_SCHED __builtin_amdgcn_sched_barrier(0)
; template <class Epi, class Sched, bool ALIGN_EPI = false, bool SP2 = false>
; __device__ __forceinline__ void gemm_phase(PG8_LAS unsigned char* lds, const Gemm g, const Sched& S, const Epi& E) {
;     ...
;             PG8_WAIT_V(8); PG8_WAIT_L(0); PG8_BAR; PG8_MMA(1, 0, At, B0); PG8_MMA(1, 1, At, B1); PG8_BAR; PG8_SCHED;
;             PG8_LDB(B0, 1, 0); PG8_LDB(B1, 1, 1); PG8_SCHED; PG8_LDA(At, 1, 0); PG8_STAGE(PG8_SA(0, 1), a2 + hstepA, voffA);
;             PG8_WAIT_V(8); PG8_WAIT_L(0); PG8_BAR; PG8_MMA(0, 0, At, B0); PG8_MMA(0, 1, At, B1); PG8_BAR; PG8_SCHED;
	s_setprio 1
	s_waitcnt lgkmcnt(0)
	v_mfma_f32_16x16x32_bf16 v[62:65], v[154:157], v[186:189], v[62:65]
	v_mfma_f32_16x16x32_bf16 v[58:61], v[162:165], v[186:189], v[58:61]
	v_mfma_f32_16x16x32_bf16 v[50:53], v[154:157], v[194:197], v[50:53]
	v_mfma_f32_16x16x32_bf16 v[42:45], v[162:165], v[194:197], v[42:45]
	v_mfma_f32_16x16x32_bf16 v[34:37], v[154:157], v[202:205], v[34:37]
	v_mfma_f32_16x16x32_bf16 v[26:29], v[162:165], v[202:205], v[26:29]
	v_mfma_f32_16x16x32_bf16 v[18:21], v[154:157], v[210:213], v[18:21]
	v_mfma_f32_16x16x32_bf16 v[10:13], v[162:165], v[210:213], v[10:13]
	v_mfma_f32_16x16x32_bf16 v[62:65], v[158:161], v[190:193], v[62:65]
	v_mfma_f32_16x16x32_bf16 v[58:61], v[166:169], v[190:193], v[58:61]
	v_mfma_f32_16x16x32_bf16 v[50:53], v[158:161], v[198:201], v[50:53]
	v_mfma_f32_16x16x32_bf16 v[42:45], v[166:169], v[198:201], v[42:45]
	v_mfma_f32_16x16x32_bf16 v[34:37], v[158:161], v[206:209], v[34:37]
	v_mfma_f32_16x16x32_bf16 v[26:29], v[166:169], v[206:209], v[26:29]
	v_mfma_f32_16x16x32_bf16 v[18:21], v[158:161], v[218:221], v[18:21]
	v_mfma_f32_16x16x32_bf16 v[10:13], v[166:169], v[218:221], v[10:13]
	s_setprio 0
	s_setprio 1
	v_mfma_f32_16x16x32_bf16 v[54:57], v[170:173], v[186:189], v[54:57]
	v_mfma_f32_16x16x32_bf16 v[46:49], v[178:181], v[186:189], v[46:49]
	v_mfma_f32_16x16x32_bf16 v[38:41], v[170:173], v[194:197], v[38:41]
	v_mfma_f32_16x16x32_bf16 v[30:33], v[178:181], v[194:197], v[30:33]
	v_mfma_f32_16x16x32_bf16 v[22:25], v[170:173], v[202:205], v[22:25]
	v_mfma_f32_16x16x32_bf16 v[14:17], v[178:181], v[202:205], v[14:17]
	v_mfma_f32_16x16x32_bf16 v[6:9], v[170:173], v[210:213], v[6:9]
	v_mfma_f32_16x16x32_bf16 v[2:5], v[178:181], v[210:213], v[2:5]
	v_mfma_f32_16x16x32_bf16 v[54:57], v[174:177], v[190:193], v[54:57]
	v_mfma_f32_16x16x32_bf16 v[46:49], v[182:185], v[190:193], v[46:49]
	v_mfma_f32_16x16x32_bf16 v[38:41], v[174:177], v[198:201], v[38:41]
	v_mfma_f32_16x16x32_bf16 v[30:33], v[182:185], v[198:201], v[30:33]
	v_mfma_f32_16x16x32_bf16 v[22:25], v[174:177], v[206:209], v[22:25]
	v_mfma_f32_16x16x32_bf16 v[14:17], v[182:185], v[206:209], v[14:17]
	v_mfma_f32_16x16x32_bf16 v[6:9], v[174:177], v[218:221], v[6:9]
	v_mfma_f32_16x16x32_bf16 v[2:5], v[182:185], v[218:221], v[2:5]
	s_setprio 0
	s_barrier
	s_add_i32 s62, 0, 0x18000
	v_add_u32_e32 v153, s62, v148
	s_add_i32 s63, 0, 0x1c000
	ds_read_b128 v[154:157], v153
	ds_read_b128 v[158:161], v153 offset:1024
	ds_read_b128 v[162:165], v153 offset:2048
	ds_read_b128 v[166:169], v153 offset:3072
	v_add_u32_e32 v153, s63, v148
	ds_read_b128 v[170:173], v153
	ds_read_b128 v[174:177], v153 offset:1024
	ds_read_b128 v[178:181], v153 offset:2048
	ds_read_b128 v[182:185], v153 offset:3072
	s_add_u32 s36, s36, 0x100000
	s_addc_u32 s37, s37, 0
	s_mov_b32 m0, s44
	v_lshl_add_u64 v[226:227], s[36:37], 0, v[130:131]
	ds_read_b128 v[186:189], v152 offset:32768
	ds_read_b128 v[190:193], v152 offset:33792
	ds_read_b128 v[194:197], v152 offset:34816
	ds_read_b128 v[198:201], v152 offset:35840
	ds_read_b128 v[202:205], v152 offset:36864
	ds_read_b128 v[206:209], v152 offset:37888
	ds_read_b128 v[210:213], v152 offset:38912
	ds_read_b128 v[218:221], v152 offset:39936
	global_load_lds_dwordx4 v[226:227], off
	v_lshl_add_u64 v[226:227], s[36:37], 0, v[134:135]
	s_mov_b32 m0, s45
	s_nop 0
	global_load_lds_dwordx4 v[226:227], off
	s_waitcnt vmcnt(8)
	s_waitcnt lgkmcnt(0)
	s_barrier
	s_setprio 1
	s_waitcnt lgkmcnt(0)
	v_mfma_f32_16x16x32_bf16 v[126:129], v[154:157], v[186:189], v[126:129]
	v_mfma_f32_16x16x32_bf16 v[122:125], v[162:165], v[186:189], v[122:125]
	v_mfma_f32_16x16x32_bf16 v[114:117], v[154:157], v[194:197], v[114:117]
	v_mfma_f32_16x16x32_bf16 v[106:109], v[162:165], v[194:197], v[106:109]
	v_mfma_f32_16x16x32_bf16 v[98:101], v[154:157], v[202:205], v[98:101]
	v_mfma_f32_16x16x32_bf16 v[90:93], v[162:165], v[202:205], v[90:93]
	v_mfma_f32_16x16x32_bf16 v[82:85], v[154:157], v[210:213], v[82:85]
	v_mfma_f32_16x16x32_bf16 v[74:77], v[162:165], v[210:213], v[74:77]
	v_mfma_f32_16x16x32_bf16 v[126:129], v[158:161], v[190:193], v[126:129]
	v_mfma_f32_16x16x32_bf16 v[122:125], v[166:169], v[190:193], v[122:125]
	v_mfma_f32_16x16x32_bf16 v[114:117], v[158:161], v[198:201], v[114:117]
	v_mfma_f32_16x16x32_bf16 v[106:109], v[166:169], v[198:201], v[106:109]
	v_mfma_f32_16x16x32_bf16 v[98:101], v[158:161], v[206:209], v[98:101]
	v_mfma_f32_16x16x32_bf16 v[90:93], v[166:169], v[206:209], v[90:93]
	v_mfma_f32_16x16x32_bf16 v[82:85], v[158:161], v[218:221], v[82:85]
	v_mfma_f32_16x16x32_bf16 v[74:77], v[166:169], v[218:221], v[74:77]
	s_setprio 0
	s_setprio 1
	v_mfma_f32_16x16x32_bf16 v[118:121], v[170:173], v[186:189], v[118:121]
	v_mfma_f32_16x16x32_bf16 v[110:113], v[178:181], v[186:189], v[110:113]
	v_mfma_f32_16x16x32_bf16 v[102:105], v[170:173], v[194:197], v[102:105]
	v_mfma_f32_16x16x32_bf16 v[94:97], v[178:181], v[194:197], v[94:97]
	v_mfma_f32_16x16x32_bf16 v[86:89], v[170:173], v[202:205], v[86:89]
	v_mfma_f32_16x16x32_bf16 v[78:81], v[178:181], v[202:205], v[78:81]
	v_mfma_f32_16x16x32_bf16 v[70:73], v[170:173], v[210:213], v[70:73]
	v_mfma_f32_16x16x32_bf16 v[66:69], v[178:181], v[210:213], v[66:69]
	v_mfma_f32_16x16x32_bf16 v[118:121], v[174:177], v[190:193], v[118:121]
	v_mfma_f32_16x16x32_bf16 v[110:113], v[182:185], v[190:193], v[110:113]
	v_mfma_f32_16x16x32_bf16 v[102:105], v[174:177], v[198:201], v[102:105]
	v_mfma_f32_16x16x32_bf16 v[94:97], v[182:185], v[198:201], v[94:97]
	v_mfma_f32_16x16x32_bf16 v[86:89], v[174:177], v[206:209], v[86:89]
	v_mfma_f32_16x16x32_bf16 v[78:81], v[182:185], v[206:209], v[78:81]
	v_mfma_f32_16x16x32_bf16 v[70:73], v[174:177], v[218:221], v[70:73]
	v_mfma_f32_16x16x32_bf16 v[66:69], v[182:185], v[218:221], v[66:69]
	s_setprio 0
	s_barrier
; #define PG8_STAGE(bufoff, gbase, voff) do { _Pragma("unroll") for (int _i = 0; _i < 2; ++_i) \
;         __builtin_amdgcn_global_load_lds((const unsigned*)((const char*)(gbase) + (voff)[_i]), (PG8_LAS unsigned*)(lds + (bufoff) + ldsw + _i * 8192), 16, 0, 0); } while (0)
; #define PG8_LDA(dst, b, h) do { _Pragma("unroll") for (int m = 0; m < 4; ++m) _Pragma("unroll") for (int k = 0; k < 2; ++k) dst[m][k] = *(const PG8_LAS bf16x8*)(lds + PG8_SA(b, h) + aoff + m * 2048 + k * 1024); } while (0)
; #define PG8_MMA(ai, bj, At, Bt) do { __builtin_amdgcn_s_setprio(1); _Pragma("unroll") for (int m = 0; m < 4; ++m) _Pragma("unroll") for (int n = 0; n < 2; ++n) _Pragma("unroll") for (int k = 0; k < 2; ++k) \
;         acc[ai][bj][m][n] = __builtin_amdgcn_mfma_f32_16x16x32_bf16(Bt[n][k], At[m][k], acc[ai][bj][m][n], 0, 0, 0); __builtin_amdgcn_s_setprio(0); } while (0)
; #define PG8_WAIT_V(n) asm volatile("s_waitcnt vmcnt(" #n ")" ::: "memory")
; #define PG8_WAIT_L(n) asm volatile("s_waitcnt lgkmcnt(" #n ")" ::: "memory")
; #define PG8_BAR __builtin_amdgcn_s_barrier()
; #define PG8_SCHED __builtin_amdgcn_sched_barrier(0)
; template <class Epi, class Sched, bool ALIGN_EPI = false, bool SP2 = false>
; __device__ __forceinline__ void gemm_phase(PG8_LAS unsigned char* lds, const Gemm g, const Sched& S, const Epi& E) {
;     ...
;             PG8_LDA(At, 1, 1); PG8_STAGE(PG8_SB(1, 0), b3, voffB); PG8_STAGE(PG8_SB(1, 1), b3 + hstepB, voffB); PG8_STAGE(PG8_SA(1, 0), a3, voffA);
;             PG8_WAIT_V(8); PG8_WAIT_L(0); PG8_BAR; PG8_MMA(1, 0, At, B0); PG8_MMA(1, 1, At, B1); PG8_BAR; PG8_SCHED;
;     ...
;         if constexpr (ALIGN_EPI) { if (wr == 0) PG8_BAR; }
	s_add_i32 s36, s62, s42
	v_lshl_add_u64 v[146:147], v[146:147], 0, s[10:11]
	s_mov_b32 m0, s36
	global_load_lds_dwordx4 v[146:147], off
	s_add_i32 m0, s36, 0x2000
	s_add_u32 s34, s34, 0x100080
	v_lshl_add_u64 v[146:147], v[214:215], 0, s[10:11]
	s_addc_u32 s35, s35, 0
	s_add_i32 s36, s63, s42
	global_load_lds_dwordx4 v[146:147], off
	v_lshl_add_u64 v[146:147], s[34:35], 0, v[132:133]
	s_mov_b32 m0, s36
	s_nop 0
	global_load_lds_dwordx4 v[146:147], off
	v_lshl_add_u64 v[146:147], s[34:35], 0, v[136:137]
	s_add_i32 m0, s36, 0x2000
	s_nop 0
	global_load_lds_dwordx4 v[146:147], off
	v_lshl_add_u64 v[146:147], v[222:223], 0, s[10:11]
	s_mov_b32 m0, s47
	s_nop 0
	global_load_lds_dwordx4 v[146:147], off
	v_lshl_add_u64 v[146:147], v[224:225], 0, s[10:11]
	s_mov_b32 m0, s48
	s_nop 0
	global_load_lds_dwordx4 v[146:147], off
	ds_read_b128 v[186:189], v152 offset:49152
	ds_read_b128 v[190:193], v152 offset:50176
	ds_read_b128 v[194:197], v152 offset:51200
	ds_read_b128 v[198:201], v152 offset:52224
	ds_read_b128 v[202:205], v152 offset:53248
	ds_read_b128 v[206:209], v152 offset:54272
	ds_read_b128 v[210:213], v152 offset:55296
	ds_read_b128 v[218:221], v152 offset:56320
	s_waitcnt vmcnt(8)
	s_waitcnt lgkmcnt(0)
	s_barrier
	s_setprio 1
	s_waitcnt lgkmcnt(0)
	v_mfma_f32_16x16x32_bf16 v[62:65], v[154:157], v[186:189], v[62:65]
	v_mfma_f32_16x16x32_bf16 v[58:61], v[162:165], v[186:189], v[58:61]
	v_mfma_f32_16x16x32_bf16 v[50:53], v[154:157], v[194:197], v[50:53]
	v_mfma_f32_16x16x32_bf16 v[42:45], v[162:165], v[194:197], v[42:45]
	v_mfma_f32_16x16x32_bf16 v[34:37], v[154:157], v[202:205], v[34:37]
	v_mfma_f32_16x16x32_bf16 v[26:29], v[162:165], v[202:205], v[26:29]
	v_mfma_f32_16x16x32_bf16 v[18:21], v[154:157], v[210:213], v[18:21]
	v_mfma_f32_16x16x32_bf16 v[10:13], v[162:165], v[210:213], v[10:13]
	v_mfma_f32_16x16x32_bf16 v[62:65], v[158:161], v[190:193], v[62:65]
	v_mfma_f32_16x16x32_bf16 v[58:61], v[166:169], v[190:193], v[58:61]
	v_mfma_f32_16x16x32_bf16 v[50:53], v[158:161], v[198:201], v[50:53]
	v_mfma_f32_16x16x32_bf16 v[42:45], v[166:169], v[198:201], v[42:45]
	v_mfma_f32_16x16x32_bf16 v[34:37], v[158:161], v[206:209], v[34:37]
	v_mfma_f32_16x16x32_bf16 v[26:29], v[166:169], v[206:209], v[26:29]
	v_mfma_f32_16x16x32_bf16 v[18:21], v[158:161], v[218:221], v[18:21]
	v_mfma_f32_16x16x32_bf16 v[10:13], v[166:169], v[218:221], v[10:13]
	s_setprio 0
	s_setprio 1
	v_mfma_f32_16x16x32_bf16 v[54:57], v[170:173], v[186:189], v[54:57]
	v_mfma_f32_16x16x32_bf16 v[46:49], v[178:181], v[186:189], v[46:49]
	v_mfma_f32_16x16x32_bf16 v[38:41], v[170:173], v[194:197], v[38:41]
	v_mfma_f32_16x16x32_bf16 v[30:33], v[178:181], v[194:197], v[30:33]
	v_mfma_f32_16x16x32_bf16 v[22:25], v[170:173], v[202:205], v[22:25]
	v_mfma_f32_16x16x32_bf16 v[14:17], v[178:181], v[202:205], v[14:17]
	v_mfma_f32_16x16x32_bf16 v[6:9], v[170:173], v[210:213], v[6:9]
	v_mfma_f32_16x16x32_bf16 v[2:5], v[178:181], v[210:213], v[2:5]
	v_mfma_f32_16x16x32_bf16 v[54:57], v[174:177], v[190:193], v[54:57]
	v_mfma_f32_16x16x32_bf16 v[46:49], v[182:185], v[190:193], v[46:49]
	v_mfma_f32_16x16x32_bf16 v[38:41], v[174:177], v[198:201], v[38:41]
	v_mfma_f32_16x16x32_bf16 v[30:33], v[182:185], v[198:201], v[30:33]
	v_mfma_f32_16x16x32_bf16 v[22:25], v[174:177], v[206:209], v[22:25]
	v_mfma_f32_16x16x32_bf16 v[14:17], v[182:185], v[206:209], v[14:17]
	v_mfma_f32_16x16x32_bf16 v[6:9], v[174:177], v[218:221], v[6:9]
	v_mfma_f32_16x16x32_bf16 v[2:5], v[182:185], v[218:221], v[2:5]
	s_setprio 0
	s_barrier
	s_add_i32 s61, s61, 2
	s_add_u32 s30, s30, 0x100
	s_addc_u32 s31, s31, 0
	s_add_u32 s59, s59, 0x100
	s_addc_u32 s60, s60, 0
	s_cmp_gt_u32 s61, 61
	s_cbranch_scc0 .LBB0_966
	s_and_b64 vcc, exec, s[12:13]
	s_cbranch_vccz .LBB0_969
	s_barrier

; #define PG8_STAGE(bufoff, gbase, voff) do { _Pragma("unroll") for (int _i = 0; _i < 2; ++_i) \
;         __builtin_amdgcn_global_load_lds((const unsigned*)((const char*)(gbase) + (voff)[_i]), (PG8_LAS unsigned*)(lds + (bufoff) + ldsw + _i * 8192), 16, 0, 0); } while (0)
; #define PG8_LDA(dst, b, h) do { _Pragma("unroll") for (int m = 0; m < 4; ++m) _Pragma("unroll") for (int k = 0; k < 2; ++k) dst[m][k] = *(const PG8_LAS bf16x8*)(lds + PG8_SA(b, h) + aoff + m * 2048 + k * 1024); } while (0)
; #define PG8_LDB(dst, b, h) do { _Pragma("unroll") for (int n = 0; n < 2; ++n) _Pragma("unroll") for (int k = 0; k < 2; ++k) dst[n][k] = *(const PG8_LAS bf16x8*)(lds + PG8_SB(b, h) + boff + n * 2048 + k * 1024); } while (0)
; #define PG8_MMA(ai, bj, At, Bt) do { __builtin_amdgcn_s_setprio(1); _Pragma("unroll") for (int m = 0; m < 4; ++m) _Pragma("unroll") for (int n = 0; n < 2; ++n) _Pragma("unroll") for (int k = 0; k < 2; ++k) \
;         acc[ai][bj][m][n] = __builtin_amdgcn_mfma_f32_16x16x32_bf16(Bt[n][k], At[m][k], acc[ai][bj][m][n], 0, 0, 0); __builtin_amdgcn_s_setprio(0); } while (0)
; #define PG8_WAIT_V(n) asm volatile("s_waitcnt vmcnt(" #n ")" ::: "memory")
; #define PG8_WAIT_L(n) asm volatile("s_waitcnt lgkmcnt(" #n ")" ::: "memory")
; template <class Epi, class Sched, bool ALIGN_EPI = false, bool SP2 = false>
; __device__ __forceinline__ void gemm_phase(PG8_LAS unsigned char* lds, const Gemm g, const Sched& S, const Epi& E) {
;     ...
;             const bool last = (t == nt - 2);
;             const char* a1 = cA + (size_t)(t + 1) * kstep;
;             const char* a2 = last ? nA : cA + (size_t)(t + 2) * kstep; const char* b2 = last ? nB : cB + (size_t)(t + 2) * kstep;
;             const char* a3 = a2 + kstep; const char* b3 = b2 + kstep;
;             if (last && has_next) S.a_ready(nxt);
;             if constexpr (SP2) {
;             PG8_LDB(B0, 0, 0); PG8_LDB(B1, 0, 1); PG8_SCHED; PG8_LDA(At, 0, 0); PG8_STAGE(PG8_SA(1, 1), a1 + hstepA, voffA);
;             PG8_WAIT_V(8); PG8_WAIT_L(0); PG8_BAR; PG8_MMA(0, 0, At, B0); PG8_MMA(0, 1, At, B1); PG8_BAR; PG8_SCHED;
;             PG8_LDA(At, 0, 1); PG8_STAGE(PG8_SB(0, 0), b2, voffB); PG8_STAGE(PG8_SB(0, 1), b2 + hstepB, voffB); PG8_STAGE(PG8_SA(0, 0), a2, voffA);
;             PG8_WAIT_V(8); PG8_WAIT_L(0); PG8_BAR; PG8_MMA(1, 0, At, B0); PG8_MMA(1, 1, At, B1); PG8_BAR; PG8_SCHED;
.LBB0_1097:
	ds_read_b128 v[156:159], v153
	ds_read_b128 v[160:163], v153 offset:1024
	ds_read_b128 v[164:167], v153 offset:2048
	ds_read_b128 v[168:171], v153 offset:3072
	ds_read_b128 v[172:175], v154
	ds_read_b128 v[176:179], v154 offset:1024
	ds_read_b128 v[180:183], v154 offset:2048
	ds_read_b128 v[184:187], v154 offset:3072
	s_add_u32 s36, s34, 0xfff00080
	s_addc_u32 s37, s35, -1
	s_cmp_eq_u32 s63, 60
	s_cselect_b32 s39, s25, s37
	s_cselect_b32 s38, s59, s36
	s_cselect_b32 s37, s23, s62
	s_cselect_b32 s36, s60, s61
	v_lshl_add_u64 v[148:149], s[34:35], 0, v[138:139]
	s_add_i32 m0, s31, 0xc000
	ds_read_b128 v[188:191], v155
	ds_read_b128 v[192:195], v155 offset:1024
	ds_read_b128 v[196:199], v155 offset:2048
	ds_read_b128 v[200:203], v155 offset:3072
	ds_read_b128 v[204:207], v155 offset:4096
	ds_read_b128 v[208:211], v155 offset:5120
	ds_read_b128 v[212:215], v155 offset:6144
	ds_read_b128 v[218:221], v155 offset:7168
	global_load_lds_dwordx4 v[148:149], off
	v_lshl_add_u64 v[148:149], s[34:35], 0, v[140:141]
	s_add_i32 m0, s31, 0xe000
	s_nop 0
	global_load_lds_dwordx4 v[148:149], off
	s_waitcnt vmcnt(8)
	s_waitcnt lgkmcnt(0)
	s_barrier
	s_setprio 1
	s_waitcnt lgkmcnt(0)
	v_mfma_f32_16x16x32_bf16 v[126:129], v[156:159], v[188:191], v[126:129]
	v_mfma_f32_16x16x32_bf16 v[122:125], v[164:167], v[188:191], v[122:125]
	v_mfma_f32_16x16x32_bf16 v[118:121], v[156:159], v[196:199], v[118:121]
	v_mfma_f32_16x16x32_bf16 v[114:117], v[164:167], v[196:199], v[114:117]
	v_mfma_f32_16x16x32_bf16 v[110:113], v[156:159], v[204:207], v[110:113]
	v_mfma_f32_16x16x32_bf16 v[102:105], v[164:167], v[204:207], v[102:105]
	v_mfma_f32_16x16x32_bf16 v[94:97], v[156:159], v[212:215], v[94:97]
	v_mfma_f32_16x16x32_bf16 v[74:77], v[164:167], v[212:215], v[74:77]
	v_mfma_f32_16x16x32_bf16 v[126:129], v[160:163], v[192:195], v[126:129]
	v_mfma_f32_16x16x32_bf16 v[122:125], v[168:171], v[192:195], v[122:125]
	v_mfma_f32_16x16x32_bf16 v[118:121], v[160:163], v[200:203], v[118:121]
	v_mfma_f32_16x16x32_bf16 v[114:117], v[168:171], v[200:203], v[114:117]
	v_mfma_f32_16x16x32_bf16 v[110:113], v[160:163], v[208:211], v[110:113]
	v_mfma_f32_16x16x32_bf16 v[102:105], v[168:171], v[208:211], v[102:105]
	v_mfma_f32_16x16x32_bf16 v[94:97], v[160:163], v[218:221], v[94:97]
	v_mfma_f32_16x16x32_bf16 v[74:77], v[168:171], v[218:221], v[74:77]
	s_setprio 0
	s_setprio 1
	v_mfma_f32_16x16x32_bf16 v[106:109], v[172:175], v[188:191], v[106:109]
	v_mfma_f32_16x16x32_bf16 v[98:101], v[180:183], v[188:191], v[98:101]
	v_mfma_f32_16x16x32_bf16 v[90:93], v[172:175], v[196:199], v[90:93]
	v_mfma_f32_16x16x32_bf16 v[86:89], v[180:183], v[196:199], v[86:89]
	v_mfma_f32_16x16x32_bf16 v[82:85], v[172:175], v[204:207], v[82:85]
	v_mfma_f32_16x16x32_bf16 v[78:81], v[180:183], v[204:207], v[78:81]
	v_mfma_f32_16x16x32_bf16 v[70:73], v[172:175], v[212:215], v[70:73]
	v_mfma_f32_16x16x32_bf16 v[66:69], v[180:183], v[212:215], v[66:69]
	v_mfma_f32_16x16x32_bf16 v[106:109], v[176:179], v[192:195], v[106:109]
	v_mfma_f32_16x16x32_bf16 v[98:101], v[184:187], v[192:195], v[98:101]
	v_mfma_f32_16x16x32_bf16 v[90:93], v[176:179], v[200:203], v[90:93]
	v_mfma_f32_16x16x32_bf16 v[86:89], v[184:187], v[200:203], v[86:89]
	v_mfma_f32_16x16x32_bf16 v[82:85], v[176:179], v[208:211], v[82:85]
	v_mfma_f32_16x16x32_bf16 v[78:81], v[184:187], v[208:211], v[78:81]
	v_mfma_f32_16x16x32_bf16 v[70:73], v[176:179], v[218:221], v[70:73]
	v_mfma_f32_16x16x32_bf16 v[66:69], v[184:187], v[218:221], v[66:69]
	s_setprio 0
	s_barrier
	s_add_i32 s64, s52, s44
	v_lshl_add_u64 v[148:149], s[36:37], 0, v[132:133]
	s_mov_b32 m0, s64
	global_load_lds_dwordx4 v[148:149], off
	s_add_i32 m0, s64, 0x2000
	s_add_u32 s64, s36, 0x100000
	v_lshl_add_u64 v[222:223], s[36:37], 0, v[136:137]
	s_addc_u32 s65, s37, 0
	s_add_i32 s66, s53, s44
	global_load_lds_dwordx4 v[222:223], off
	v_lshl_add_u64 v[224:225], s[64:65], 0, v[132:133]
	s_mov_b32 m0, s66
	v_lshl_add_u64 v[226:227], s[38:39], 0, v[134:135]
	global_load_lds_dwordx4 v[224:225], off
	v_lshl_add_u64 v[224:225], s[64:65], 0, v[136:137]
	s_add_i32 m0, s66, 0x2000
	s_nop 0
	global_load_lds_dwordx4 v[224:225], off
	v_lshl_add_u64 v[224:225], s[38:39], 0, v[130:131]
	s_mov_b32 m0, s31
	s_nop 0
	global_load_lds_dwordx4 v[224:225], off
	s_mov_b32 m0, s45
	s_nop 0
	global_load_lds_dwordx4 v[226:227], off
	ds_read_b128 v[188:191], v155 offset:16384
	ds_read_b128 v[192:195], v155 offset:17408
	ds_read_b128 v[196:199], v155 offset:18432
	ds_read_b128 v[200:203], v155 offset:19456
	ds_read_b128 v[204:207], v155 offset:20480
	ds_read_b128 v[208:211], v155 offset:21504
	ds_read_b128 v[212:215], v155 offset:22528
	ds_read_b128 v[218:221], v155 offset:23552
	s_waitcnt vmcnt(8)
	s_waitcnt lgkmcnt(0)
	s_barrier
; #define PG8_STAGE(bufoff, gbase, voff) do { _Pragma("unroll") for (int _i = 0; _i < 2; ++_i) \
;         __builtin_amdgcn_global_load_lds((const unsigned*)((const char*)(gbase) + (voff)[_i]), (PG8_LAS unsigned*)(lds + (bufoff) + ldsw + _i * 8192), 16, 0, 0); } while (0)
; #define PG8_LDA(dst, b, h) do { _Pragma("unroll") for (int m = 0; m < 4; ++m) _Pragma("unroll") for (int k = 0; k < 2; ++k) dst[m][k] = *(const PG8_LAS bf16x8*)(lds + PG8_SA(b, h) + aoff + m * 2048 + k * 1024); } while (0)
; #define PG8_LDB(dst, b, h) do { _Pragma("unroll") for (int n = 0; n < 2; ++n) _Pragma("unroll") for (int k = 0; k < 2; ++k) dst[n][k] = *(const PG8_LAS bf16x8*)(lds + PG8_SB(b, h) + boff + n * 2048 + k * 1024); } while (0)
; #define PG8_MMA(ai, bj, At, Bt) do { __builtin_amdgcn_s_setprio(1); _Pragma("unroll") for (int m = 0; m < 4; ++m) _Pragma("unroll") for (int n = 0; n < 2; ++n) _Pragma("unroll") for (int k = 0; k < 2; ++k) \
;         acc[ai][bj][m][n] = __builtin_amdgcn_mfma_f32_16x16x32_bf16(Bt[n][k], At[m][k], acc[ai][bj][m][n], 0, 0, 0); __builtin_amdgcn_s_setprio(0); } while (0)
; #define PG8_WAIT_V(n) asm volatile("s_waitcnt vmcnt(" #n ")" ::: "memory")
; #define PG8_WAIT_L(n) asm volatile("s_waitcnt lgkmcnt(" #n ")" ::: "memory")
; #define PG8_BAR __builtin_amdgcn_s_barrier()
; #define PG8_SCHED __builtin_amdgcn_sched_barrier(0)
; template <class Epi, class Sched, bool ALIGN_EPI = false, bool SP2 = false>
; __device__ __forceinline__ void gemm_phase(PG8_LAS unsigned char* lds, const Gemm g, const Sched& S, const Epi& E) {
;     ...
;             PG8_WAIT_V(8); PG8_WAIT_L(0); PG8_BAR; PG8_MMA(1, 0, At, B0); PG8_MMA(1, 1, At, B1); PG8_BAR; PG8_SCHED;
;             PG8_LDB(B0, 1, 0); PG8_LDB(B1, 1, 1); PG8_SCHED; PG8_LDA(At, 1, 0); PG8_STAGE(PG8_SA(0, 1), a2 + hstepA, voffA);
;             PG8_WAIT_V(8); PG8_WAIT_L(0); PG8_BAR; PG8_MMA(0, 0, At, B0); PG8_MMA(0, 1, At, B1); PG8_BAR; PG8_SCHED;
	s_setprio 1
	s_waitcnt lgkmcnt(0)
	v_mfma_f32_16x16x32_bf16 v[62:65], v[156:159], v[188:191], v[62:65]
	v_mfma_f32_16x16x32_bf16 v[58:61], v[164:167], v[188:191], v[58:61]
	v_mfma_f32_16x16x32_bf16 v[50:53], v[156:159], v[196:199], v[50:53]
	v_mfma_f32_16x16x32_bf16 v[42:45], v[164:167], v[196:199], v[42:45]
	v_mfma_f32_16x16x32_bf16 v[34:37], v[156:159], v[204:207], v[34:37]
	v_mfma_f32_16x16x32_bf16 v[26:29], v[164:167], v[204:207], v[26:29]
	v_mfma_f32_16x16x32_bf16 v[18:21], v[156:159], v[212:215], v[18:21]
	v_mfma_f32_16x16x32_bf16 v[10:13], v[164:167], v[212:215], v[10:13]
	v_mfma_f32_16x16x32_bf16 v[62:65], v[160:163], v[192:195], v[62:65]
	v_mfma_f32_16x16x32_bf16 v[58:61], v[168:171], v[192:195], v[58:61]
	v_mfma_f32_16x16x32_bf16 v[50:53], v[160:163], v[200:203], v[50:53]
	v_mfma_f32_16x16x32_bf16 v[42:45], v[168:171], v[200:203], v[42:45]
	v_mfma_f32_16x16x32_bf16 v[34:37], v[160:163], v[208:211], v[34:37]
	v_mfma_f32_16x16x32_bf16 v[26:29], v[168:171], v[208:211], v[26:29]
	v_mfma_f32_16x16x32_bf16 v[18:21], v[160:163], v[218:221], v[18:21]
	v_mfma_f32_16x16x32_bf16 v[10:13], v[168:171], v[218:221], v[10:13]
	s_setprio 0
	s_setprio 1
	v_mfma_f32_16x16x32_bf16 v[54:57], v[172:175], v[188:191], v[54:57]
	v_mfma_f32_16x16x32_bf16 v[46:49], v[180:183], v[188:191], v[46:49]
	v_mfma_f32_16x16x32_bf16 v[38:41], v[172:175], v[196:199], v[38:41]
	v_mfma_f32_16x16x32_bf16 v[30:33], v[180:183], v[196:199], v[30:33]
	v_mfma_f32_16x16x32_bf16 v[22:25], v[172:175], v[204:207], v[22:25]
	v_mfma_f32_16x16x32_bf16 v[14:17], v[180:183], v[204:207], v[14:17]
	v_mfma_f32_16x16x32_bf16 v[6:9], v[172:175], v[212:215], v[6:9]
	v_mfma_f32_16x16x32_bf16 v[2:5], v[180:183], v[212:215], v[2:5]
	v_mfma_f32_16x16x32_bf16 v[54:57], v[176:179], v[192:195], v[54:57]
	v_mfma_f32_16x16x32_bf16 v[46:49], v[184:187], v[192:195], v[46:49]
	v_mfma_f32_16x16x32_bf16 v[38:41], v[176:179], v[200:203], v[38:41]
	v_mfma_f32_16x16x32_bf16 v[30:33], v[184:187], v[200:203], v[30:33]
	v_mfma_f32_16x16x32_bf16 v[22:25], v[176:179], v[208:211], v[22:25]
	v_mfma_f32_16x16x32_bf16 v[14:17], v[184:187], v[208:211], v[14:17]
	v_mfma_f32_16x16x32_bf16 v[6:9], v[176:179], v[218:221], v[6:9]
	v_mfma_f32_16x16x32_bf16 v[2:5], v[184:187], v[218:221], v[2:5]
	s_setprio 0
	s_barrier
	s_add_i32 s64, 0, 0x18000
	v_add_u32_e32 v146, s64, v147
	s_add_i32 s65, 0, 0x1c000
	ds_read_b128 v[156:159], v146
	ds_read_b128 v[160:163], v146 offset:1024
	ds_read_b128 v[164:167], v146 offset:2048
	ds_read_b128 v[168:171], v146 offset:3072
	v_add_u32_e32 v146, s65, v147
	ds_read_b128 v[172:175], v146
	ds_read_b128 v[176:179], v146 offset:1024
	ds_read_b128 v[180:183], v146 offset:2048
	ds_read_b128 v[184:187], v146 offset:3072
	s_add_u32 s38, s38, 0x100000
	s_addc_u32 s39, s39, 0
	s_mov_b32 m0, s46
	v_lshl_add_u64 v[228:229], s[38:39], 0, v[130:131]
	ds_read_b128 v[188:191], v155 offset:32768
	ds_read_b128 v[192:195], v155 offset:33792
	ds_read_b128 v[196:199], v155 offset:34816
	ds_read_b128 v[200:203], v155 offset:35840
	ds_read_b128 v[204:207], v155 offset:36864
	ds_read_b128 v[208:211], v155 offset:37888
	ds_read_b128 v[212:215], v155 offset:38912
	ds_read_b128 v[218:221], v155 offset:39936
	global_load_lds_dwordx4 v[228:229], off
	v_lshl_add_u64 v[228:229], s[38:39], 0, v[134:135]
	s_mov_b32 m0, s47
	s_nop 0
	global_load_lds_dwordx4 v[228:229], off
	s_waitcnt vmcnt(8)
	s_waitcnt lgkmcnt(0)
	s_barrier
	s_setprio 1
	s_waitcnt lgkmcnt(0)
	v_mfma_f32_16x16x32_bf16 v[126:129], v[156:159], v[188:191], v[126:129]
	v_mfma_f32_16x16x32_bf16 v[122:125], v[164:167], v[188:191], v[122:125]
	v_mfma_f32_16x16x32_bf16 v[118:121], v[156:159], v[196:199], v[118:121]
	v_mfma_f32_16x16x32_bf16 v[114:117], v[164:167], v[196:199], v[114:117]
	v_mfma_f32_16x16x32_bf16 v[110:113], v[156:159], v[204:207], v[110:113]
	v_mfma_f32_16x16x32_bf16 v[102:105], v[164:167], v[204:207], v[102:105]
	v_mfma_f32_16x16x32_bf16 v[94:97], v[156:159], v[212:215], v[94:97]
	v_mfma_f32_16x16x32_bf16 v[74:77], v[164:167], v[212:215], v[74:77]
	v_mfma_f32_16x16x32_bf16 v[126:129], v[160:163], v[192:195], v[126:129]
	v_mfma_f32_16x16x32_bf16 v[122:125], v[168:171], v[192:195], v[122:125]
	v_mfma_f32_16x16x32_bf16 v[118:121], v[160:163], v[200:203], v[118:121]
	v_mfma_f32_16x16x32_bf16 v[114:117], v[168:171], v[200:203], v[114:117]
	v_mfma_f32_16x16x32_bf16 v[110:113], v[160:163], v[208:211], v[110:113]
	v_mfma_f32_16x16x32_bf16 v[102:105], v[168:171], v[208:211], v[102:105]
	v_mfma_f32_16x16x32_bf16 v[94:97], v[160:163], v[218:221], v[94:97]
	v_mfma_f32_16x16x32_bf16 v[74:77], v[168:171], v[218:221], v[74:77]
	s_setprio 0
	s_setprio 1
	v_mfma_f32_16x16x32_bf16 v[106:109], v[172:175], v[188:191], v[106:109]
	v_mfma_f32_16x16x32_bf16 v[98:101], v[180:183], v[188:191], v[98:101]
	v_mfma_f32_16x16x32_bf16 v[90:93], v[172:175], v[196:199], v[90:93]
	v_mfma_f32_16x16x32_bf16 v[86:89], v[180:183], v[196:199], v[86:89]
	v_mfma_f32_16x16x32_bf16 v[82:85], v[172:175], v[204:207], v[82:85]
	v_mfma_f32_16x16x32_bf16 v[78:81], v[180:183], v[204:207], v[78:81]
	v_mfma_f32_16x16x32_bf16 v[70:73], v[172:175], v[212:215], v[70:73]
	v_mfma_f32_16x16x32_bf16 v[66:69], v[180:183], v[212:215], v[66:69]
	v_mfma_f32_16x16x32_bf16 v[106:109], v[176:179], v[192:195], v[106:109]
	v_mfma_f32_16x16x32_bf16 v[98:101], v[184:187], v[192:195], v[98:101]
	v_mfma_f32_16x16x32_bf16 v[90:93], v[176:179], v[200:203], v[90:93]
	v_mfma_f32_16x16x32_bf16 v[86:89], v[184:187], v[200:203], v[86:89]
	v_mfma_f32_16x16x32_bf16 v[82:85], v[176:179], v[208:211], v[82:85]
	v_mfma_f32_16x16x32_bf16 v[78:81], v[184:187], v[208:211], v[78:81]
	v_mfma_f32_16x16x32_bf16 v[70:73], v[176:179], v[218:221], v[70:73]
	v_mfma_f32_16x16x32_bf16 v[66:69], v[184:187], v[218:221], v[66:69]
	s_setprio 0
	s_barrier
; #define PG8_STAGE(bufoff, gbase, voff) do { _Pragma("unroll") for (int _i = 0; _i < 2; ++_i) \
;         __builtin_amdgcn_global_load_lds((const unsigned*)((const char*)(gbase) + (voff)[_i]), (PG8_LAS unsigned*)(lds + (bufoff) + ldsw + _i * 8192), 16, 0, 0); } while (0)
; #define PG8_LDA(dst, b, h) do { _Pragma("unroll") for (int m = 0; m < 4; ++m) _Pragma("unroll") for (int k = 0; k < 2; ++k) dst[m][k] = *(const PG8_LAS bf16x8*)(lds + PG8_SA(b, h) + aoff + m * 2048 + k * 1024); } while (0)
; #define PG8_MMA(ai, bj, At, Bt) do { __builtin_amdgcn_s_setprio(1); _Pragma("unroll") for (int m = 0; m < 4; ++m) _Pragma("unroll") for (int n = 0; n < 2; ++n) _Pragma("unroll") for (int k = 0; k < 2; ++k) \
;         acc[ai][bj][m][n] = __builtin_amdgcn_mfma_f32_16x16x32_bf16(Bt[n][k], At[m][k], acc[ai][bj][m][n], 0, 0, 0); __builtin_amdgcn_s_setprio(0); } while (0)
; #define PG8_WAIT_V(n) asm volatile("s_waitcnt vmcnt(" #n ")" ::: "memory")
; #define PG8_WAIT_L(n) asm volatile("s_waitcnt lgkmcnt(" #n ")" ::: "memory")
; #define PG8_BAR __builtin_amdgcn_s_barrier()
; #define PG8_SCHED __builtin_amdgcn_sched_barrier(0)
; template <class Epi, class Sched, bool ALIGN_EPI = false, bool SP2 = false>
; __device__ __forceinline__ void gemm_phase(PG8_LAS unsigned char* lds, const Gemm g, const Sched& S, const Epi& E) {
;     ...
;             PG8_LDA(At, 1, 1); PG8_STAGE(PG8_SB(1, 0), b3, voffB); PG8_STAGE(PG8_SB(1, 1), b3 + hstepB, voffB); PG8_STAGE(PG8_SA(1, 0), a3, voffA);
;             PG8_WAIT_V(8); PG8_WAIT_L(0); PG8_BAR; PG8_MMA(1, 0, At, B0); PG8_MMA(1, 1, At, B1); PG8_BAR; PG8_SCHED;
;     ...
;         if constexpr (ALIGN_EPI) { if (wr == 0) PG8_BAR; }
	s_add_i32 s38, s64, s44
	v_lshl_add_u64 v[148:149], v[148:149], 0, s[10:11]
	s_mov_b32 m0, s38
	global_load_lds_dwordx4 v[148:149], off
	s_add_i32 m0, s38, 0x2000
	s_add_u32 s36, s36, 0x100080
	v_lshl_add_u64 v[148:149], v[222:223], 0, s[10:11]
	s_addc_u32 s37, s37, 0
	s_add_i32 s38, s65, s44
	global_load_lds_dwordx4 v[148:149], off
	v_lshl_add_u64 v[148:149], s[36:37], 0, v[132:133]
	s_mov_b32 m0, s38
	s_nop 0
	global_load_lds_dwordx4 v[148:149], off
	v_lshl_add_u64 v[148:149], s[36:37], 0, v[136:137]
	s_add_i32 m0, s38, 0x2000
	s_nop 0
	global_load_lds_dwordx4 v[148:149], off
	v_lshl_add_u64 v[148:149], v[224:225], 0, s[10:11]
	s_mov_b32 m0, s49
	s_nop 0
	global_load_lds_dwordx4 v[148:149], off
	v_lshl_add_u64 v[148:149], v[226:227], 0, s[10:11]
	s_mov_b32 m0, s50
	s_nop 0
	global_load_lds_dwordx4 v[148:149], off
	ds_read_b128 v[188:191], v155 offset:49152
	ds_read_b128 v[192:195], v155 offset:50176
	ds_read_b128 v[196:199], v155 offset:51200
	ds_read_b128 v[200:203], v155 offset:52224
	ds_read_b128 v[204:207], v155 offset:53248
	ds_read_b128 v[208:211], v155 offset:54272
	ds_read_b128 v[212:215], v155 offset:55296
	ds_read_b128 v[218:221], v155 offset:56320
	s_waitcnt vmcnt(8)
	s_waitcnt lgkmcnt(0)
	s_barrier
	s_setprio 1
	s_waitcnt lgkmcnt(0)
	v_mfma_f32_16x16x32_bf16 v[62:65], v[156:159], v[188:191], v[62:65]
	v_mfma_f32_16x16x32_bf16 v[58:61], v[164:167], v[188:191], v[58:61]
	v_mfma_f32_16x16x32_bf16 v[50:53], v[156:159], v[196:199], v[50:53]
	v_mfma_f32_16x16x32_bf16 v[42:45], v[164:167], v[196:199], v[42:45]
	v_mfma_f32_16x16x32_bf16 v[34:37], v[156:159], v[204:207], v[34:37]
	v_mfma_f32_16x16x32_bf16 v[26:29], v[164:167], v[204:207], v[26:29]
	v_mfma_f32_16x16x32_bf16 v[18:21], v[156:159], v[212:215], v[18:21]
	v_mfma_f32_16x16x32_bf16 v[10:13], v[164:167], v[212:215], v[10:13]
	v_mfma_f32_16x16x32_bf16 v[62:65], v[160:163], v[192:195], v[62:65]
	v_mfma_f32_16x16x32_bf16 v[58:61], v[168:171], v[192:195], v[58:61]
	v_mfma_f32_16x16x32_bf16 v[50:53], v[160:163], v[200:203], v[50:53]
	v_mfma_f32_16x16x32_bf16 v[42:45], v[168:171], v[200:203], v[42:45]
	v_mfma_f32_16x16x32_bf16 v[34:37], v[160:163], v[208:211], v[34:37]
	v_mfma_f32_16x16x32_bf16 v[26:29], v[168:171], v[208:211], v[26:29]
	v_mfma_f32_16x16x32_bf16 v[18:21], v[160:163], v[218:221], v[18:21]
	v_mfma_f32_16x16x32_bf16 v[10:13], v[168:171], v[218:221], v[10:13]
	s_setprio 0
	s_setprio 1
	v_mfma_f32_16x16x32_bf16 v[54:57], v[172:175], v[188:191], v[54:57]
	v_mfma_f32_16x16x32_bf16 v[46:49], v[180:183], v[188:191], v[46:49]
	v_mfma_f32_16x16x32_bf16 v[38:41], v[172:175], v[196:199], v[38:41]
	v_mfma_f32_16x16x32_bf16 v[30:33], v[180:183], v[196:199], v[30:33]
	v_mfma_f32_16x16x32_bf16 v[22:25], v[172:175], v[204:207], v[22:25]
	v_mfma_f32_16x16x32_bf16 v[14:17], v[180:183], v[204:207], v[14:17]
	v_mfma_f32_16x16x32_bf16 v[6:9], v[172:175], v[212:215], v[6:9]
	v_mfma_f32_16x16x32_bf16 v[2:5], v[180:183], v[212:215], v[2:5]
	v_mfma_f32_16x16x32_bf16 v[54:57], v[176:179], v[192:195], v[54:57]
	v_mfma_f32_16x16x32_bf16 v[46:49], v[184:187], v[192:195], v[46:49]
	v_mfma_f32_16x16x32_bf16 v[38:41], v[176:179], v[200:203], v[38:41]
	v_mfma_f32_16x16x32_bf16 v[30:33], v[184:187], v[200:203], v[30:33]
	v_mfma_f32_16x16x32_bf16 v[22:25], v[176:179], v[208:211], v[22:25]
	v_mfma_f32_16x16x32_bf16 v[14:17], v[184:187], v[208:211], v[14:17]
	v_mfma_f32_16x16x32_bf16 v[6:9], v[176:179], v[218:221], v[6:9]
	v_mfma_f32_16x16x32_bf16 v[2:5], v[184:187], v[218:221], v[2:5]
	s_setprio 0
	s_barrier
	s_add_i32 s63, s63, 2
	s_add_u32 s34, s34, 0x100
	s_addc_u32 s35, s35, 0
	s_add_u32 s61, s61, 0x100
	s_addc_u32 s62, s62, 0
	s_cmp_gt_u32 s63, 61
	s_cbranch_scc0 .LBB0_1097
	s_and_b64 vcc, exec, s[12:13]
	s_cbranch_vccz .LBB0_1100
	s_barrier

; #define PG8_STAGE(bufoff, gbase, voff) do { _Pragma("unroll") for (int _i = 0; _i < 2; ++_i) \
;         __builtin_amdgcn_global_load_lds((const unsigned*)((const char*)(gbase) + (voff)[_i]), (PG8_LAS unsigned*)(lds + (bufoff) + ldsw + _i * 8192), 16, 0, 0); } while (0)
; #define PG8_LDA(dst, b, h) do { _Pragma("unroll") for (int m = 0; m < 4; ++m) _Pragma("unroll") for (int k = 0; k < 2; ++k) dst[m][k] = *(const PG8_LAS bf16x8*)(lds + PG8_SA(b, h) + aoff + m * 2048 + k * 1024); } while (0)
; #define PG8_LDB(dst, b, h) do { _Pragma("unroll") for (int n = 0; n < 2; ++n) _Pragma("unroll") for (int k = 0; k < 2; ++k) dst[n][k] = *(const PG8_LAS bf16x8*)(lds + PG8_SB(b, h) + boff + n * 2048 + k * 1024); } while (0)
; #define PG8_MMA(ai, bj, At, Bt) do { __builtin_amdgcn_s_setprio(1); _Pragma("unroll") for (int m = 0; m < 4; ++m) _Pragma("unroll") for (int n = 0; n < 2; ++n) _Pragma("unroll") for (int k = 0; k < 2; ++k) \
;         acc[ai][bj][m][n] = __builtin_amdgcn_mfma_f32_16x16x32_bf16(Bt[n][k], At[m][k], acc[ai][bj][m][n], 0, 0, 0); __builtin_amdgcn_s_setprio(0); } while (0)
; #define PG8_WAIT_V(n) asm volatile("s_waitcnt vmcnt(" #n ")" ::: "memory")
; #define PG8_WAIT_L(n) asm volatile("s_waitcnt lgkmcnt(" #n ")" ::: "memory")
; template <class Epi, class Sched, bool ALIGN_EPI = false, bool SP2 = false>
; __device__ __forceinline__ void gemm_phase(PG8_LAS unsigned char* lds, const Gemm g, const Sched& S, const Epi& E) {
;     ...
;             const bool last = (t == nt - 2);
;             const char* a1 = cA + (size_t)(t + 1) * kstep;
;             const char* a2 = last ? nA : cA + (size_t)(t + 2) * kstep; const char* b2 = last ? nB : cB + (size_t)(t + 2) * kstep;
;             const char* a3 = a2 + kstep; const char* b3 = b2 + kstep;
;             if (last && has_next) S.a_ready(nxt);
;             if constexpr (SP2) {
;             PG8_LDB(B0, 0, 0); PG8_LDB(B1, 0, 1); PG8_SCHED; PG8_LDA(At, 0, 0); PG8_STAGE(PG8_SA(1, 1), a1 + hstepA, voffA);
;             PG8_WAIT_V(8); PG8_WAIT_L(0); PG8_BAR; PG8_MMA(0, 0, At, B0); PG8_MMA(0, 1, At, B1); PG8_BAR; PG8_SCHED;
;             PG8_LDA(At, 0, 1); PG8_STAGE(PG8_SB(0, 0), b2, voffB); PG8_STAGE(PG8_SB(0, 1), b2 + hstepB, voffB); PG8_STAGE(PG8_SA(0, 0), a2, voffA);
;             PG8_WAIT_V(8); PG8_WAIT_L(0); PG8_BAR; PG8_MMA(1, 0, At, B0); PG8_MMA(1, 1, At, B1); PG8_BAR; PG8_SCHED;
.LBB0_1231:
	ds_read_b128 v[74:77], v219
	ds_read_b128 v[78:81], v219 offset:1024
	ds_read_b128 v[82:85], v219 offset:2048
	ds_read_b128 v[142:145], v219 offset:3072
	ds_read_b128 v[146:149], v220
	ds_read_b128 v[150:153], v220 offset:1024
	ds_read_b128 v[170:173], v220 offset:2048
	ds_read_b128 v[174:177], v220 offset:3072
	s_add_i32 s14, s8, 2
	s_add_u32 s15, s4, 0xfff00080
	s_addc_u32 s9, s5, -1
	s_cmp_eq_u32 s61, s8
	s_cselect_b32 s8, s13, s15
	s_cselect_b32 s9, s7, s9
	s_cselect_b32 s17, s45, s11
	s_cselect_b32 s16, s44, s10
	v_lshl_add_u64 v[210:211], s[4:5], 0, v[162:163]
	s_add_i32 m0, s51, 0xc000
	ds_read_b128 v[178:181], v221
	ds_read_b128 v[182:185], v221 offset:1024
	ds_read_b128 v[186:189], v221 offset:2048
	ds_read_b128 v[190:193], v221 offset:3072
	ds_read_b128 v[194:197], v221 offset:4096
	ds_read_b128 v[198:201], v221 offset:5120
	ds_read_b128 v[202:205], v221 offset:6144
	ds_read_b128 v[206:209], v221 offset:7168
	global_load_lds_dwordx4 v[210:211], off
	v_lshl_add_u64 v[210:211], s[4:5], 0, v[164:165]
	s_add_i32 m0, s51, 0xe000
	s_nop 0
	global_load_lds_dwordx4 v[210:211], off
	s_waitcnt vmcnt(8)
	s_waitcnt lgkmcnt(0)
	s_barrier
	s_setprio 1
	s_waitcnt lgkmcnt(0)
	v_mfma_f32_16x16x32_bf16 v[134:137], v[74:77], v[178:181], v[134:137]
	v_mfma_f32_16x16x32_bf16 v[58:61], v[82:85], v[178:181], v[58:61]
	v_mfma_f32_16x16x32_bf16 v[126:129], v[74:77], v[186:189], v[126:129]
	v_mfma_f32_16x16x32_bf16 v[50:53], v[82:85], v[186:189], v[50:53]
	v_mfma_f32_16x16x32_bf16 v[118:121], v[74:77], v[194:197], v[118:121]
	v_mfma_f32_16x16x32_bf16 v[42:45], v[82:85], v[194:197], v[42:45]
	v_mfma_f32_16x16x32_bf16 v[110:113], v[74:77], v[202:205], v[110:113]
	v_mfma_f32_16x16x32_bf16 v[34:37], v[82:85], v[202:205], v[34:37]
	v_mfma_f32_16x16x32_bf16 v[134:137], v[78:81], v[182:185], v[134:137]
	v_mfma_f32_16x16x32_bf16 v[58:61], v[142:145], v[182:185], v[58:61]
	v_mfma_f32_16x16x32_bf16 v[126:129], v[78:81], v[190:193], v[126:129]
	v_mfma_f32_16x16x32_bf16 v[50:53], v[142:145], v[190:193], v[50:53]
	v_mfma_f32_16x16x32_bf16 v[118:121], v[78:81], v[198:201], v[118:121]
	v_mfma_f32_16x16x32_bf16 v[42:45], v[142:145], v[198:201], v[42:45]
	v_mfma_f32_16x16x32_bf16 v[110:113], v[78:81], v[206:209], v[110:113]
	v_mfma_f32_16x16x32_bf16 v[34:37], v[142:145], v[206:209], v[34:37]
	s_setprio 0
	s_setprio 1
	v_mfma_f32_16x16x32_bf16 v[138:141], v[146:149], v[178:181], v[138:141]
	v_mfma_f32_16x16x32_bf16 v[62:65], v[170:173], v[178:181], v[62:65]
	v_mfma_f32_16x16x32_bf16 v[130:133], v[146:149], v[186:189], v[130:133]
	v_mfma_f32_16x16x32_bf16 v[54:57], v[170:173], v[186:189], v[54:57]
	v_mfma_f32_16x16x32_bf16 v[122:125], v[146:149], v[194:197], v[122:125]
	v_mfma_f32_16x16x32_bf16 v[46:49], v[170:173], v[194:197], v[46:49]
	v_mfma_f32_16x16x32_bf16 v[114:117], v[146:149], v[202:205], v[114:117]
	v_mfma_f32_16x16x32_bf16 v[38:41], v[170:173], v[202:205], v[38:41]
	v_mfma_f32_16x16x32_bf16 v[138:141], v[150:153], v[182:185], v[138:141]
	v_mfma_f32_16x16x32_bf16 v[62:65], v[174:177], v[182:185], v[62:65]
	v_mfma_f32_16x16x32_bf16 v[130:133], v[150:153], v[190:193], v[130:133]
	v_mfma_f32_16x16x32_bf16 v[54:57], v[174:177], v[190:193], v[54:57]
	v_mfma_f32_16x16x32_bf16 v[122:125], v[150:153], v[198:201], v[122:125]
	v_mfma_f32_16x16x32_bf16 v[46:49], v[174:177], v[198:201], v[46:49]
	v_mfma_f32_16x16x32_bf16 v[114:117], v[150:153], v[206:209], v[114:117]
	v_mfma_f32_16x16x32_bf16 v[38:41], v[174:177], v[206:209], v[38:41]
	s_setprio 0
	s_barrier
	s_add_i32 s15, s63, s50
	v_lshl_add_u64 v[210:211], s[16:17], 0, v[156:157]
	s_mov_b32 m0, s15
	global_load_lds_dwordx4 v[210:211], off
	s_add_i32 m0, s15, 0x2000
	v_lshl_add_u64 v[212:213], s[16:17], 0, v[160:161]
	s_add_u32 s16, s16, s22
	s_addc_u32 s17, s17, s23
	s_add_i32 s15, s64, s50
	global_load_lds_dwordx4 v[212:213], off
	v_lshl_add_u64 v[214:215], s[16:17], 0, v[156:157]
	s_mov_b32 m0, s15
	v_lshl_add_u64 v[222:223], s[16:17], 0, v[160:161]
	global_load_lds_dwordx4 v[214:215], off
	s_add_i32 m0, s15, 0x2000
	v_lshl_add_u64 v[224:225], s[8:9], 0, v[154:155]
	global_load_lds_dwordx4 v[222:223], off
	s_mov_b32 m0, s51
	v_lshl_add_u64 v[226:227], s[8:9], 0, v[158:159]
	global_load_lds_dwordx4 v[224:225], off
	s_mov_b32 m0, s52
	s_nop 0
	global_load_lds_dwordx4 v[226:227], off
	ds_read_b128 v[178:181], v221 offset:16384
	ds_read_b128 v[182:185], v221 offset:17408
	ds_read_b128 v[186:189], v221 offset:18432
	ds_read_b128 v[190:193], v221 offset:19456
	ds_read_b128 v[194:197], v221 offset:20480
	ds_read_b128 v[198:201], v221 offset:21504
	ds_read_b128 v[202:205], v221 offset:22528
	ds_read_b128 v[206:209], v221 offset:23552
	s_waitcnt vmcnt(8)
	s_waitcnt lgkmcnt(0)
	s_barrier
; #define PG8_STAGE(bufoff, gbase, voff) do { _Pragma("unroll") for (int _i = 0; _i < 2; ++_i) \
;         __builtin_amdgcn_global_load_lds((const unsigned*)((const char*)(gbase) + (voff)[_i]), (PG8_LAS unsigned*)(lds + (bufoff) + ldsw + _i * 8192), 16, 0, 0); } while (0)
; #define PG8_LDA(dst, b, h) do { _Pragma("unroll") for (int m = 0; m < 4; ++m) _Pragma("unroll") for (int k = 0; k < 2; ++k) dst[m][k] = *(const PG8_LAS bf16x8*)(lds + PG8_SA(b, h) + aoff + m * 2048 + k * 1024); } while (0)
; #define PG8_LDB(dst, b, h) do { _Pragma("unroll") for (int n = 0; n < 2; ++n) _Pragma("unroll") for (int k = 0; k < 2; ++k) dst[n][k] = *(const PG8_LAS bf16x8*)(lds + PG8_SB(b, h) + boff + n * 2048 + k * 1024); } while (0)
; #define PG8_MMA(ai, bj, At, Bt) do { __builtin_amdgcn_s_setprio(1); _Pragma("unroll") for (int m = 0; m < 4; ++m) _Pragma("unroll") for (int n = 0; n < 2; ++n) _Pragma("unroll") for (int k = 0; k < 2; ++k) \
;         acc[ai][bj][m][n] = __builtin_amdgcn_mfma_f32_16x16x32_bf16(Bt[n][k], At[m][k], acc[ai][bj][m][n], 0, 0, 0); __builtin_amdgcn_s_setprio(0); } while (0)
; #define PG8_WAIT_V(n) asm volatile("s_waitcnt vmcnt(" #n ")" ::: "memory")
; #define PG8_WAIT_L(n) asm volatile("s_waitcnt lgkmcnt(" #n ")" ::: "memory")
; #define PG8_BAR __builtin_amdgcn_s_barrier()
; #define PG8_SCHED __builtin_amdgcn_sched_barrier(0)
; template <class Epi, class Sched, bool ALIGN_EPI = false, bool SP2 = false>
; __device__ __forceinline__ void gemm_phase(PG8_LAS unsigned char* lds, const Gemm g, const Sched& S, const Epi& E) {
;     ...
;             PG8_WAIT_V(8); PG8_WAIT_L(0); PG8_BAR; PG8_MMA(1, 0, At, B0); PG8_MMA(1, 1, At, B1); PG8_BAR; PG8_SCHED;
;             PG8_LDB(B0, 1, 0); PG8_LDB(B1, 1, 1); PG8_SCHED; PG8_LDA(At, 1, 0); PG8_STAGE(PG8_SA(0, 1), a2 + hstepA, voffA);
;             PG8_WAIT_V(8); PG8_WAIT_L(0); PG8_BAR; PG8_MMA(0, 0, At, B0); PG8_MMA(0, 1, At, B1); PG8_BAR; PG8_SCHED;
	s_setprio 1
	s_waitcnt lgkmcnt(0)
	v_mfma_f32_16x16x32_bf16 v[102:105], v[74:77], v[178:181], v[102:105]
	v_mfma_f32_16x16x32_bf16 v[26:29], v[82:85], v[178:181], v[26:29]
	v_mfma_f32_16x16x32_bf16 v[94:97], v[74:77], v[186:189], v[94:97]
	v_mfma_f32_16x16x32_bf16 v[18:21], v[82:85], v[186:189], v[18:21]
	v_mfma_f32_16x16x32_bf16 v[86:89], v[74:77], v[194:197], v[86:89]
	v_mfma_f32_16x16x32_bf16 v[10:13], v[82:85], v[194:197], v[10:13]
	v_mfma_f32_16x16x32_bf16 v[66:69], v[74:77], v[202:205], v[66:69]
	v_mfma_f32_16x16x32_bf16 v[2:5], v[82:85], v[202:205], v[2:5]
	v_mfma_f32_16x16x32_bf16 v[102:105], v[78:81], v[182:185], v[102:105]
	v_mfma_f32_16x16x32_bf16 v[26:29], v[142:145], v[182:185], v[26:29]
	v_mfma_f32_16x16x32_bf16 v[94:97], v[78:81], v[190:193], v[94:97]
	v_mfma_f32_16x16x32_bf16 v[18:21], v[142:145], v[190:193], v[18:21]
	v_mfma_f32_16x16x32_bf16 v[86:89], v[78:81], v[198:201], v[86:89]
	v_mfma_f32_16x16x32_bf16 v[10:13], v[142:145], v[198:201], v[10:13]
	v_mfma_f32_16x16x32_bf16 v[66:69], v[78:81], v[206:209], v[66:69]
	v_mfma_f32_16x16x32_bf16 v[2:5], v[142:145], v[206:209], v[2:5]
	s_setprio 0
	s_setprio 1
	v_mfma_f32_16x16x32_bf16 v[30:33], v[170:173], v[178:181], v[30:33]
	v_mfma_f32_16x16x32_bf16 v[22:25], v[170:173], v[186:189], v[22:25]
	v_mfma_f32_16x16x32_bf16 v[14:17], v[170:173], v[194:197], v[14:17]
	v_mfma_f32_16x16x32_bf16 v[70:73], v[146:149], v[202:205], v[70:73]
	v_mfma_f32_16x16x32_bf16 v[6:9], v[170:173], v[202:205], v[6:9]
	v_mfma_f32_16x16x32_bf16 v[74:77], v[146:149], v[178:181], v[106:109]
	v_mfma_f32_16x16x32_bf16 v[30:33], v[174:177], v[182:185], v[30:33]
	v_mfma_f32_16x16x32_bf16 v[78:81], v[146:149], v[186:189], v[98:101]
	v_mfma_f32_16x16x32_bf16 v[22:25], v[174:177], v[190:193], v[22:25]
	v_mfma_f32_16x16x32_bf16 v[82:85], v[146:149], v[194:197], v[90:93]
	v_mfma_f32_16x16x32_bf16 v[14:17], v[174:177], v[198:201], v[14:17]
	v_mfma_f32_16x16x32_bf16 v[70:73], v[150:153], v[206:209], v[70:73]
	v_mfma_f32_16x16x32_bf16 v[6:9], v[174:177], v[206:209], v[6:9]
	v_mfma_f32_16x16x32_bf16 v[74:77], v[150:153], v[182:185], v[74:77]
	v_mfma_f32_16x16x32_bf16 v[78:81], v[150:153], v[190:193], v[78:81]
	v_mfma_f32_16x16x32_bf16 v[82:85], v[150:153], v[198:201], v[82:85]
	s_setprio 0
	s_barrier
	s_add_i32 s15, 0, 0x18000
	s_add_i32 s16, 0, 0x1c000
	v_add_u32_e32 v142, s15, v218
	v_add_u32_e32 v174, s16, v218
	ds_read_b128 v[90:93], v142
	ds_read_b128 v[98:101], v142 offset:1024
	ds_read_b128 v[106:109], v142 offset:2048
	ds_read_b128 v[142:145], v142 offset:3072
	ds_read_b128 v[146:149], v174
	ds_read_b128 v[150:153], v174 offset:1024
	ds_read_b128 v[170:173], v174 offset:2048
	ds_read_b128 v[174:177], v174 offset:3072
	s_add_u32 s8, s8, 0x100000
	s_addc_u32 s9, s9, 0
	s_mov_b32 m0, s53
	v_lshl_add_u64 v[228:229], s[8:9], 0, v[154:155]
	ds_read_b128 v[178:181], v221 offset:32768
	ds_read_b128 v[182:185], v221 offset:33792
	ds_read_b128 v[186:189], v221 offset:34816
	ds_read_b128 v[190:193], v221 offset:35840
	ds_read_b128 v[194:197], v221 offset:36864
	ds_read_b128 v[198:201], v221 offset:37888
	ds_read_b128 v[202:205], v221 offset:38912
	ds_read_b128 v[206:209], v221 offset:39936
	global_load_lds_dwordx4 v[228:229], off
	v_lshl_add_u64 v[228:229], s[8:9], 0, v[158:159]
	s_mov_b32 m0, s54
	s_nop 0
	global_load_lds_dwordx4 v[228:229], off
	s_waitcnt vmcnt(8)
	s_waitcnt lgkmcnt(0)
	s_barrier
	s_setprio 1
	s_waitcnt lgkmcnt(0)
	v_mfma_f32_16x16x32_bf16 v[134:137], v[90:93], v[178:181], v[134:137]
	v_mfma_f32_16x16x32_bf16 v[58:61], v[106:109], v[178:181], v[58:61]
	v_mfma_f32_16x16x32_bf16 v[126:129], v[90:93], v[186:189], v[126:129]
	v_mfma_f32_16x16x32_bf16 v[50:53], v[106:109], v[186:189], v[50:53]
	v_mfma_f32_16x16x32_bf16 v[118:121], v[90:93], v[194:197], v[118:121]
	v_mfma_f32_16x16x32_bf16 v[42:45], v[106:109], v[194:197], v[42:45]
	v_mfma_f32_16x16x32_bf16 v[110:113], v[90:93], v[202:205], v[110:113]
	v_mfma_f32_16x16x32_bf16 v[34:37], v[106:109], v[202:205], v[34:37]
	v_mfma_f32_16x16x32_bf16 v[134:137], v[98:101], v[182:185], v[134:137]
	v_mfma_f32_16x16x32_bf16 v[58:61], v[142:145], v[182:185], v[58:61]
	v_mfma_f32_16x16x32_bf16 v[126:129], v[98:101], v[190:193], v[126:129]
	v_mfma_f32_16x16x32_bf16 v[50:53], v[142:145], v[190:193], v[50:53]
	v_mfma_f32_16x16x32_bf16 v[118:121], v[98:101], v[198:201], v[118:121]
	v_mfma_f32_16x16x32_bf16 v[42:45], v[142:145], v[198:201], v[42:45]
	v_mfma_f32_16x16x32_bf16 v[110:113], v[98:101], v[206:209], v[110:113]
	v_mfma_f32_16x16x32_bf16 v[34:37], v[142:145], v[206:209], v[34:37]
	s_setprio 0
	s_setprio 1
	v_mfma_f32_16x16x32_bf16 v[138:141], v[146:149], v[178:181], v[138:141]
	v_mfma_f32_16x16x32_bf16 v[62:65], v[170:173], v[178:181], v[62:65]
	v_mfma_f32_16x16x32_bf16 v[130:133], v[146:149], v[186:189], v[130:133]
	v_mfma_f32_16x16x32_bf16 v[54:57], v[170:173], v[186:189], v[54:57]
	v_mfma_f32_16x16x32_bf16 v[122:125], v[146:149], v[194:197], v[122:125]
	v_mfma_f32_16x16x32_bf16 v[46:49], v[170:173], v[194:197], v[46:49]
	v_mfma_f32_16x16x32_bf16 v[114:117], v[146:149], v[202:205], v[114:117]
	v_mfma_f32_16x16x32_bf16 v[38:41], v[170:173], v[202:205], v[38:41]
	v_mfma_f32_16x16x32_bf16 v[138:141], v[150:153], v[182:185], v[138:141]
	v_mfma_f32_16x16x32_bf16 v[62:65], v[174:177], v[182:185], v[62:65]
	v_mfma_f32_16x16x32_bf16 v[130:133], v[150:153], v[190:193], v[130:133]
	v_mfma_f32_16x16x32_bf16 v[54:57], v[174:177], v[190:193], v[54:57]
	v_mfma_f32_16x16x32_bf16 v[122:125], v[150:153], v[198:201], v[122:125]
	v_mfma_f32_16x16x32_bf16 v[46:49], v[174:177], v[198:201], v[46:49]
	v_mfma_f32_16x16x32_bf16 v[114:117], v[150:153], v[206:209], v[114:117]
	v_mfma_f32_16x16x32_bf16 v[38:41], v[174:177], v[206:209], v[38:41]
	s_setprio 0
	s_barrier
; #define PG8_STAGE(bufoff, gbase, voff) do { _Pragma("unroll") for (int _i = 0; _i < 2; ++_i) \
;         __builtin_amdgcn_global_load_lds((const unsigned*)((const char*)(gbase) + (voff)[_i]), (PG8_LAS unsigned*)(lds + (bufoff) + ldsw + _i * 8192), 16, 0, 0); } while (0)
; #define PG8_LDA(dst, b, h) do { _Pragma("unroll") for (int m = 0; m < 4; ++m) _Pragma("unroll") for (int k = 0; k < 2; ++k) dst[m][k] = *(const PG8_LAS bf16x8*)(lds + PG8_SA(b, h) + aoff + m * 2048 + k * 1024); } while (0)
; #define PG8_MMA(ai, bj, At, Bt) do { __builtin_amdgcn_s_setprio(1); _Pragma("unroll") for (int m = 0; m < 4; ++m) _Pragma("unroll") for (int n = 0; n < 2; ++n) _Pragma("unroll") for (int k = 0; k < 2; ++k) \
;         acc[ai][bj][m][n] = __builtin_amdgcn_mfma_f32_16x16x32_bf16(Bt[n][k], At[m][k], acc[ai][bj][m][n], 0, 0, 0); __builtin_amdgcn_s_setprio(0); } while (0)
; #define PG8_WAIT_V(n) asm volatile("s_waitcnt vmcnt(" #n ")" ::: "memory")
; #define PG8_WAIT_L(n) asm volatile("s_waitcnt lgkmcnt(" #n ")" ::: "memory")
; #define PG8_BAR __builtin_amdgcn_s_barrier()
; #define PG8_SCHED __builtin_amdgcn_sched_barrier(0)
; template <class Epi, class Sched, bool ALIGN_EPI = false, bool SP2 = false>
; __device__ __forceinline__ void gemm_phase(PG8_LAS unsigned char* lds, const Gemm g, const Sched& S, const Epi& E) {
;     ...
;             PG8_LDA(At, 1, 1); PG8_STAGE(PG8_SB(1, 0), b3, voffB); PG8_STAGE(PG8_SB(1, 1), b3 + hstepB, voffB); PG8_STAGE(PG8_SA(1, 0), a3, voffA);
;             PG8_WAIT_V(8); PG8_WAIT_L(0); PG8_BAR; PG8_MMA(1, 0, At, B0); PG8_MMA(1, 1, At, B1); PG8_BAR; PG8_SCHED;
	s_add_i32 s8, s15, s50
	v_lshl_add_u64 v[210:211], v[210:211], 0, s[34:35]
	s_mov_b32 m0, s8
	global_load_lds_dwordx4 v[210:211], off
	v_lshl_add_u64 v[210:211], v[212:213], 0, s[34:35]
	s_add_i32 m0, s8, 0x2000
	s_add_i32 s8, s16, s50
	global_load_lds_dwordx4 v[210:211], off
	v_lshl_add_u64 v[210:211], v[214:215], 0, s[34:35]
	s_mov_b32 m0, s8
	s_nop 0
	global_load_lds_dwordx4 v[210:211], off
	v_lshl_add_u64 v[210:211], v[222:223], 0, s[34:35]
	s_add_i32 m0, s8, 0x2000
	s_nop 0
	global_load_lds_dwordx4 v[210:211], off
	v_lshl_add_u64 v[210:211], v[224:225], 0, s[34:35]
	s_mov_b32 m0, s56
	s_nop 0
	global_load_lds_dwordx4 v[210:211], off
	v_lshl_add_u64 v[210:211], v[226:227], 0, s[34:35]
	s_mov_b32 m0, s57
	s_nop 0
	global_load_lds_dwordx4 v[210:211], off
	ds_read_b128 v[178:181], v221 offset:49152
	ds_read_b128 v[182:185], v221 offset:50176
	ds_read_b128 v[186:189], v221 offset:51200
	ds_read_b128 v[190:193], v221 offset:52224
	ds_read_b128 v[194:197], v221 offset:53248
	ds_read_b128 v[198:201], v221 offset:54272
	ds_read_b128 v[202:205], v221 offset:55296
	ds_read_b128 v[206:209], v221 offset:56320
	s_waitcnt vmcnt(8)
	s_waitcnt lgkmcnt(0)
	s_barrier
	s_setprio 1
	s_waitcnt lgkmcnt(0)
	v_mfma_f32_16x16x32_bf16 v[102:105], v[90:93], v[178:181], v[102:105]
	v_mfma_f32_16x16x32_bf16 v[26:29], v[106:109], v[178:181], v[26:29]
	v_mfma_f32_16x16x32_bf16 v[94:97], v[90:93], v[186:189], v[94:97]
	v_mfma_f32_16x16x32_bf16 v[18:21], v[106:109], v[186:189], v[18:21]
	v_mfma_f32_16x16x32_bf16 v[86:89], v[90:93], v[194:197], v[86:89]
	v_mfma_f32_16x16x32_bf16 v[10:13], v[106:109], v[194:197], v[10:13]
	v_mfma_f32_16x16x32_bf16 v[66:69], v[90:93], v[202:205], v[66:69]
	v_mfma_f32_16x16x32_bf16 v[2:5], v[106:109], v[202:205], v[2:5]
	v_mfma_f32_16x16x32_bf16 v[102:105], v[98:101], v[182:185], v[102:105]
	v_mfma_f32_16x16x32_bf16 v[26:29], v[142:145], v[182:185], v[26:29]
	v_mfma_f32_16x16x32_bf16 v[94:97], v[98:101], v[190:193], v[94:97]
	v_mfma_f32_16x16x32_bf16 v[18:21], v[142:145], v[190:193], v[18:21]
	v_mfma_f32_16x16x32_bf16 v[86:89], v[98:101], v[198:201], v[86:89]
	v_mfma_f32_16x16x32_bf16 v[10:13], v[142:145], v[198:201], v[10:13]
	v_mfma_f32_16x16x32_bf16 v[66:69], v[98:101], v[206:209], v[66:69]
	v_mfma_f32_16x16x32_bf16 v[2:5], v[142:145], v[206:209], v[2:5]
	s_setprio 0
	s_setprio 1
	v_mfma_f32_16x16x32_bf16 v[74:77], v[146:149], v[178:181], v[74:77]
	v_mfma_f32_16x16x32_bf16 v[106:109], v[150:153], v[182:185], v[74:77]
	v_mfma_f32_16x16x32_bf16 v[74:77], v[146:149], v[186:189], v[78:81]
	v_mfma_f32_16x16x32_bf16 v[30:33], v[170:173], v[178:181], v[30:33]
	v_mfma_f32_16x16x32_bf16 v[98:101], v[150:153], v[190:193], v[74:77]
	v_mfma_f32_16x16x32_bf16 v[22:25], v[170:173], v[186:189], v[22:25]
	v_mfma_f32_16x16x32_bf16 v[74:77], v[146:149], v[194:197], v[82:85]
	v_mfma_f32_16x16x32_bf16 v[14:17], v[170:173], v[194:197], v[14:17]
	v_mfma_f32_16x16x32_bf16 v[70:73], v[146:149], v[202:205], v[70:73]
	v_mfma_f32_16x16x32_bf16 v[6:9], v[170:173], v[202:205], v[6:9]
	v_mfma_f32_16x16x32_bf16 v[30:33], v[174:177], v[182:185], v[30:33]
	v_mfma_f32_16x16x32_bf16 v[22:25], v[174:177], v[190:193], v[22:25]
	v_mfma_f32_16x16x32_bf16 v[90:93], v[150:153], v[198:201], v[74:77]
	v_mfma_f32_16x16x32_bf16 v[14:17], v[174:177], v[198:201], v[14:17]
	v_mfma_f32_16x16x32_bf16 v[70:73], v[150:153], v[206:209], v[70:73]
	v_mfma_f32_16x16x32_bf16 v[6:9], v[174:177], v[206:209], v[6:9]
	s_setprio 0
	s_barrier
	s_add_u32 s4, s4, 0x100
	s_addc_u32 s5, s5, 0
	s_add_u32 s10, s10, 0x100
	s_addc_u32 s11, s11, 0
	s_cmp_ge_i32 s14, s58
	s_mov_b32 s8, s14
	s_cbranch_scc0 .LBB0_1231

; #define PG8_STAGE(bufoff, gbase, voff) do { _Pragma("unroll") for (int _i = 0; _i < 2; ++_i) \
;         __builtin_amdgcn_global_load_lds((const unsigned*)((const char*)(gbase) + (voff)[_i]), (PG8_LAS unsigned*)(lds + (bufoff) + ldsw + _i * 8192), 16, 0, 0); } while (0)
; #define PG8_LDA(dst, b, h) do { _Pragma("unroll") for (int m = 0; m < 4; ++m) _Pragma("unroll") for (int k = 0; k < 2; ++k) dst[m][k] = *(const PG8_LAS bf16x8*)(lds + PG8_SA(b, h) + aoff + m * 2048 + k * 1024); } while (0)
; #define PG8_LDB(dst, b, h) do { _Pragma("unroll") for (int n = 0; n < 2; ++n) _Pragma("unroll") for (int k = 0; k < 2; ++k) dst[n][k] = *(const PG8_LAS bf16x8*)(lds + PG8_SB(b, h) + boff + n * 2048 + k * 1024); } while (0)
; #define PG8_MMA(ai, bj, At, Bt) do { __builtin_amdgcn_s_setprio(1); _Pragma("unroll") for (int m = 0; m < 4; ++m) _Pragma("unroll") for (int n = 0; n < 2; ++n) _Pragma("unroll") for (int k = 0; k < 2; ++k) \
;         acc[ai][bj][m][n] = __builtin_amdgcn_mfma_f32_16x16x32_bf16(Bt[n][k], At[m][k], acc[ai][bj][m][n], 0, 0, 0); __builtin_amdgcn_s_setprio(0); } while (0)
; #define PG8_WAIT_V(n) asm volatile("s_waitcnt vmcnt(" #n ")" ::: "memory")
; #define PG8_WAIT_L(n) asm volatile("s_waitcnt lgkmcnt(" #n ")" ::: "memory")
; template <class Epi, class Sched, bool ALIGN_EPI = false, bool SP2 = false>
; __device__ __forceinline__ void gemm_phase(PG8_LAS unsigned char* lds, const Gemm g, const Sched& S, const Epi& E) {
;     ...
;             const bool last = (t == nt - 2);
;             const char* a1 = cA + (size_t)(t + 1) * kstep;
;             const char* a2 = last ? nA : cA + (size_t)(t + 2) * kstep; const char* b2 = last ? nB : cB + (size_t)(t + 2) * kstep;
;             const char* a3 = a2 + kstep; const char* b3 = b2 + kstep;
;             if (last && has_next) S.a_ready(nxt);
;             if constexpr (SP2) {
;             PG8_LDB(B0, 0, 0); PG8_LDB(B1, 0, 1); PG8_SCHED; PG8_LDA(At, 0, 0); PG8_STAGE(PG8_SA(1, 1), a1 + hstepA, voffA);
;             PG8_WAIT_V(8); PG8_WAIT_L(0); PG8_BAR; PG8_MMA(0, 0, At, B0); PG8_MMA(0, 1, At, B1); PG8_BAR; PG8_SCHED;
;             PG8_LDA(At, 0, 1); PG8_STAGE(PG8_SB(0, 0), b2, voffB); PG8_STAGE(PG8_SB(0, 1), b2 + hstepB, voffB); PG8_STAGE(PG8_SA(0, 0), a2, voffA);
;             PG8_WAIT_V(8); PG8_WAIT_L(0); PG8_BAR; PG8_MMA(1, 0, At, B0); PG8_MMA(1, 1, At, B1); PG8_BAR; PG8_SCHED;
.LBB0_1743:
	s_lshl_b32 s36, s62, 7
	s_add_u32 s37, s24, s36
	s_addc_u32 s38, s25, 0
	v_add_u32_e32 v140, s53, v143
	s_add_u32 s39, s37, 0x100
	ds_read_b128 v[146:149], v140
	ds_read_b128 v[150:153], v140 offset:1024
	ds_read_b128 v[154:157], v140 offset:2048
	ds_read_b128 v[158:161], v140 offset:3072
	v_add_u32_e32 v140, s54, v143
	s_addc_u32 s63, s38, 0
	ds_read_b128 v[162:165], v140
	ds_read_b128 v[166:169], v140 offset:1024
	ds_read_b128 v[170:173], v140 offset:2048
	ds_read_b128 v[174:177], v140 offset:3072
	s_and_b64 s[34:35], s[30:31], exec
	s_cselect_b32 s35, s23, s63
	s_cselect_b32 s34, s59, s39
	s_add_u32 s36, s26, s36
	s_addc_u32 s39, s27, 0
	s_add_u32 s36, s36, 0x100
	s_addc_u32 s39, s39, 0
	s_and_b64 s[30:31], s[30:31], exec
	s_cselect_b32 s31, s60, s39
	s_cselect_b32 s30, s61, s36
	s_add_u32 s36, s37, 0x100080
	s_addc_u32 s37, s38, 0
	v_lshl_add_u64 v[140:141], s[36:37], 0, v[130:131]
	s_add_i32 m0, s45, 0xc000
	ds_read_b128 v[178:181], v144
	ds_read_b128 v[182:185], v144 offset:1024
	ds_read_b128 v[186:189], v144 offset:2048
	ds_read_b128 v[190:193], v144 offset:3072
	ds_read_b128 v[194:197], v144 offset:4096
	ds_read_b128 v[198:201], v144 offset:5120
	ds_read_b128 v[202:205], v144 offset:6144
	ds_read_b128 v[206:209], v144 offset:7168
	global_load_lds_dwordx4 v[140:141], off
	v_lshl_add_u64 v[140:141], s[36:37], 0, v[134:135]
	s_add_i32 m0, s45, 0xe000
	s_nop 0
	global_load_lds_dwordx4 v[140:141], off
	s_waitcnt vmcnt(8)
	s_waitcnt lgkmcnt(0)
	s_barrier
	s_setprio 1
	s_waitcnt lgkmcnt(0)
	v_mfma_f32_16x16x32_bf16 v[126:129], v[146:149], v[178:181], v[126:129]
	v_mfma_f32_16x16x32_bf16 v[122:125], v[154:157], v[178:181], v[122:125]
	v_mfma_f32_16x16x32_bf16 v[114:117], v[146:149], v[186:189], v[114:117]
	v_mfma_f32_16x16x32_bf16 v[106:109], v[154:157], v[186:189], v[106:109]
	v_mfma_f32_16x16x32_bf16 v[98:101], v[146:149], v[194:197], v[98:101]
	v_mfma_f32_16x16x32_bf16 v[90:93], v[154:157], v[194:197], v[90:93]
	v_mfma_f32_16x16x32_bf16 v[82:85], v[146:149], v[202:205], v[82:85]
	v_mfma_f32_16x16x32_bf16 v[74:77], v[154:157], v[202:205], v[74:77]
	v_mfma_f32_16x16x32_bf16 v[126:129], v[150:153], v[182:185], v[126:129]
	v_mfma_f32_16x16x32_bf16 v[122:125], v[158:161], v[182:185], v[122:125]
	v_mfma_f32_16x16x32_bf16 v[114:117], v[150:153], v[190:193], v[114:117]
	v_mfma_f32_16x16x32_bf16 v[106:109], v[158:161], v[190:193], v[106:109]
	v_mfma_f32_16x16x32_bf16 v[98:101], v[150:153], v[198:201], v[98:101]
	v_mfma_f32_16x16x32_bf16 v[90:93], v[158:161], v[198:201], v[90:93]
	v_mfma_f32_16x16x32_bf16 v[82:85], v[150:153], v[206:209], v[82:85]
	v_mfma_f32_16x16x32_bf16 v[74:77], v[158:161], v[206:209], v[74:77]
	s_setprio 0
	s_setprio 1
	v_mfma_f32_16x16x32_bf16 v[118:121], v[162:165], v[178:181], v[118:121]
	v_mfma_f32_16x16x32_bf16 v[110:113], v[170:173], v[178:181], v[110:113]
	v_mfma_f32_16x16x32_bf16 v[102:105], v[162:165], v[186:189], v[102:105]
	v_mfma_f32_16x16x32_bf16 v[94:97], v[170:173], v[186:189], v[94:97]
	v_mfma_f32_16x16x32_bf16 v[86:89], v[162:165], v[194:197], v[86:89]
	v_mfma_f32_16x16x32_bf16 v[78:81], v[170:173], v[194:197], v[78:81]
	v_mfma_f32_16x16x32_bf16 v[70:73], v[162:165], v[202:205], v[70:73]
	v_mfma_f32_16x16x32_bf16 v[66:69], v[170:173], v[202:205], v[66:69]
	v_mfma_f32_16x16x32_bf16 v[118:121], v[166:169], v[182:185], v[118:121]
	v_mfma_f32_16x16x32_bf16 v[110:113], v[174:177], v[182:185], v[110:113]
	v_mfma_f32_16x16x32_bf16 v[102:105], v[166:169], v[190:193], v[102:105]
	v_mfma_f32_16x16x32_bf16 v[94:97], v[174:177], v[190:193], v[94:97]
	v_mfma_f32_16x16x32_bf16 v[86:89], v[166:169], v[198:201], v[86:89]
	v_mfma_f32_16x16x32_bf16 v[78:81], v[174:177], v[198:201], v[78:81]
	v_mfma_f32_16x16x32_bf16 v[70:73], v[166:169], v[206:209], v[70:73]
	v_mfma_f32_16x16x32_bf16 v[66:69], v[174:177], v[206:209], v[66:69]
	s_setprio 0
	s_barrier
	s_add_i32 s36, s53, s43
	v_lshl_add_u64 v[140:141], s[30:31], 0, v[132:133]
	s_mov_b32 m0, s36
	global_load_lds_dwordx4 v[140:141], off
	s_add_i32 m0, s36, 0x2000
	s_add_u32 s36, s30, 0x100000
	v_lshl_add_u64 v[210:211], s[30:31], 0, v[136:137]
	s_addc_u32 s37, s31, 0
	s_add_i32 s38, s54, s43
	global_load_lds_dwordx4 v[210:211], off
	v_lshl_add_u64 v[212:213], s[36:37], 0, v[132:133]
	s_mov_b32 m0, s38
	v_lshl_add_u64 v[214:215], s[34:35], 0, v[134:135]
	global_load_lds_dwordx4 v[212:213], off
	v_lshl_add_u64 v[212:213], s[36:37], 0, v[136:137]
	s_add_i32 m0, s38, 0x2000
	s_nop 0
	global_load_lds_dwordx4 v[212:213], off
	v_lshl_add_u64 v[212:213], s[34:35], 0, v[130:131]
	s_mov_b32 m0, s45
	s_nop 0
	global_load_lds_dwordx4 v[212:213], off
	s_mov_b32 m0, s46
	s_nop 0
	global_load_lds_dwordx4 v[214:215], off
	ds_read_b128 v[178:181], v144 offset:16384
	ds_read_b128 v[182:185], v144 offset:17408
	ds_read_b128 v[186:189], v144 offset:18432
	ds_read_b128 v[190:193], v144 offset:19456
	ds_read_b128 v[194:197], v144 offset:20480
	ds_read_b128 v[198:201], v144 offset:21504
	ds_read_b128 v[202:205], v144 offset:22528
	ds_read_b128 v[206:209], v144 offset:23552
	s_waitcnt vmcnt(8)
	s_waitcnt lgkmcnt(0)
	s_barrier
; #define PG8_STAGE(bufoff, gbase, voff) do { _Pragma("unroll") for (int _i = 0; _i < 2; ++_i) \
;         __builtin_amdgcn_global_load_lds((const unsigned*)((const char*)(gbase) + (voff)[_i]), (PG8_LAS unsigned*)(lds + (bufoff) + ldsw + _i * 8192), 16, 0, 0); } while (0)
; #define PG8_LDA(dst, b, h) do { _Pragma("unroll") for (int m = 0; m < 4; ++m) _Pragma("unroll") for (int k = 0; k < 2; ++k) dst[m][k] = *(const PG8_LAS bf16x8*)(lds + PG8_SA(b, h) + aoff + m * 2048 + k * 1024); } while (0)
; #define PG8_LDB(dst, b, h) do { _Pragma("unroll") for (int n = 0; n < 2; ++n) _Pragma("unroll") for (int k = 0; k < 2; ++k) dst[n][k] = *(const PG8_LAS bf16x8*)(lds + PG8_SB(b, h) + boff + n * 2048 + k * 1024); } while (0)
; #define PG8_MMA(ai, bj, At, Bt) do { __builtin_amdgcn_s_setprio(1); _Pragma("unroll") for (int m = 0; m < 4; ++m) _Pragma("unroll") for (int n = 0; n < 2; ++n) _Pragma("unroll") for (int k = 0; k < 2; ++k) \
;         acc[ai][bj][m][n] = __builtin_amdgcn_mfma_f32_16x16x32_bf16(Bt[n][k], At[m][k], acc[ai][bj][m][n], 0, 0, 0); __builtin_amdgcn_s_setprio(0); } while (0)
; #define PG8_WAIT_V(n) asm volatile("s_waitcnt vmcnt(" #n ")" ::: "memory")
; #define PG8_WAIT_L(n) asm volatile("s_waitcnt lgkmcnt(" #n ")" ::: "memory")
; #define PG8_BAR __builtin_amdgcn_s_barrier()
; #define PG8_SCHED __builtin_amdgcn_sched_barrier(0)
; template <class Epi, class Sched, bool ALIGN_EPI = false, bool SP2 = false>
; __device__ __forceinline__ void gemm_phase(PG8_LAS unsigned char* lds, const Gemm g, const Sched& S, const Epi& E) {
;     ...
;             PG8_WAIT_V(8); PG8_WAIT_L(0); PG8_BAR; PG8_MMA(1, 0, At, B0); PG8_MMA(1, 1, At, B1); PG8_BAR; PG8_SCHED;
;             PG8_LDB(B0, 1, 0); PG8_LDB(B1, 1, 1); PG8_SCHED; PG8_LDA(At, 1, 0); PG8_STAGE(PG8_SA(0, 1), a2 + hstepA, voffA);
;             PG8_WAIT_V(8); PG8_WAIT_L(0); PG8_BAR; PG8_MMA(0, 0, At, B0); PG8_MMA(0, 1, At, B1); PG8_BAR; PG8_SCHED;
	s_setprio 1
	s_waitcnt lgkmcnt(0)
	v_mfma_f32_16x16x32_bf16 v[62:65], v[146:149], v[178:181], v[62:65]
	v_mfma_f32_16x16x32_bf16 v[58:61], v[154:157], v[178:181], v[58:61]
	v_mfma_f32_16x16x32_bf16 v[50:53], v[146:149], v[186:189], v[50:53]
	v_mfma_f32_16x16x32_bf16 v[42:45], v[154:157], v[186:189], v[42:45]
	v_mfma_f32_16x16x32_bf16 v[34:37], v[146:149], v[194:197], v[34:37]
	v_mfma_f32_16x16x32_bf16 v[26:29], v[154:157], v[194:197], v[26:29]
	v_mfma_f32_16x16x32_bf16 v[18:21], v[146:149], v[202:205], v[18:21]
	v_mfma_f32_16x16x32_bf16 v[10:13], v[154:157], v[202:205], v[10:13]
	v_mfma_f32_16x16x32_bf16 v[62:65], v[150:153], v[182:185], v[62:65]
	v_mfma_f32_16x16x32_bf16 v[58:61], v[158:161], v[182:185], v[58:61]
	v_mfma_f32_16x16x32_bf16 v[50:53], v[150:153], v[190:193], v[50:53]
	v_mfma_f32_16x16x32_bf16 v[42:45], v[158:161], v[190:193], v[42:45]
	v_mfma_f32_16x16x32_bf16 v[34:37], v[150:153], v[198:201], v[34:37]
	v_mfma_f32_16x16x32_bf16 v[26:29], v[158:161], v[198:201], v[26:29]
	v_mfma_f32_16x16x32_bf16 v[18:21], v[150:153], v[206:209], v[18:21]
	v_mfma_f32_16x16x32_bf16 v[10:13], v[158:161], v[206:209], v[10:13]
	s_setprio 0
	s_setprio 1
	v_mfma_f32_16x16x32_bf16 v[54:57], v[162:165], v[178:181], v[54:57]
	v_mfma_f32_16x16x32_bf16 v[46:49], v[170:173], v[178:181], v[46:49]
	v_mfma_f32_16x16x32_bf16 v[38:41], v[162:165], v[186:189], v[38:41]
	v_mfma_f32_16x16x32_bf16 v[30:33], v[170:173], v[186:189], v[30:33]
	v_mfma_f32_16x16x32_bf16 v[22:25], v[162:165], v[194:197], v[22:25]
	v_mfma_f32_16x16x32_bf16 v[14:17], v[170:173], v[194:197], v[14:17]
	v_mfma_f32_16x16x32_bf16 v[6:9], v[162:165], v[202:205], v[6:9]
	v_mfma_f32_16x16x32_bf16 v[2:5], v[170:173], v[202:205], v[2:5]
	v_mfma_f32_16x16x32_bf16 v[54:57], v[166:169], v[182:185], v[54:57]
	v_mfma_f32_16x16x32_bf16 v[46:49], v[174:177], v[182:185], v[46:49]
	v_mfma_f32_16x16x32_bf16 v[38:41], v[166:169], v[190:193], v[38:41]
	v_mfma_f32_16x16x32_bf16 v[30:33], v[174:177], v[190:193], v[30:33]
	v_mfma_f32_16x16x32_bf16 v[22:25], v[166:169], v[198:201], v[22:25]
	v_mfma_f32_16x16x32_bf16 v[14:17], v[174:177], v[198:201], v[14:17]
	v_mfma_f32_16x16x32_bf16 v[6:9], v[166:169], v[206:209], v[6:9]
	v_mfma_f32_16x16x32_bf16 v[2:5], v[174:177], v[206:209], v[2:5]
	s_setprio 0
	s_barrier
	s_add_i32 s36, 0, 0x18000
	v_add_u32_e32 v145, s36, v143
	s_add_i32 s37, 0, 0x1c000
	ds_read_b128 v[146:149], v145
	ds_read_b128 v[150:153], v145 offset:1024
	ds_read_b128 v[154:157], v145 offset:2048
	ds_read_b128 v[158:161], v145 offset:3072
	v_add_u32_e32 v145, s37, v143
	ds_read_b128 v[162:165], v145
	ds_read_b128 v[166:169], v145 offset:1024
	ds_read_b128 v[170:173], v145 offset:2048
	ds_read_b128 v[174:177], v145 offset:3072
	s_add_u32 s34, s34, 0x100000
	s_addc_u32 s35, s35, 0
	s_mov_b32 m0, s47
	v_lshl_add_u64 v[218:219], s[34:35], 0, v[130:131]
	ds_read_b128 v[178:181], v144 offset:32768
	ds_read_b128 v[182:185], v144 offset:33792
	ds_read_b128 v[186:189], v144 offset:34816
	ds_read_b128 v[190:193], v144 offset:35840
	ds_read_b128 v[194:197], v144 offset:36864
	ds_read_b128 v[198:201], v144 offset:37888
	ds_read_b128 v[202:205], v144 offset:38912
	ds_read_b128 v[206:209], v144 offset:39936
	global_load_lds_dwordx4 v[218:219], off
	v_lshl_add_u64 v[218:219], s[34:35], 0, v[134:135]
	s_mov_b32 m0, s48
	s_nop 0
	global_load_lds_dwordx4 v[218:219], off
	s_waitcnt vmcnt(8)
	s_waitcnt lgkmcnt(0)
	s_barrier
	s_setprio 1
	s_waitcnt lgkmcnt(0)
	v_mfma_f32_16x16x32_bf16 v[126:129], v[146:149], v[178:181], v[126:129]
	v_mfma_f32_16x16x32_bf16 v[122:125], v[154:157], v[178:181], v[122:125]
	v_mfma_f32_16x16x32_bf16 v[114:117], v[146:149], v[186:189], v[114:117]
	v_mfma_f32_16x16x32_bf16 v[106:109], v[154:157], v[186:189], v[106:109]
	v_mfma_f32_16x16x32_bf16 v[98:101], v[146:149], v[194:197], v[98:101]
	v_mfma_f32_16x16x32_bf16 v[90:93], v[154:157], v[194:197], v[90:93]
	v_mfma_f32_16x16x32_bf16 v[82:85], v[146:149], v[202:205], v[82:85]
	v_mfma_f32_16x16x32_bf16 v[74:77], v[154:157], v[202:205], v[74:77]
	v_mfma_f32_16x16x32_bf16 v[126:129], v[150:153], v[182:185], v[126:129]
	v_mfma_f32_16x16x32_bf16 v[122:125], v[158:161], v[182:185], v[122:125]
	v_mfma_f32_16x16x32_bf16 v[114:117], v[150:153], v[190:193], v[114:117]
	v_mfma_f32_16x16x32_bf16 v[106:109], v[158:161], v[190:193], v[106:109]
	v_mfma_f32_16x16x32_bf16 v[98:101], v[150:153], v[198:201], v[98:101]
	v_mfma_f32_16x16x32_bf16 v[90:93], v[158:161], v[198:201], v[90:93]
	v_mfma_f32_16x16x32_bf16 v[82:85], v[150:153], v[206:209], v[82:85]
	v_mfma_f32_16x16x32_bf16 v[74:77], v[158:161], v[206:209], v[74:77]
	s_setprio 0
	s_setprio 1
	v_mfma_f32_16x16x32_bf16 v[118:121], v[162:165], v[178:181], v[118:121]
	v_mfma_f32_16x16x32_bf16 v[110:113], v[170:173], v[178:181], v[110:113]
	v_mfma_f32_16x16x32_bf16 v[102:105], v[162:165], v[186:189], v[102:105]
	v_mfma_f32_16x16x32_bf16 v[94:97], v[170:173], v[186:189], v[94:97]
	v_mfma_f32_16x16x32_bf16 v[86:89], v[162:165], v[194:197], v[86:89]
	v_mfma_f32_16x16x32_bf16 v[78:81], v[170:173], v[194:197], v[78:81]
	v_mfma_f32_16x16x32_bf16 v[70:73], v[162:165], v[202:205], v[70:73]
	v_mfma_f32_16x16x32_bf16 v[66:69], v[170:173], v[202:205], v[66:69]
	v_mfma_f32_16x16x32_bf16 v[118:121], v[166:169], v[182:185], v[118:121]
	v_mfma_f32_16x16x32_bf16 v[110:113], v[174:177], v[182:185], v[110:113]
	v_mfma_f32_16x16x32_bf16 v[102:105], v[166:169], v[190:193], v[102:105]
	v_mfma_f32_16x16x32_bf16 v[94:97], v[174:177], v[190:193], v[94:97]
	v_mfma_f32_16x16x32_bf16 v[86:89], v[166:169], v[198:201], v[86:89]
	v_mfma_f32_16x16x32_bf16 v[78:81], v[174:177], v[198:201], v[78:81]
	v_mfma_f32_16x16x32_bf16 v[70:73], v[166:169], v[206:209], v[70:73]
	v_mfma_f32_16x16x32_bf16 v[66:69], v[174:177], v[206:209], v[66:69]
	s_setprio 0
	s_barrier
; #define PG8_STAGE(bufoff, gbase, voff) do { _Pragma("unroll") for (int _i = 0; _i < 2; ++_i) \
;         __builtin_amdgcn_global_load_lds((const unsigned*)((const char*)(gbase) + (voff)[_i]), (PG8_LAS unsigned*)(lds + (bufoff) + ldsw + _i * 8192), 16, 0, 0); } while (0)
; #define PG8_LDA(dst, b, h) do { _Pragma("unroll") for (int m = 0; m < 4; ++m) _Pragma("unroll") for (int k = 0; k < 2; ++k) dst[m][k] = *(const PG8_LAS bf16x8*)(lds + PG8_SA(b, h) + aoff + m * 2048 + k * 1024); } while (0)
; #define PG8_MMA(ai, bj, At, Bt) do { __builtin_amdgcn_s_setprio(1); _Pragma("unroll") for (int m = 0; m < 4; ++m) _Pragma("unroll") for (int n = 0; n < 2; ++n) _Pragma("unroll") for (int k = 0; k < 2; ++k) \
;         acc[ai][bj][m][n] = __builtin_amdgcn_mfma_f32_16x16x32_bf16(Bt[n][k], At[m][k], acc[ai][bj][m][n], 0, 0, 0); __builtin_amdgcn_s_setprio(0); } while (0)
; #define PG8_WAIT_V(n) asm volatile("s_waitcnt vmcnt(" #n ")" ::: "memory")
; #define PG8_WAIT_L(n) asm volatile("s_waitcnt lgkmcnt(" #n ")" ::: "memory")
; #define PG8_BAR __builtin_amdgcn_s_barrier()
; #define PG8_SCHED __builtin_amdgcn_sched_barrier(0)
; template <class Epi, class Sched, bool ALIGN_EPI = false, bool SP2 = false>
; __device__ __forceinline__ void gemm_phase(PG8_LAS unsigned char* lds, const Gemm g, const Sched& S, const Epi& E) {
;     ...
;             PG8_LDA(At, 1, 1); PG8_STAGE(PG8_SB(1, 0), b3, voffB); PG8_STAGE(PG8_SB(1, 1), b3 + hstepB, voffB); PG8_STAGE(PG8_SA(1, 0), a3, voffA);
;             PG8_WAIT_V(8); PG8_WAIT_L(0); PG8_BAR; PG8_MMA(1, 0, At, B0); PG8_MMA(1, 1, At, B1); PG8_BAR; PG8_SCHED;
	s_add_i32 s34, s36, s43
	v_lshl_add_u64 v[140:141], v[140:141], 0, s[10:11]
	s_mov_b32 m0, s34
	global_load_lds_dwordx4 v[140:141], off
	s_add_i32 m0, s34, 0x2000
	s_add_u32 s30, s30, 0x100080
	v_lshl_add_u64 v[140:141], v[210:211], 0, s[10:11]
	s_addc_u32 s31, s31, 0
	s_add_i32 s34, s37, s43
	global_load_lds_dwordx4 v[140:141], off
	v_lshl_add_u64 v[140:141], s[30:31], 0, v[132:133]
	s_mov_b32 m0, s34
	s_nop 0
	global_load_lds_dwordx4 v[140:141], off
	v_lshl_add_u64 v[140:141], s[30:31], 0, v[136:137]
	s_add_i32 m0, s34, 0x2000
	s_nop 0
	global_load_lds_dwordx4 v[140:141], off
	v_lshl_add_u64 v[140:141], v[212:213], 0, s[10:11]
	s_mov_b32 m0, s49
	s_nop 0
	global_load_lds_dwordx4 v[140:141], off
	v_lshl_add_u64 v[140:141], v[214:215], 0, s[10:11]
	s_mov_b32 m0, s50
	s_nop 0
	global_load_lds_dwordx4 v[140:141], off
	ds_read_b128 v[178:181], v144 offset:49152
	ds_read_b128 v[182:185], v144 offset:50176
	ds_read_b128 v[186:189], v144 offset:51200
	ds_read_b128 v[190:193], v144 offset:52224
	ds_read_b128 v[194:197], v144 offset:53248
	ds_read_b128 v[198:201], v144 offset:54272
	ds_read_b128 v[202:205], v144 offset:55296
	ds_read_b128 v[206:209], v144 offset:56320
	s_waitcnt vmcnt(8)
	s_waitcnt lgkmcnt(0)
	s_barrier
	s_setprio 1
	s_waitcnt lgkmcnt(0)
	v_mfma_f32_16x16x32_bf16 v[62:65], v[146:149], v[178:181], v[62:65]
	v_mfma_f32_16x16x32_bf16 v[58:61], v[154:157], v[178:181], v[58:61]
	v_mfma_f32_16x16x32_bf16 v[50:53], v[146:149], v[186:189], v[50:53]
	v_mfma_f32_16x16x32_bf16 v[42:45], v[154:157], v[186:189], v[42:45]
	v_mfma_f32_16x16x32_bf16 v[34:37], v[146:149], v[194:197], v[34:37]
	v_mfma_f32_16x16x32_bf16 v[26:29], v[154:157], v[194:197], v[26:29]
	v_mfma_f32_16x16x32_bf16 v[18:21], v[146:149], v[202:205], v[18:21]
	v_mfma_f32_16x16x32_bf16 v[10:13], v[154:157], v[202:205], v[10:13]
	v_mfma_f32_16x16x32_bf16 v[62:65], v[150:153], v[182:185], v[62:65]
	v_mfma_f32_16x16x32_bf16 v[58:61], v[158:161], v[182:185], v[58:61]
	v_mfma_f32_16x16x32_bf16 v[50:53], v[150:153], v[190:193], v[50:53]
	v_mfma_f32_16x16x32_bf16 v[42:45], v[158:161], v[190:193], v[42:45]
	v_mfma_f32_16x16x32_bf16 v[34:37], v[150:153], v[198:201], v[34:37]
	v_mfma_f32_16x16x32_bf16 v[26:29], v[158:161], v[198:201], v[26:29]
	v_mfma_f32_16x16x32_bf16 v[18:21], v[150:153], v[206:209], v[18:21]
	v_mfma_f32_16x16x32_bf16 v[10:13], v[158:161], v[206:209], v[10:13]
	s_setprio 0
	s_setprio 1
	v_mfma_f32_16x16x32_bf16 v[54:57], v[162:165], v[178:181], v[54:57]
	v_mfma_f32_16x16x32_bf16 v[46:49], v[170:173], v[178:181], v[46:49]
	v_mfma_f32_16x16x32_bf16 v[38:41], v[162:165], v[186:189], v[38:41]
	v_mfma_f32_16x16x32_bf16 v[30:33], v[170:173], v[186:189], v[30:33]
	v_mfma_f32_16x16x32_bf16 v[22:25], v[162:165], v[194:197], v[22:25]
	v_mfma_f32_16x16x32_bf16 v[14:17], v[170:173], v[194:197], v[14:17]
	v_mfma_f32_16x16x32_bf16 v[6:9], v[162:165], v[202:205], v[6:9]
	v_mfma_f32_16x16x32_bf16 v[2:5], v[170:173], v[202:205], v[2:5]
	v_mfma_f32_16x16x32_bf16 v[54:57], v[166:169], v[182:185], v[54:57]
	v_mfma_f32_16x16x32_bf16 v[46:49], v[174:177], v[182:185], v[46:49]
	v_mfma_f32_16x16x32_bf16 v[38:41], v[166:169], v[190:193], v[38:41]
	v_mfma_f32_16x16x32_bf16 v[30:33], v[174:177], v[190:193], v[30:33]
	v_mfma_f32_16x16x32_bf16 v[22:25], v[166:169], v[198:201], v[22:25]
	v_mfma_f32_16x16x32_bf16 v[14:17], v[174:177], v[198:201], v[14:17]
	v_mfma_f32_16x16x32_bf16 v[6:9], v[166:169], v[206:209], v[6:9]
	v_mfma_f32_16x16x32_bf16 v[2:5], v[174:177], v[206:209], v[2:5]
	s_setprio 0
	s_barrier
	s_add_i32 s30, s62, 2
	s_cmp_gt_u32 s62, 61
	s_mov_b32 s62, s30
	s_cbranch_scc1 .LBB0_1770

; #define PG8_STAGE(bufoff, gbase, voff) do { _Pragma("unroll") for (int _i = 0; _i < 2; ++_i) \
;         __builtin_amdgcn_global_load_lds((const unsigned*)((const char*)(gbase) + (voff)[_i]), (PG8_LAS unsigned*)(lds + (bufoff) + ldsw + _i * 8192), 16, 0, 0); } while (0)
; #define PG8_LDA(dst, b, h) do { _Pragma("unroll") for (int m = 0; m < 4; ++m) _Pragma("unroll") for (int k = 0; k < 2; ++k) dst[m][k] = *(const PG8_LAS bf16x8*)(lds + PG8_SA(b, h) + aoff + m * 2048 + k * 1024); } while (0)
; #define PG8_LDB(dst, b, h) do { _Pragma("unroll") for (int n = 0; n < 2; ++n) _Pragma("unroll") for (int k = 0; k < 2; ++k) dst[n][k] = *(const PG8_LAS bf16x8*)(lds + PG8_SB(b, h) + boff + n * 2048 + k * 1024); } while (0)
; #define PG8_MMA(ai, bj, At, Bt) do { __builtin_amdgcn_s_setprio(1); _Pragma("unroll") for (int m = 0; m < 4; ++m) _Pragma("unroll") for (int n = 0; n < 2; ++n) _Pragma("unroll") for (int k = 0; k < 2; ++k) \
;         acc[ai][bj][m][n] = __builtin_amdgcn_mfma_f32_16x16x32_bf16(Bt[n][k], At[m][k], acc[ai][bj][m][n], 0, 0, 0); __builtin_amdgcn_s_setprio(0); } while (0)
; #define PG8_WAIT_V(n) asm volatile("s_waitcnt vmcnt(" #n ")" ::: "memory")
; #define PG8_WAIT_L(n) asm volatile("s_waitcnt lgkmcnt(" #n ")" ::: "memory")
; template <class Epi, class Sched, bool ALIGN_EPI = false, bool SP2 = false>
; __device__ __forceinline__ void gemm_phase(PG8_LAS unsigned char* lds, const Gemm g, const Sched& S, const Epi& E) {
;     ...
;             const bool last = (t == nt - 2);
;             const char* a1 = cA + (size_t)(t + 1) * kstep;
;             const char* a2 = last ? nA : cA + (size_t)(t + 2) * kstep; const char* b2 = last ? nB : cB + (size_t)(t + 2) * kstep;
;             const char* a3 = a2 + kstep; const char* b3 = b2 + kstep;
;             if (last && has_next) S.a_ready(nxt);
;             if constexpr (SP2) {
;             PG8_LDB(B0, 0, 0); PG8_LDB(B1, 0, 1); PG8_SCHED; PG8_LDA(At, 0, 0); PG8_STAGE(PG8_SA(1, 1), a1 + hstepA, voffA);
;             PG8_WAIT_V(8); PG8_WAIT_L(0); PG8_BAR; PG8_MMA(0, 0, At, B0); PG8_MMA(0, 1, At, B1); PG8_BAR; PG8_SCHED;
;             PG8_LDA(At, 0, 1); PG8_STAGE(PG8_SB(0, 0), b2, voffB); PG8_STAGE(PG8_SB(0, 1), b2 + hstepB, voffB); PG8_STAGE(PG8_SA(0, 0), a2, voffA);
;             PG8_WAIT_V(8); PG8_WAIT_L(0); PG8_BAR; PG8_MMA(1, 0, At, B0); PG8_MMA(1, 1, At, B1); PG8_BAR; PG8_SCHED;
.LBB0_1868:
	ds_read_b128 v[160:163], v156
	ds_read_b128 v[164:167], v156 offset:1024
	ds_read_b128 v[168:171], v156 offset:2048
	ds_read_b128 v[172:175], v156 offset:3072
	ds_read_b128 v[176:179], v157
	ds_read_b128 v[180:183], v157 offset:1024
	ds_read_b128 v[184:187], v157 offset:2048
	ds_read_b128 v[188:191], v157 offset:3072
	s_add_u32 s34, s30, 0xfff00080
	s_addc_u32 s35, s31, -1
	s_cmp_eq_u32 s61, 60
	s_cselect_b32 s37, s23, s35
	s_cselect_b32 s36, s57, s34
	s_cselect_b32 s35, s21, s60
	s_cselect_b32 s34, s58, s59
	v_lshl_add_u64 v[146:147], s[30:31], 0, v[138:139]
	s_add_i32 m0, s29, 0xc000
	ds_read_b128 v[192:195], v158
	ds_read_b128 v[196:199], v158 offset:1024
	ds_read_b128 v[200:203], v158 offset:2048
	ds_read_b128 v[204:207], v158 offset:3072
	ds_read_b128 v[208:211], v158 offset:4096
	ds_read_b128 v[212:215], v158 offset:5120
	ds_read_b128 v[218:221], v158 offset:6144
	ds_read_b128 v[222:225], v158 offset:7168
	global_load_lds_dwordx4 v[146:147], off
	v_lshl_add_u64 v[146:147], s[30:31], 0, v[140:141]
	s_add_i32 m0, s29, 0xe000
	s_nop 0
	global_load_lds_dwordx4 v[146:147], off
	s_waitcnt vmcnt(8)
	s_waitcnt lgkmcnt(0)
	s_barrier
	s_setprio 1
	s_waitcnt lgkmcnt(0)
	v_mfma_f32_16x16x32_bf16 v[126:129], v[160:163], v[192:195], v[126:129]
	v_mfma_f32_16x16x32_bf16 v[122:125], v[168:171], v[192:195], v[122:125]
	v_mfma_f32_16x16x32_bf16 v[114:117], v[160:163], v[200:203], v[114:117]
	v_mfma_f32_16x16x32_bf16 v[106:109], v[168:171], v[200:203], v[106:109]
	v_mfma_f32_16x16x32_bf16 v[98:101], v[160:163], v[208:211], v[98:101]
	v_mfma_f32_16x16x32_bf16 v[90:93], v[168:171], v[208:211], v[90:93]
	v_mfma_f32_16x16x32_bf16 v[82:85], v[160:163], v[218:221], v[82:85]
	v_mfma_f32_16x16x32_bf16 v[74:77], v[168:171], v[218:221], v[74:77]
	v_mfma_f32_16x16x32_bf16 v[126:129], v[164:167], v[196:199], v[126:129]
	v_mfma_f32_16x16x32_bf16 v[122:125], v[172:175], v[196:199], v[122:125]
	v_mfma_f32_16x16x32_bf16 v[114:117], v[164:167], v[204:207], v[114:117]
	v_mfma_f32_16x16x32_bf16 v[106:109], v[172:175], v[204:207], v[106:109]
	v_mfma_f32_16x16x32_bf16 v[98:101], v[164:167], v[212:215], v[98:101]
	v_mfma_f32_16x16x32_bf16 v[90:93], v[172:175], v[212:215], v[90:93]
	v_mfma_f32_16x16x32_bf16 v[82:85], v[164:167], v[222:225], v[82:85]
	v_mfma_f32_16x16x32_bf16 v[74:77], v[172:175], v[222:225], v[74:77]
	s_setprio 0
	s_setprio 1
	v_mfma_f32_16x16x32_bf16 v[118:121], v[176:179], v[192:195], v[118:121]
	v_mfma_f32_16x16x32_bf16 v[110:113], v[184:187], v[192:195], v[110:113]
	v_mfma_f32_16x16x32_bf16 v[102:105], v[176:179], v[200:203], v[102:105]
	v_mfma_f32_16x16x32_bf16 v[94:97], v[184:187], v[200:203], v[94:97]
	v_mfma_f32_16x16x32_bf16 v[86:89], v[176:179], v[208:211], v[86:89]
	v_mfma_f32_16x16x32_bf16 v[78:81], v[184:187], v[208:211], v[78:81]
	v_mfma_f32_16x16x32_bf16 v[70:73], v[176:179], v[218:221], v[70:73]
	v_mfma_f32_16x16x32_bf16 v[66:69], v[184:187], v[218:221], v[66:69]
	v_mfma_f32_16x16x32_bf16 v[118:121], v[180:183], v[196:199], v[118:121]
	v_mfma_f32_16x16x32_bf16 v[110:113], v[188:191], v[196:199], v[110:113]
	v_mfma_f32_16x16x32_bf16 v[102:105], v[180:183], v[204:207], v[102:105]
	v_mfma_f32_16x16x32_bf16 v[94:97], v[188:191], v[204:207], v[94:97]
	v_mfma_f32_16x16x32_bf16 v[86:89], v[180:183], v[212:215], v[86:89]
	v_mfma_f32_16x16x32_bf16 v[78:81], v[188:191], v[212:215], v[78:81]
	v_mfma_f32_16x16x32_bf16 v[70:73], v[180:183], v[222:225], v[70:73]
	v_mfma_f32_16x16x32_bf16 v[66:69], v[188:191], v[222:225], v[66:69]
	s_setprio 0
	s_barrier
	s_add_i32 s62, s50, s42
	v_lshl_add_u64 v[146:147], s[34:35], 0, v[132:133]
	s_mov_b32 m0, s62
	global_load_lds_dwordx4 v[146:147], off
	s_add_i32 m0, s62, 0x2000
	s_add_u32 s62, s34, 0x100000
	v_lshl_add_u64 v[226:227], s[34:35], 0, v[136:137]
	s_addc_u32 s63, s35, 0
	s_add_i32 s64, s51, s42
	global_load_lds_dwordx4 v[226:227], off
	v_lshl_add_u64 v[228:229], s[62:63], 0, v[132:133]
	s_mov_b32 m0, s64
	v_lshl_add_u64 v[230:231], s[36:37], 0, v[134:135]
	global_load_lds_dwordx4 v[228:229], off
	v_lshl_add_u64 v[228:229], s[62:63], 0, v[136:137]
	s_add_i32 m0, s64, 0x2000
	s_nop 0
	global_load_lds_dwordx4 v[228:229], off
	v_lshl_add_u64 v[228:229], s[36:37], 0, v[130:131]
	s_mov_b32 m0, s29
	s_nop 0
	global_load_lds_dwordx4 v[228:229], off
	s_mov_b32 m0, s43
	s_nop 0
	global_load_lds_dwordx4 v[230:231], off
	ds_read_b128 v[192:195], v158 offset:16384
	ds_read_b128 v[196:199], v158 offset:17408
	ds_read_b128 v[200:203], v158 offset:18432
	ds_read_b128 v[204:207], v158 offset:19456
	ds_read_b128 v[208:211], v158 offset:20480
	ds_read_b128 v[212:215], v158 offset:21504
	ds_read_b128 v[218:221], v158 offset:22528
	ds_read_b128 v[222:225], v158 offset:23552
	s_waitcnt vmcnt(8)
	s_waitcnt lgkmcnt(0)
	s_barrier
; #define PG8_STAGE(bufoff, gbase, voff) do { _Pragma("unroll") for (int _i = 0; _i < 2; ++_i) \
;         __builtin_amdgcn_global_load_lds((const unsigned*)((const char*)(gbase) + (voff)[_i]), (PG8_LAS unsigned*)(lds + (bufoff) + ldsw + _i * 8192), 16, 0, 0); } while (0)
; #define PG8_LDA(dst, b, h) do { _Pragma("unroll") for (int m = 0; m < 4; ++m) _Pragma("unroll") for (int k = 0; k < 2; ++k) dst[m][k] = *(const PG8_LAS bf16x8*)(lds + PG8_SA(b, h) + aoff + m * 2048 + k * 1024); } while (0)
; #define PG8_LDB(dst, b, h) do { _Pragma("unroll") for (int n = 0; n < 2; ++n) _Pragma("unroll") for (int k = 0; k < 2; ++k) dst[n][k] = *(const PG8_LAS bf16x8*)(lds + PG8_SB(b, h) + boff + n * 2048 + k * 1024); } while (0)
; #define PG8_MMA(ai, bj, At, Bt) do { __builtin_amdgcn_s_setprio(1); _Pragma("unroll") for (int m = 0; m < 4; ++m) _Pragma("unroll") for (int n = 0; n < 2; ++n) _Pragma("unroll") for (int k = 0; k < 2; ++k) \
;         acc[ai][bj][m][n] = __builtin_amdgcn_mfma_f32_16x16x32_bf16(Bt[n][k], At[m][k], acc[ai][bj][m][n], 0, 0, 0); __builtin_amdgcn_s_setprio(0); } while (0)
; #define PG8_WAIT_V(n) asm volatile("s_waitcnt vmcnt(" #n ")" ::: "memory")
; #define PG8_WAIT_L(n) asm volatile("s_waitcnt lgkmcnt(" #n ")" ::: "memory")
; #define PG8_BAR __builtin_amdgcn_s_barrier()
; #define PG8_SCHED __builtin_amdgcn_sched_barrier(0)
; template <class Epi, class Sched, bool ALIGN_EPI = false, bool SP2 = false>
; __device__ __forceinline__ void gemm_phase(PG8_LAS unsigned char* lds, const Gemm g, const Sched& S, const Epi& E) {
;     ...
;             PG8_WAIT_V(8); PG8_WAIT_L(0); PG8_BAR; PG8_MMA(1, 0, At, B0); PG8_MMA(1, 1, At, B1); PG8_BAR; PG8_SCHED;
;             PG8_LDB(B0, 1, 0); PG8_LDB(B1, 1, 1); PG8_SCHED; PG8_LDA(At, 1, 0); PG8_STAGE(PG8_SA(0, 1), a2 + hstepA, voffA);
;             PG8_WAIT_V(8); PG8_WAIT_L(0); PG8_BAR; PG8_MMA(0, 0, At, B0); PG8_MMA(0, 1, At, B1); PG8_BAR; PG8_SCHED;
	s_setprio 1
	s_waitcnt lgkmcnt(0)
	v_mfma_f32_16x16x32_bf16 v[62:65], v[160:163], v[192:195], v[62:65]
	v_mfma_f32_16x16x32_bf16 v[58:61], v[168:171], v[192:195], v[58:61]
	v_mfma_f32_16x16x32_bf16 v[50:53], v[160:163], v[200:203], v[50:53]
	v_mfma_f32_16x16x32_bf16 v[42:45], v[168:171], v[200:203], v[42:45]
	v_mfma_f32_16x16x32_bf16 v[34:37], v[160:163], v[208:211], v[34:37]
	v_mfma_f32_16x16x32_bf16 v[26:29], v[168:171], v[208:211], v[26:29]
	v_mfma_f32_16x16x32_bf16 v[18:21], v[160:163], v[218:221], v[18:21]
	v_mfma_f32_16x16x32_bf16 v[10:13], v[168:171], v[218:221], v[10:13]
	v_mfma_f32_16x16x32_bf16 v[62:65], v[164:167], v[196:199], v[62:65]
	v_mfma_f32_16x16x32_bf16 v[58:61], v[172:175], v[196:199], v[58:61]
	v_mfma_f32_16x16x32_bf16 v[50:53], v[164:167], v[204:207], v[50:53]
	v_mfma_f32_16x16x32_bf16 v[42:45], v[172:175], v[204:207], v[42:45]
	v_mfma_f32_16x16x32_bf16 v[34:37], v[164:167], v[212:215], v[34:37]
	v_mfma_f32_16x16x32_bf16 v[26:29], v[172:175], v[212:215], v[26:29]
	v_mfma_f32_16x16x32_bf16 v[18:21], v[164:167], v[222:225], v[18:21]
	v_mfma_f32_16x16x32_bf16 v[10:13], v[172:175], v[222:225], v[10:13]
	s_setprio 0
	s_setprio 1
	v_mfma_f32_16x16x32_bf16 v[54:57], v[176:179], v[192:195], v[54:57]
	v_mfma_f32_16x16x32_bf16 v[46:49], v[184:187], v[192:195], v[46:49]
	v_mfma_f32_16x16x32_bf16 v[38:41], v[176:179], v[200:203], v[38:41]
	v_mfma_f32_16x16x32_bf16 v[30:33], v[184:187], v[200:203], v[30:33]
	v_mfma_f32_16x16x32_bf16 v[22:25], v[176:179], v[208:211], v[22:25]
	v_mfma_f32_16x16x32_bf16 v[14:17], v[184:187], v[208:211], v[14:17]
	v_mfma_f32_16x16x32_bf16 v[6:9], v[176:179], v[218:221], v[6:9]
	v_mfma_f32_16x16x32_bf16 v[2:5], v[184:187], v[218:221], v[2:5]
	v_mfma_f32_16x16x32_bf16 v[54:57], v[180:183], v[196:199], v[54:57]
	v_mfma_f32_16x16x32_bf16 v[46:49], v[188:191], v[196:199], v[46:49]
	v_mfma_f32_16x16x32_bf16 v[38:41], v[180:183], v[204:207], v[38:41]
	v_mfma_f32_16x16x32_bf16 v[30:33], v[188:191], v[204:207], v[30:33]
	v_mfma_f32_16x16x32_bf16 v[22:25], v[180:183], v[212:215], v[22:25]
	v_mfma_f32_16x16x32_bf16 v[14:17], v[188:191], v[212:215], v[14:17]
	v_mfma_f32_16x16x32_bf16 v[6:9], v[180:183], v[222:225], v[6:9]
	v_mfma_f32_16x16x32_bf16 v[2:5], v[188:191], v[222:225], v[2:5]
	s_setprio 0
	s_barrier
	s_add_i32 s62, 0, 0x18000
	v_add_u32_e32 v159, s62, v154
	s_add_i32 s63, 0, 0x1c000
	ds_read_b128 v[160:163], v159
	ds_read_b128 v[164:167], v159 offset:1024
	ds_read_b128 v[168:171], v159 offset:2048
	ds_read_b128 v[172:175], v159 offset:3072
	v_add_u32_e32 v159, s63, v154
	ds_read_b128 v[176:179], v159
	ds_read_b128 v[180:183], v159 offset:1024
	ds_read_b128 v[184:187], v159 offset:2048
	ds_read_b128 v[188:191], v159 offset:3072
	s_add_u32 s36, s36, 0x100000
	s_addc_u32 s37, s37, 0
	s_mov_b32 m0, s44
	v_lshl_add_u64 v[232:233], s[36:37], 0, v[130:131]
	ds_read_b128 v[192:195], v158 offset:32768
	ds_read_b128 v[196:199], v158 offset:33792
	ds_read_b128 v[200:203], v158 offset:34816
	ds_read_b128 v[204:207], v158 offset:35840
	ds_read_b128 v[208:211], v158 offset:36864
	ds_read_b128 v[212:215], v158 offset:37888
	ds_read_b128 v[218:221], v158 offset:38912
	ds_read_b128 v[222:225], v158 offset:39936
	global_load_lds_dwordx4 v[232:233], off
	v_lshl_add_u64 v[232:233], s[36:37], 0, v[134:135]
	s_mov_b32 m0, s45
	s_nop 0
	global_load_lds_dwordx4 v[232:233], off
	s_waitcnt vmcnt(8)
	s_waitcnt lgkmcnt(0)
	s_barrier
	s_setprio 1
	s_waitcnt lgkmcnt(0)
	v_mfma_f32_16x16x32_bf16 v[126:129], v[160:163], v[192:195], v[126:129]
	v_mfma_f32_16x16x32_bf16 v[122:125], v[168:171], v[192:195], v[122:125]
	v_mfma_f32_16x16x32_bf16 v[114:117], v[160:163], v[200:203], v[114:117]
	v_mfma_f32_16x16x32_bf16 v[106:109], v[168:171], v[200:203], v[106:109]
	v_mfma_f32_16x16x32_bf16 v[98:101], v[160:163], v[208:211], v[98:101]
	v_mfma_f32_16x16x32_bf16 v[90:93], v[168:171], v[208:211], v[90:93]
	v_mfma_f32_16x16x32_bf16 v[82:85], v[160:163], v[218:221], v[82:85]
	v_mfma_f32_16x16x32_bf16 v[74:77], v[168:171], v[218:221], v[74:77]
	v_mfma_f32_16x16x32_bf16 v[126:129], v[164:167], v[196:199], v[126:129]
	v_mfma_f32_16x16x32_bf16 v[122:125], v[172:175], v[196:199], v[122:125]
	v_mfma_f32_16x16x32_bf16 v[114:117], v[164:167], v[204:207], v[114:117]
	v_mfma_f32_16x16x32_bf16 v[106:109], v[172:175], v[204:207], v[106:109]
	v_mfma_f32_16x16x32_bf16 v[98:101], v[164:167], v[212:215], v[98:101]
	v_mfma_f32_16x16x32_bf16 v[90:93], v[172:175], v[212:215], v[90:93]
	v_mfma_f32_16x16x32_bf16 v[82:85], v[164:167], v[222:225], v[82:85]
	v_mfma_f32_16x16x32_bf16 v[74:77], v[172:175], v[222:225], v[74:77]
	s_setprio 0
	s_setprio 1
	v_mfma_f32_16x16x32_bf16 v[118:121], v[176:179], v[192:195], v[118:121]
	v_mfma_f32_16x16x32_bf16 v[110:113], v[184:187], v[192:195], v[110:113]
	v_mfma_f32_16x16x32_bf16 v[102:105], v[176:179], v[200:203], v[102:105]
	v_mfma_f32_16x16x32_bf16 v[94:97], v[184:187], v[200:203], v[94:97]
	v_mfma_f32_16x16x32_bf16 v[86:89], v[176:179], v[208:211], v[86:89]
	v_mfma_f32_16x16x32_bf16 v[78:81], v[184:187], v[208:211], v[78:81]
	v_mfma_f32_16x16x32_bf16 v[70:73], v[176:179], v[218:221], v[70:73]
	v_mfma_f32_16x16x32_bf16 v[66:69], v[184:187], v[218:221], v[66:69]
	v_mfma_f32_16x16x32_bf16 v[118:121], v[180:183], v[196:199], v[118:121]
	v_mfma_f32_16x16x32_bf16 v[110:113], v[188:191], v[196:199], v[110:113]
	v_mfma_f32_16x16x32_bf16 v[102:105], v[180:183], v[204:207], v[102:105]
	v_mfma_f32_16x16x32_bf16 v[94:97], v[188:191], v[204:207], v[94:97]
	v_mfma_f32_16x16x32_bf16 v[86:89], v[180:183], v[212:215], v[86:89]
	v_mfma_f32_16x16x32_bf16 v[78:81], v[188:191], v[212:215], v[78:81]
	v_mfma_f32_16x16x32_bf16 v[70:73], v[180:183], v[222:225], v[70:73]
	v_mfma_f32_16x16x32_bf16 v[66:69], v[188:191], v[222:225], v[66:69]
	s_setprio 0
	s_barrier
; #define PG8_STAGE(bufoff, gbase, voff) do { _Pragma("unroll") for (int _i = 0; _i < 2; ++_i) \
;         __builtin_amdgcn_global_load_lds((const unsigned*)((const char*)(gbase) + (voff)[_i]), (PG8_LAS unsigned*)(lds + (bufoff) + ldsw + _i * 8192), 16, 0, 0); } while (0)
; #define PG8_LDA(dst, b, h) do { _Pragma("unroll") for (int m = 0; m < 4; ++m) _Pragma("unroll") for (int k = 0; k < 2; ++k) dst[m][k] = *(const PG8_LAS bf16x8*)(lds + PG8_SA(b, h) + aoff + m * 2048 + k * 1024); } while (0)
; #define PG8_MMA(ai, bj, At, Bt) do { __builtin_amdgcn_s_setprio(1); _Pragma("unroll") for (int m = 0; m < 4; ++m) _Pragma("unroll") for (int n = 0; n < 2; ++n) _Pragma("unroll") for (int k = 0; k < 2; ++k) \
;         acc[ai][bj][m][n] = __builtin_amdgcn_mfma_f32_16x16x32_bf16(Bt[n][k], At[m][k], acc[ai][bj][m][n], 0, 0, 0); __builtin_amdgcn_s_setprio(0); } while (0)
; #define PG8_WAIT_V(n) asm volatile("s_waitcnt vmcnt(" #n ")" ::: "memory")
; #define PG8_WAIT_L(n) asm volatile("s_waitcnt lgkmcnt(" #n ")" ::: "memory")
; #define PG8_BAR __builtin_amdgcn_s_barrier()
; #define PG8_SCHED __builtin_amdgcn_sched_barrier(0)
; template <class Epi, class Sched, bool ALIGN_EPI = false, bool SP2 = false>
; __device__ __forceinline__ void gemm_phase(PG8_LAS unsigned char* lds, const Gemm g, const Sched& S, const Epi& E) {
;     ...
;             PG8_LDA(At, 1, 1); PG8_STAGE(PG8_SB(1, 0), b3, voffB); PG8_STAGE(PG8_SB(1, 1), b3 + hstepB, voffB); PG8_STAGE(PG8_SA(1, 0), a3, voffA);
;             PG8_WAIT_V(8); PG8_WAIT_L(0); PG8_BAR; PG8_MMA(1, 0, At, B0); PG8_MMA(1, 1, At, B1); PG8_BAR; PG8_SCHED;
;     ...
;         if constexpr (ALIGN_EPI) { if (wr == 0) PG8_BAR; }
	s_add_i32 s36, s62, s42
	v_lshl_add_u64 v[146:147], v[146:147], 0, s[10:11]
	s_mov_b32 m0, s36
	global_load_lds_dwordx4 v[146:147], off
	s_add_i32 m0, s36, 0x2000
	s_add_u32 s34, s34, 0x100080
	v_lshl_add_u64 v[146:147], v[226:227], 0, s[10:11]
	s_addc_u32 s35, s35, 0
	s_add_i32 s36, s63, s42
	global_load_lds_dwordx4 v[146:147], off
	v_lshl_add_u64 v[146:147], s[34:35], 0, v[132:133]
	s_mov_b32 m0, s36
	s_nop 0
	global_load_lds_dwordx4 v[146:147], off
	v_lshl_add_u64 v[146:147], s[34:35], 0, v[136:137]
	s_add_i32 m0, s36, 0x2000
	s_nop 0
	global_load_lds_dwordx4 v[146:147], off
	v_lshl_add_u64 v[146:147], v[228:229], 0, s[10:11]
	s_mov_b32 m0, s47
	s_nop 0
	global_load_lds_dwordx4 v[146:147], off
	v_lshl_add_u64 v[146:147], v[230:231], 0, s[10:11]
	s_mov_b32 m0, s48
	s_nop 0
	global_load_lds_dwordx4 v[146:147], off
	ds_read_b128 v[192:195], v158 offset:49152
	ds_read_b128 v[196:199], v158 offset:50176
	ds_read_b128 v[200:203], v158 offset:51200
	ds_read_b128 v[204:207], v158 offset:52224
	ds_read_b128 v[208:211], v158 offset:53248
	ds_read_b128 v[212:215], v158 offset:54272
	ds_read_b128 v[218:221], v158 offset:55296
	ds_read_b128 v[222:225], v158 offset:56320
	s_waitcnt vmcnt(8)
	s_waitcnt lgkmcnt(0)
	s_barrier
	s_setprio 1
	s_waitcnt lgkmcnt(0)
	v_mfma_f32_16x16x32_bf16 v[62:65], v[160:163], v[192:195], v[62:65]
	v_mfma_f32_16x16x32_bf16 v[58:61], v[168:171], v[192:195], v[58:61]
	v_mfma_f32_16x16x32_bf16 v[50:53], v[160:163], v[200:203], v[50:53]
	v_mfma_f32_16x16x32_bf16 v[42:45], v[168:171], v[200:203], v[42:45]
	v_mfma_f32_16x16x32_bf16 v[34:37], v[160:163], v[208:211], v[34:37]
	v_mfma_f32_16x16x32_bf16 v[26:29], v[168:171], v[208:211], v[26:29]
	v_mfma_f32_16x16x32_bf16 v[18:21], v[160:163], v[218:221], v[18:21]
	v_mfma_f32_16x16x32_bf16 v[10:13], v[168:171], v[218:221], v[10:13]
	v_mfma_f32_16x16x32_bf16 v[62:65], v[164:167], v[196:199], v[62:65]
	v_mfma_f32_16x16x32_bf16 v[58:61], v[172:175], v[196:199], v[58:61]
	v_mfma_f32_16x16x32_bf16 v[50:53], v[164:167], v[204:207], v[50:53]
	v_mfma_f32_16x16x32_bf16 v[42:45], v[172:175], v[204:207], v[42:45]
	v_mfma_f32_16x16x32_bf16 v[34:37], v[164:167], v[212:215], v[34:37]
	v_mfma_f32_16x16x32_bf16 v[26:29], v[172:175], v[212:215], v[26:29]
	v_mfma_f32_16x16x32_bf16 v[18:21], v[164:167], v[222:225], v[18:21]
	v_mfma_f32_16x16x32_bf16 v[10:13], v[172:175], v[222:225], v[10:13]
	s_setprio 0
	s_setprio 1
	v_mfma_f32_16x16x32_bf16 v[54:57], v[176:179], v[192:195], v[54:57]
	v_mfma_f32_16x16x32_bf16 v[46:49], v[184:187], v[192:195], v[46:49]
	v_mfma_f32_16x16x32_bf16 v[38:41], v[176:179], v[200:203], v[38:41]
	v_mfma_f32_16x16x32_bf16 v[30:33], v[184:187], v[200:203], v[30:33]
	v_mfma_f32_16x16x32_bf16 v[22:25], v[176:179], v[208:211], v[22:25]
	v_mfma_f32_16x16x32_bf16 v[14:17], v[184:187], v[208:211], v[14:17]
	v_mfma_f32_16x16x32_bf16 v[6:9], v[176:179], v[218:221], v[6:9]
	v_mfma_f32_16x16x32_bf16 v[2:5], v[184:187], v[218:221], v[2:5]
	v_mfma_f32_16x16x32_bf16 v[54:57], v[180:183], v[196:199], v[54:57]
	v_mfma_f32_16x16x32_bf16 v[46:49], v[188:191], v[196:199], v[46:49]
	v_mfma_f32_16x16x32_bf16 v[38:41], v[180:183], v[204:207], v[38:41]
	v_mfma_f32_16x16x32_bf16 v[30:33], v[188:191], v[204:207], v[30:33]
	v_mfma_f32_16x16x32_bf16 v[22:25], v[180:183], v[212:215], v[22:25]
	v_mfma_f32_16x16x32_bf16 v[14:17], v[188:191], v[212:215], v[14:17]
	v_mfma_f32_16x16x32_bf16 v[6:9], v[180:183], v[222:225], v[6:9]
	v_mfma_f32_16x16x32_bf16 v[2:5], v[188:191], v[222:225], v[2:5]
	s_setprio 0
	s_barrier
	s_add_i32 s61, s61, 2
	s_add_u32 s30, s30, 0x100
	s_addc_u32 s31, s31, 0
	s_add_u32 s59, s59, 0x100
	s_addc_u32 s60, s60, 0
	s_cmp_gt_u32 s61, 61
	s_cbranch_scc0 .LBB0_1868
	s_and_b64 vcc, exec, s[12:13]
	s_cbranch_vccz .LBB0_1871
	s_barrier

; #define PG8_STAGE(bufoff, gbase, voff) do { _Pragma("unroll") for (int _i = 0; _i < 2; ++_i) \
;         __builtin_amdgcn_global_load_lds((const unsigned*)((const char*)(gbase) + (voff)[_i]), (PG8_LAS unsigned*)(lds + (bufoff) + ldsw + _i * 8192), 16, 0, 0); } while (0)
; #define PG8_LDA(dst, b, h) do { _Pragma("unroll") for (int m = 0; m < 4; ++m) _Pragma("unroll") for (int k = 0; k < 2; ++k) dst[m][k] = *(const PG8_LAS bf16x8*)(lds + PG8_SA(b, h) + aoff + m * 2048 + k * 1024); } while (0)
; #define PG8_LDB(dst, b, h) do { _Pragma("unroll") for (int n = 0; n < 2; ++n) _Pragma("unroll") for (int k = 0; k < 2; ++k) dst[n][k] = *(const PG8_LAS bf16x8*)(lds + PG8_SB(b, h) + boff + n * 2048 + k * 1024); } while (0)
; #define PG8_MMA(ai, bj, At, Bt) do { __builtin_amdgcn_s_setprio(1); _Pragma("unroll") for (int m = 0; m < 4; ++m) _Pragma("unroll") for (int n = 0; n < 2; ++n) _Pragma("unroll") for (int k = 0; k < 2; ++k) \
;         acc[ai][bj][m][n] = __builtin_amdgcn_mfma_f32_16x16x32_bf16(Bt[n][k], At[m][k], acc[ai][bj][m][n], 0, 0, 0); __builtin_amdgcn_s_setprio(0); } while (0)
; #define PG8_WAIT_V(n) asm volatile("s_waitcnt vmcnt(" #n ")" ::: "memory")
; #define PG8_WAIT_L(n) asm volatile("s_waitcnt lgkmcnt(" #n ")" ::: "memory")
; template <class Epi, class Sched, bool ALIGN_EPI = false, bool SP2 = false>
; __device__ __forceinline__ void gemm_phase(PG8_LAS unsigned char* lds, const Gemm g, const Sched& S, const Epi& E) {
;     ...
;             const bool last = (t == nt - 2);
;             const char* a1 = cA + (size_t)(t + 1) * kstep;
;             const char* a2 = last ? nA : cA + (size_t)(t + 2) * kstep; const char* b2 = last ? nB : cB + (size_t)(t + 2) * kstep;
;             const char* a3 = a2 + kstep; const char* b3 = b2 + kstep;
;             if (last && has_next) S.a_ready(nxt);
;             if constexpr (SP2) {
;             PG8_LDB(B0, 0, 0); PG8_LDB(B1, 0, 1); PG8_SCHED; PG8_LDA(At, 0, 0); PG8_STAGE(PG8_SA(1, 1), a1 + hstepA, voffA);
;             PG8_WAIT_V(8); PG8_WAIT_L(0); PG8_BAR; PG8_MMA(0, 0, At, B0); PG8_MMA(0, 1, At, B1); PG8_BAR; PG8_SCHED;
;             PG8_LDA(At, 0, 1); PG8_STAGE(PG8_SB(0, 0), b2, voffB); PG8_STAGE(PG8_SB(0, 1), b2 + hstepB, voffB); PG8_STAGE(PG8_SA(0, 0), a2, voffA);
;             PG8_WAIT_V(8); PG8_WAIT_L(0); PG8_BAR; PG8_MMA(1, 0, At, B0); PG8_MMA(1, 1, At, B1); PG8_BAR; PG8_SCHED;
.LBB0_1880:
	ds_read_b128 v[148:151], v143
	ds_read_b128 v[152:155], v143 offset:1024
	ds_read_b128 v[156:159], v143 offset:2048
	ds_read_b128 v[160:163], v143 offset:3072
	ds_read_b128 v[164:167], v144
	ds_read_b128 v[168:171], v144 offset:1024
	ds_read_b128 v[172:175], v144 offset:2048
	ds_read_b128 v[176:179], v144 offset:3072
	s_add_u32 s16, s12, s14
	s_addc_u32 s17, s13, s15
	s_add_u32 s16, s16, 0x34000100
	s_addc_u32 s17, s17, 0
	s_add_u32 s42, s28, s14
	s_addc_u32 s43, s29, s15
	s_cmpk_eq_i32 s14, 0x1f00
	s_cselect_b32 s19, s9, s17
	s_cselect_b32 s18, s8, s16
	s_cselect_b32 s17, s7, s43
	s_cselect_b32 s16, s6, s42
	s_mov_b32 m0, s31
	v_lshl_add_u64 v[212:213], v[138:139], 0, s[14:15]
	ds_read_b128 v[180:183], v145
	ds_read_b128 v[184:187], v145 offset:1024
	ds_read_b128 v[188:191], v145 offset:2048
	ds_read_b128 v[192:195], v145 offset:3072
	ds_read_b128 v[196:199], v145 offset:4096
	ds_read_b128 v[200:203], v145 offset:5120
	ds_read_b128 v[204:207], v145 offset:6144
	ds_read_b128 v[208:211], v145 offset:7168
	global_load_lds_dwordx4 v[212:213], off
	v_lshl_add_u64 v[212:213], v[140:141], 0, s[14:15]
	s_mov_b32 m0, s33
	s_nop 0
	global_load_lds_dwordx4 v[212:213], off
	s_waitcnt vmcnt(8)
	s_waitcnt lgkmcnt(0)
	s_barrier
	s_setprio 1
	s_waitcnt lgkmcnt(0)
	v_mfma_f32_16x16x32_bf16 v[126:129], v[148:151], v[180:183], v[126:129]
	v_mfma_f32_16x16x32_bf16 v[122:125], v[156:159], v[180:183], v[122:125]
	v_mfma_f32_16x16x32_bf16 v[114:117], v[148:151], v[188:191], v[114:117]
	v_mfma_f32_16x16x32_bf16 v[106:109], v[156:159], v[188:191], v[106:109]
	v_mfma_f32_16x16x32_bf16 v[98:101], v[148:151], v[196:199], v[98:101]
	v_mfma_f32_16x16x32_bf16 v[90:93], v[156:159], v[196:199], v[90:93]
	v_mfma_f32_16x16x32_bf16 v[82:85], v[148:151], v[204:207], v[82:85]
	v_mfma_f32_16x16x32_bf16 v[74:77], v[156:159], v[204:207], v[74:77]
	v_mfma_f32_16x16x32_bf16 v[126:129], v[152:155], v[184:187], v[126:129]
	v_mfma_f32_16x16x32_bf16 v[122:125], v[160:163], v[184:187], v[122:125]
	v_mfma_f32_16x16x32_bf16 v[114:117], v[152:155], v[192:195], v[114:117]
	v_mfma_f32_16x16x32_bf16 v[106:109], v[160:163], v[192:195], v[106:109]
	v_mfma_f32_16x16x32_bf16 v[98:101], v[152:155], v[200:203], v[98:101]
	v_mfma_f32_16x16x32_bf16 v[90:93], v[160:163], v[200:203], v[90:93]
	v_mfma_f32_16x16x32_bf16 v[82:85], v[152:155], v[208:211], v[82:85]
	v_mfma_f32_16x16x32_bf16 v[74:77], v[160:163], v[208:211], v[74:77]
	s_setprio 0
	s_setprio 1
	v_mfma_f32_16x16x32_bf16 v[118:121], v[164:167], v[180:183], v[118:121]
	v_mfma_f32_16x16x32_bf16 v[110:113], v[172:175], v[180:183], v[110:113]
	v_mfma_f32_16x16x32_bf16 v[102:105], v[164:167], v[188:191], v[102:105]
	v_mfma_f32_16x16x32_bf16 v[94:97], v[172:175], v[188:191], v[94:97]
	v_mfma_f32_16x16x32_bf16 v[86:89], v[164:167], v[196:199], v[86:89]
	v_mfma_f32_16x16x32_bf16 v[78:81], v[172:175], v[196:199], v[78:81]
	v_mfma_f32_16x16x32_bf16 v[70:73], v[164:167], v[204:207], v[70:73]
	v_mfma_f32_16x16x32_bf16 v[66:69], v[172:175], v[204:207], v[66:69]
	v_mfma_f32_16x16x32_bf16 v[118:121], v[168:171], v[184:187], v[118:121]
	v_mfma_f32_16x16x32_bf16 v[110:113], v[176:179], v[184:187], v[110:113]
	v_mfma_f32_16x16x32_bf16 v[102:105], v[168:171], v[192:195], v[102:105]
	v_mfma_f32_16x16x32_bf16 v[94:97], v[176:179], v[192:195], v[94:97]
	v_mfma_f32_16x16x32_bf16 v[86:89], v[168:171], v[200:203], v[86:89]
	v_mfma_f32_16x16x32_bf16 v[78:81], v[176:179], v[200:203], v[78:81]
	v_mfma_f32_16x16x32_bf16 v[70:73], v[168:171], v[208:211], v[70:73]
	v_mfma_f32_16x16x32_bf16 v[66:69], v[176:179], v[208:211], v[66:69]
	s_setprio 0
	s_barrier
	s_mov_b32 m0, s34
	v_lshl_add_u64 v[212:213], s[16:17], 0, v[132:133]
	s_add_u32 s42, s16, 0x100000
	global_load_lds_dwordx4 v[212:213], off
	v_lshl_add_u64 v[214:215], s[16:17], 0, v[136:137]
	s_mov_b32 m0, s35
	s_addc_u32 s43, s17, 0
	global_load_lds_dwordx4 v[214:215], off
	v_lshl_add_u64 v[218:219], s[42:43], 0, v[132:133]
	s_mov_b32 m0, s36
	v_lshl_add_u64 v[220:221], s[18:19], 0, v[134:135]
	global_load_lds_dwordx4 v[218:219], off
	v_lshl_add_u64 v[218:219], s[42:43], 0, v[136:137]
	s_mov_b32 m0, s37
	s_nop 0
	global_load_lds_dwordx4 v[218:219], off
	v_lshl_add_u64 v[218:219], s[18:19], 0, v[130:131]
	s_mov_b32 m0, s3
	s_nop 0
	global_load_lds_dwordx4 v[218:219], off
	s_mov_b32 m0, s22
	s_nop 0
	global_load_lds_dwordx4 v[220:221], off
	ds_read_b128 v[180:183], v145 offset:16384
	ds_read_b128 v[184:187], v145 offset:17408
	ds_read_b128 v[188:191], v145 offset:18432
	ds_read_b128 v[192:195], v145 offset:19456
	ds_read_b128 v[196:199], v145 offset:20480
	ds_read_b128 v[200:203], v145 offset:21504
	ds_read_b128 v[204:207], v145 offset:22528
	ds_read_b128 v[208:211], v145 offset:23552
	s_waitcnt vmcnt(8)
	s_waitcnt lgkmcnt(0)
	s_barrier
; #define PG8_STAGE(bufoff, gbase, voff) do { _Pragma("unroll") for (int _i = 0; _i < 2; ++_i) \
;         __builtin_amdgcn_global_load_lds((const unsigned*)((const char*)(gbase) + (voff)[_i]), (PG8_LAS unsigned*)(lds + (bufoff) + ldsw + _i * 8192), 16, 0, 0); } while (0)
; #define PG8_LDA(dst, b, h) do { _Pragma("unroll") for (int m = 0; m < 4; ++m) _Pragma("unroll") for (int k = 0; k < 2; ++k) dst[m][k] = *(const PG8_LAS bf16x8*)(lds + PG8_SA(b, h) + aoff + m * 2048 + k * 1024); } while (0)
; #define PG8_LDB(dst, b, h) do { _Pragma("unroll") for (int n = 0; n < 2; ++n) _Pragma("unroll") for (int k = 0; k < 2; ++k) dst[n][k] = *(const PG8_LAS bf16x8*)(lds + PG8_SB(b, h) + boff + n * 2048 + k * 1024); } while (0)
; #define PG8_MMA(ai, bj, At, Bt) do { __builtin_amdgcn_s_setprio(1); _Pragma("unroll") for (int m = 0; m < 4; ++m) _Pragma("unroll") for (int n = 0; n < 2; ++n) _Pragma("unroll") for (int k = 0; k < 2; ++k) \
;         acc[ai][bj][m][n] = __builtin_amdgcn_mfma_f32_16x16x32_bf16(Bt[n][k], At[m][k], acc[ai][bj][m][n], 0, 0, 0); __builtin_amdgcn_s_setprio(0); } while (0)
; #define PG8_WAIT_V(n) asm volatile("s_waitcnt vmcnt(" #n ")" ::: "memory")
; #define PG8_WAIT_L(n) asm volatile("s_waitcnt lgkmcnt(" #n ")" ::: "memory")
; #define PG8_BAR __builtin_amdgcn_s_barrier()
; #define PG8_SCHED __builtin_amdgcn_sched_barrier(0)
; template <class Epi, class Sched, bool ALIGN_EPI = false, bool SP2 = false>
; __device__ __forceinline__ void gemm_phase(PG8_LAS unsigned char* lds, const Gemm g, const Sched& S, const Epi& E) {
;     ...
;             PG8_WAIT_V(8); PG8_WAIT_L(0); PG8_BAR; PG8_MMA(1, 0, At, B0); PG8_MMA(1, 1, At, B1); PG8_BAR; PG8_SCHED;
;             PG8_LDB(B0, 1, 0); PG8_LDB(B1, 1, 1); PG8_SCHED; PG8_LDA(At, 1, 0); PG8_STAGE(PG8_SA(0, 1), a2 + hstepA, voffA);
;             PG8_WAIT_V(8); PG8_WAIT_L(0); PG8_BAR; PG8_MMA(0, 0, At, B0); PG8_MMA(0, 1, At, B1); PG8_BAR; PG8_SCHED;
	s_setprio 1
	s_waitcnt lgkmcnt(0)
	v_mfma_f32_16x16x32_bf16 v[62:65], v[148:151], v[180:183], v[62:65]
	v_mfma_f32_16x16x32_bf16 v[58:61], v[156:159], v[180:183], v[58:61]
	v_mfma_f32_16x16x32_bf16 v[50:53], v[148:151], v[188:191], v[50:53]
	v_mfma_f32_16x16x32_bf16 v[42:45], v[156:159], v[188:191], v[42:45]
	v_mfma_f32_16x16x32_bf16 v[34:37], v[148:151], v[196:199], v[34:37]
	v_mfma_f32_16x16x32_bf16 v[26:29], v[156:159], v[196:199], v[26:29]
	v_mfma_f32_16x16x32_bf16 v[18:21], v[148:151], v[204:207], v[18:21]
	v_mfma_f32_16x16x32_bf16 v[10:13], v[156:159], v[204:207], v[10:13]
	v_mfma_f32_16x16x32_bf16 v[62:65], v[152:155], v[184:187], v[62:65]
	v_mfma_f32_16x16x32_bf16 v[58:61], v[160:163], v[184:187], v[58:61]
	v_mfma_f32_16x16x32_bf16 v[50:53], v[152:155], v[192:195], v[50:53]
	v_mfma_f32_16x16x32_bf16 v[42:45], v[160:163], v[192:195], v[42:45]
	v_mfma_f32_16x16x32_bf16 v[34:37], v[152:155], v[200:203], v[34:37]
	v_mfma_f32_16x16x32_bf16 v[26:29], v[160:163], v[200:203], v[26:29]
	v_mfma_f32_16x16x32_bf16 v[18:21], v[152:155], v[208:211], v[18:21]
	v_mfma_f32_16x16x32_bf16 v[10:13], v[160:163], v[208:211], v[10:13]
	s_setprio 0
	s_setprio 1
	v_mfma_f32_16x16x32_bf16 v[54:57], v[164:167], v[180:183], v[54:57]
	v_mfma_f32_16x16x32_bf16 v[46:49], v[172:175], v[180:183], v[46:49]
	v_mfma_f32_16x16x32_bf16 v[38:41], v[164:167], v[188:191], v[38:41]
	v_mfma_f32_16x16x32_bf16 v[30:33], v[172:175], v[188:191], v[30:33]
	v_mfma_f32_16x16x32_bf16 v[22:25], v[164:167], v[196:199], v[22:25]
	v_mfma_f32_16x16x32_bf16 v[14:17], v[172:175], v[196:199], v[14:17]
	v_mfma_f32_16x16x32_bf16 v[6:9], v[164:167], v[204:207], v[6:9]
	v_mfma_f32_16x16x32_bf16 v[2:5], v[172:175], v[204:207], v[2:5]
	v_mfma_f32_16x16x32_bf16 v[54:57], v[168:171], v[184:187], v[54:57]
	v_mfma_f32_16x16x32_bf16 v[46:49], v[176:179], v[184:187], v[46:49]
	v_mfma_f32_16x16x32_bf16 v[38:41], v[168:171], v[192:195], v[38:41]
	v_mfma_f32_16x16x32_bf16 v[30:33], v[176:179], v[192:195], v[30:33]
	v_mfma_f32_16x16x32_bf16 v[22:25], v[168:171], v[200:203], v[22:25]
	v_mfma_f32_16x16x32_bf16 v[14:17], v[176:179], v[200:203], v[14:17]
	v_mfma_f32_16x16x32_bf16 v[6:9], v[168:171], v[208:211], v[6:9]
	v_mfma_f32_16x16x32_bf16 v[2:5], v[176:179], v[208:211], v[2:5]
	s_setprio 0
	s_barrier
	ds_read_b128 v[148:151], v146
	ds_read_b128 v[152:155], v146 offset:1024
	ds_read_b128 v[156:159], v146 offset:2048
	ds_read_b128 v[160:163], v146 offset:3072
	ds_read_b128 v[164:167], v147
	ds_read_b128 v[168:171], v147 offset:1024
	ds_read_b128 v[172:175], v147 offset:2048
	ds_read_b128 v[176:179], v147 offset:3072
	s_add_u32 s18, s18, 0x100000
	s_addc_u32 s19, s19, 0
	s_mov_b32 m0, s23
	v_lshl_add_u64 v[222:223], s[18:19], 0, v[130:131]
	ds_read_b128 v[180:183], v145 offset:32768
	ds_read_b128 v[184:187], v145 offset:33792
	ds_read_b128 v[188:191], v145 offset:34816
	ds_read_b128 v[192:195], v145 offset:35840
	ds_read_b128 v[196:199], v145 offset:36864
	ds_read_b128 v[200:203], v145 offset:37888
	ds_read_b128 v[204:207], v145 offset:38912
	ds_read_b128 v[208:211], v145 offset:39936
	global_load_lds_dwordx4 v[222:223], off
	v_lshl_add_u64 v[222:223], s[18:19], 0, v[134:135]
	s_mov_b32 m0, s24
	s_nop 0
	global_load_lds_dwordx4 v[222:223], off
	s_waitcnt vmcnt(8)
	s_waitcnt lgkmcnt(0)
	s_barrier
	s_setprio 1
	s_waitcnt lgkmcnt(0)
	v_mfma_f32_16x16x32_bf16 v[126:129], v[148:151], v[180:183], v[126:129]
	v_mfma_f32_16x16x32_bf16 v[122:125], v[156:159], v[180:183], v[122:125]
	v_mfma_f32_16x16x32_bf16 v[114:117], v[148:151], v[188:191], v[114:117]
	v_mfma_f32_16x16x32_bf16 v[106:109], v[156:159], v[188:191], v[106:109]
	v_mfma_f32_16x16x32_bf16 v[98:101], v[148:151], v[196:199], v[98:101]
	v_mfma_f32_16x16x32_bf16 v[90:93], v[156:159], v[196:199], v[90:93]
	v_mfma_f32_16x16x32_bf16 v[82:85], v[148:151], v[204:207], v[82:85]
	v_mfma_f32_16x16x32_bf16 v[74:77], v[156:159], v[204:207], v[74:77]
	v_mfma_f32_16x16x32_bf16 v[126:129], v[152:155], v[184:187], v[126:129]
	v_mfma_f32_16x16x32_bf16 v[122:125], v[160:163], v[184:187], v[122:125]
	v_mfma_f32_16x16x32_bf16 v[114:117], v[152:155], v[192:195], v[114:117]
	v_mfma_f32_16x16x32_bf16 v[106:109], v[160:163], v[192:195], v[106:109]
	v_mfma_f32_16x16x32_bf16 v[98:101], v[152:155], v[200:203], v[98:101]
	v_mfma_f32_16x16x32_bf16 v[90:93], v[160:163], v[200:203], v[90:93]
	v_mfma_f32_16x16x32_bf16 v[82:85], v[152:155], v[208:211], v[82:85]
	v_mfma_f32_16x16x32_bf16 v[74:77], v[160:163], v[208:211], v[74:77]
	s_setprio 0
	s_setprio 1
	v_mfma_f32_16x16x32_bf16 v[118:121], v[164:167], v[180:183], v[118:121]
	v_mfma_f32_16x16x32_bf16 v[110:113], v[172:175], v[180:183], v[110:113]
	v_mfma_f32_16x16x32_bf16 v[102:105], v[164:167], v[188:191], v[102:105]
	v_mfma_f32_16x16x32_bf16 v[94:97], v[172:175], v[188:191], v[94:97]
	v_mfma_f32_16x16x32_bf16 v[86:89], v[164:167], v[196:199], v[86:89]
	v_mfma_f32_16x16x32_bf16 v[78:81], v[172:175], v[196:199], v[78:81]
	v_mfma_f32_16x16x32_bf16 v[70:73], v[164:167], v[204:207], v[70:73]
	v_mfma_f32_16x16x32_bf16 v[66:69], v[172:175], v[204:207], v[66:69]
	v_mfma_f32_16x16x32_bf16 v[118:121], v[168:171], v[184:187], v[118:121]
	v_mfma_f32_16x16x32_bf16 v[110:113], v[176:179], v[184:187], v[110:113]
	v_mfma_f32_16x16x32_bf16 v[102:105], v[168:171], v[192:195], v[102:105]
	v_mfma_f32_16x16x32_bf16 v[94:97], v[176:179], v[192:195], v[94:97]
	v_mfma_f32_16x16x32_bf16 v[86:89], v[168:171], v[200:203], v[86:89]
	v_mfma_f32_16x16x32_bf16 v[78:81], v[176:179], v[200:203], v[78:81]
	v_mfma_f32_16x16x32_bf16 v[70:73], v[168:171], v[208:211], v[70:73]
	v_mfma_f32_16x16x32_bf16 v[66:69], v[176:179], v[208:211], v[66:69]
	s_setprio 0
	s_barrier
; #define PG8_STAGE(bufoff, gbase, voff) do { _Pragma("unroll") for (int _i = 0; _i < 2; ++_i) \
;         __builtin_amdgcn_global_load_lds((const unsigned*)((const char*)(gbase) + (voff)[_i]), (PG8_LAS unsigned*)(lds + (bufoff) + ldsw + _i * 8192), 16, 0, 0); } while (0)
; #define PG8_LDA(dst, b, h) do { _Pragma("unroll") for (int m = 0; m < 4; ++m) _Pragma("unroll") for (int k = 0; k < 2; ++k) dst[m][k] = *(const PG8_LAS bf16x8*)(lds + PG8_SA(b, h) + aoff + m * 2048 + k * 1024); } while (0)
; #define PG8_MMA(ai, bj, At, Bt) do { __builtin_amdgcn_s_setprio(1); _Pragma("unroll") for (int m = 0; m < 4; ++m) _Pragma("unroll") for (int n = 0; n < 2; ++n) _Pragma("unroll") for (int k = 0; k < 2; ++k) \
;         acc[ai][bj][m][n] = __builtin_amdgcn_mfma_f32_16x16x32_bf16(Bt[n][k], At[m][k], acc[ai][bj][m][n], 0, 0, 0); __builtin_amdgcn_s_setprio(0); } while (0)
; #define PG8_WAIT_V(n) asm volatile("s_waitcnt vmcnt(" #n ")" ::: "memory")
; #define PG8_WAIT_L(n) asm volatile("s_waitcnt lgkmcnt(" #n ")" ::: "memory")
; #define PG8_BAR __builtin_amdgcn_s_barrier()
; #define PG8_SCHED __builtin_amdgcn_sched_barrier(0)
; template <class Epi, class Sched, bool ALIGN_EPI = false, bool SP2 = false>
; __device__ __forceinline__ void gemm_phase(PG8_LAS unsigned char* lds, const Gemm g, const Sched& S, const Epi& E) {
;     ...
;             PG8_LDA(At, 1, 1); PG8_STAGE(PG8_SB(1, 0), b3, voffB); PG8_STAGE(PG8_SB(1, 1), b3 + hstepB, voffB); PG8_STAGE(PG8_SA(1, 0), a3, voffA);
;             PG8_WAIT_V(8); PG8_WAIT_L(0); PG8_BAR; PG8_MMA(1, 0, At, B0); PG8_MMA(1, 1, At, B1); PG8_BAR; PG8_SCHED;
;     ...
;         if constexpr (ALIGN_EPI) { if (wr == 0) PG8_BAR; }
	s_mov_b32 m0, s38
	v_lshl_add_u64 v[212:213], v[212:213], 0, s[10:11]
	s_add_u32 s16, s16, 0x100080
	global_load_lds_dwordx4 v[212:213], off
	v_lshl_add_u64 v[212:213], v[214:215], 0, s[10:11]
	s_mov_b32 m0, s39
	s_addc_u32 s17, s17, 0
	global_load_lds_dwordx4 v[212:213], off
	v_lshl_add_u64 v[212:213], s[16:17], 0, v[132:133]
	s_mov_b32 m0, s40
	s_nop 0
	global_load_lds_dwordx4 v[212:213], off
	v_lshl_add_u64 v[212:213], s[16:17], 0, v[136:137]
	s_mov_b32 m0, s41
	s_nop 0
	global_load_lds_dwordx4 v[212:213], off
	v_lshl_add_u64 v[212:213], v[218:219], 0, s[10:11]
	s_mov_b32 m0, s26
	s_nop 0
	global_load_lds_dwordx4 v[212:213], off
	v_lshl_add_u64 v[212:213], v[220:221], 0, s[10:11]
	s_mov_b32 m0, s27
	s_nop 0
	global_load_lds_dwordx4 v[212:213], off
	ds_read_b128 v[180:183], v145 offset:49152
	ds_read_b128 v[184:187], v145 offset:50176
	ds_read_b128 v[188:191], v145 offset:51200
	ds_read_b128 v[192:195], v145 offset:52224
	ds_read_b128 v[196:199], v145 offset:53248
	ds_read_b128 v[200:203], v145 offset:54272
	ds_read_b128 v[204:207], v145 offset:55296
	ds_read_b128 v[208:211], v145 offset:56320
	s_waitcnt vmcnt(8)
	s_waitcnt lgkmcnt(0)
	s_barrier
	s_setprio 1
	s_waitcnt lgkmcnt(0)
	v_mfma_f32_16x16x32_bf16 v[62:65], v[148:151], v[180:183], v[62:65]
	v_mfma_f32_16x16x32_bf16 v[58:61], v[156:159], v[180:183], v[58:61]
	v_mfma_f32_16x16x32_bf16 v[50:53], v[148:151], v[188:191], v[50:53]
	v_mfma_f32_16x16x32_bf16 v[42:45], v[156:159], v[188:191], v[42:45]
	v_mfma_f32_16x16x32_bf16 v[34:37], v[148:151], v[196:199], v[34:37]
	v_mfma_f32_16x16x32_bf16 v[26:29], v[156:159], v[196:199], v[26:29]
	v_mfma_f32_16x16x32_bf16 v[18:21], v[148:151], v[204:207], v[18:21]
	v_mfma_f32_16x16x32_bf16 v[10:13], v[156:159], v[204:207], v[10:13]
	v_mfma_f32_16x16x32_bf16 v[62:65], v[152:155], v[184:187], v[62:65]
	v_mfma_f32_16x16x32_bf16 v[58:61], v[160:163], v[184:187], v[58:61]
	v_mfma_f32_16x16x32_bf16 v[50:53], v[152:155], v[192:195], v[50:53]
	v_mfma_f32_16x16x32_bf16 v[42:45], v[160:163], v[192:195], v[42:45]
	v_mfma_f32_16x16x32_bf16 v[34:37], v[152:155], v[200:203], v[34:37]
	v_mfma_f32_16x16x32_bf16 v[26:29], v[160:163], v[200:203], v[26:29]
	v_mfma_f32_16x16x32_bf16 v[18:21], v[152:155], v[208:211], v[18:21]
	v_mfma_f32_16x16x32_bf16 v[10:13], v[160:163], v[208:211], v[10:13]
	s_setprio 0
	s_setprio 1
	v_mfma_f32_16x16x32_bf16 v[54:57], v[164:167], v[180:183], v[54:57]
	v_mfma_f32_16x16x32_bf16 v[46:49], v[172:175], v[180:183], v[46:49]
	v_mfma_f32_16x16x32_bf16 v[38:41], v[164:167], v[188:191], v[38:41]
	v_mfma_f32_16x16x32_bf16 v[30:33], v[172:175], v[188:191], v[30:33]
	v_mfma_f32_16x16x32_bf16 v[22:25], v[164:167], v[196:199], v[22:25]
	v_mfma_f32_16x16x32_bf16 v[14:17], v[172:175], v[196:199], v[14:17]
	v_mfma_f32_16x16x32_bf16 v[6:9], v[164:167], v[204:207], v[6:9]
	v_mfma_f32_16x16x32_bf16 v[2:5], v[172:175], v[204:207], v[2:5]
	v_mfma_f32_16x16x32_bf16 v[54:57], v[168:171], v[184:187], v[54:57]
	v_mfma_f32_16x16x32_bf16 v[46:49], v[176:179], v[184:187], v[46:49]
	v_mfma_f32_16x16x32_bf16 v[38:41], v[168:171], v[192:195], v[38:41]
	v_mfma_f32_16x16x32_bf16 v[30:33], v[176:179], v[192:195], v[30:33]
	v_mfma_f32_16x16x32_bf16 v[22:25], v[168:171], v[200:203], v[22:25]
	v_mfma_f32_16x16x32_bf16 v[14:17], v[176:179], v[200:203], v[14:17]
	v_mfma_f32_16x16x32_bf16 v[6:9], v[168:171], v[208:211], v[6:9]
	v_mfma_f32_16x16x32_bf16 v[2:5], v[176:179], v[208:211], v[2:5]
	s_setprio 0
	s_barrier
	s_add_i32 s30, s30, 2
	s_add_u32 s14, s14, 0x100
	s_addc_u32 s15, s15, 0
	s_cmp_gt_u32 s30, 61
	s_cbranch_scc0 .LBB0_1880
	s_cmpk_lt_u32 s20, 0x100
	s_cbranch_scc0 .LBB0_1883
	s_barrier
